# static priority raise (docs 6.3/7.4): s_setprio 1 for waves 4-7 before each of the 20 GEMM K-loops, hipcc's per-cluster flips deleted, s_setprio 0 after the loop; otherwise v67
# speedup vs baseline: 1.0117x; 1.0117x over previous
; #define LAS __attribute__((address_space(3)))
;     __device__ __forceinline__ void ids() { lane = fresh_lane(); tid = wave * 64 + lane; }
; __global__ void __launch_bounds__(NTHR, 2) mega_fwd(Params P) {
;     ...
;     F.wave = __builtin_amdgcn_readfirstlane((int)threadIdx.x >> 6); F.ids();
;     F.G = gridDim.x; { const int bx = blockIdx.x; F.vcu = (F.G % 8 == 0) ? (bx % 8) * (F.G / 8) + bx / 8 : bx; }
;     volatile LAS unsigned* MISC = (volatile LAS unsigned*)(F.lds + MISC_OFF);
;     for (int u = F.tid; u < (LDS_BYTES - RING_BYTES) / 4; u += NTHR) ((LAS unsigned*)(F.lds + RING_BYTES))[u] = 0u;
.LBB0_2:
	s_and_b32 s73, s72, 0xffffffc0
	v_add_u32_e32 v1, s73, v2
	s_movk_i32 s3, 0x1000
	s_lshr_b32 s80, s72, 6
	s_nop 0
	v_writelane_b32 v246, s80, 6
	v_cmp_gt_i32_e32 vcc, s3, v1
	s_and_saveexec_b64 s[4:5], vcc
	s_cbranch_execz .LBB0_5
	s_lshl_b32 s3, s80, 8
	s_add_i32 s3, s3, 0
	v_lshl_add_u32 v2, v2, 2, s3
	v_add_u32_e32 v3, 0xfffffe00, v1
	v_add_u32_e32 v2, 0x20000, v2
	s_mov_b64 s[6:7], 0
	v_mov_b32_e32 v4, 0
	s_movk_i32 s3, 0xdff

; #define PG8_STAGE(bufoff, soff, voff) do { _Pragma("unroll") for (int _i = 0; _i < 2; ++_i) \
;         __builtin_amdgcn_raw_ptr_buffer_load_lds(rs_##voff, (PG8_LAS unsigned*)(lds + (bufoff) + ldsw + _i * 8192), 16, (int)(voff)[_i], (int)(soff), 0, 0); } while (0)
; #define PG8_LDA(dst, b, h) do { _Pragma("unroll") for (int m = 0; m < 4; ++m) _Pragma("unroll") for (int k = 0; k < 2; ++k) dst[m][k] = *(const PG8_LAS bf16x8*)(lds + PG8_SA(b, h) + aoff + m * 2048 + k * 1024); } while (0)
; #define PG8_LDB(dst, b, h) do { _Pragma("unroll") for (int n = 0; n < 2; ++n) _Pragma("unroll") for (int k = 0; k < 2; ++k) dst[n][k] = *(const PG8_LAS bf16x8*)(lds + PG8_SB(b, h) + boff + n * 2048 + k * 1024); } while (0)
; #define PG8_SCHED __builtin_amdgcn_sched_barrier(0)
; template <class Epi, class Sched, bool ALIGN_EPI = false, bool SP2 = false>
; __device__ __forceinline__ void gemm_phase(PG8_LAS unsigned char* lds, const Gemm g, const Sched& S, const Epi& E, const int wid  ) {
;     ...
;         const bool has_next = S.next(ui + 1, nxt); nxt.same = (has_next && nxt.pm == cur.pm) ? 1 : 0;
;         const unsigned nA = has_next ? (unsigned)g.asel(nxt.pn) * (unsigned)g.a_stride + (unsigned)nxt.pm * tstep : cA, nB = has_next ? (unsigned)nxt.pn * tstep : cB;
;         for (int t = 0; t < nt; t += 2) {
;             const bool last = (t == nt - 2);
;             const unsigned a1 = cA + (unsigned)(t + 1) * kstep;
;             const unsigned a2 = last ? nA : cA + (unsigned)(t + 2) * kstep, b2 = last ? nB : cB + (unsigned)(t + 2) * kstep;
;             const unsigned a3 = a2 + kstep, b3 = b2 + kstep;
;             if (last && has_next) S.a_ready(nxt);
;             if constexpr (SP2) {
;             PG8_LDB(B0, 0, 0); PG8_LDB(B1, 0, 1); PG8_SCHED; PG8_LDA(At, 0, 0); PG8_STAGE(PG8_SA(1, 1), a1 + hstep, voffA);
;     ...
; #pragma unroll
;         for (int a = 0; a < 2; ++a)
; #pragma unroll
;             for (int b = 0; b < 2; ++b)
; #pragma unroll
;                 for (int m = 0; m < 4; ++m)
; #pragma unroll
;                     for (int n = 0; n < 2; ++n) acc[a][b][m][n] = (f32x4){0.f, 0.f, 0.f, 0.f};
;         cur = nxt; cA = nA; cB = nB; ++ui;
.LBB0_203:
	s_lshl_b32 s60, s59, 20
	s_and_b64 s[14:15], s[4:5], exec
	s_cselect_b32 s63, s60, s65
	s_lshl_b32 s61, s58, 20
	s_and_b64 s[14:15], s[4:5], exec
	v_mov_b32_e32 v0, 0
	s_cselect_b32 s64, s61, s66
	s_add_i32 s65, s65, 0x80080
	s_addk_i32 s66, 0x100
	s_mov_b32 s67, -2
	v_mov_b32_e32 v1, v0
	s_waitcnt lgkmcnt(7)
	v_mov_b32_e32 v2, v0
	v_mov_b32_e32 v3, v0
	s_waitcnt lgkmcnt(6)
	v_mov_b32_e32 v4, v0
	v_mov_b32_e32 v5, v0
	s_waitcnt lgkmcnt(5)
	v_mov_b32_e32 v6, v0
	v_mov_b32_e32 v7, v0
	s_waitcnt lgkmcnt(2)
	v_mov_b32_e32 v12, v0
	v_mov_b32_e32 v13, v0
	s_waitcnt lgkmcnt(1)
	v_mov_b32_e32 v14, v0
	v_mov_b32_e32 v15, v0
	v_mov_b32_e32 v20, v0
	v_mov_b32_e32 v21, v0
	v_mov_b32_e32 v22, v0
	v_mov_b32_e32 v23, v0
	v_mov_b32_e32 v28, v0
	v_mov_b32_e32 v29, v0
	v_mov_b32_e32 v30, v0
	v_mov_b32_e32 v31, v0
	v_mov_b32_e32 v36, v0
	v_mov_b32_e32 v37, v0
	v_mov_b32_e32 v38, v0
	v_mov_b32_e32 v39, v0
	v_mov_b32_e32 v44, v0
	v_mov_b32_e32 v45, v0
	v_mov_b32_e32 v46, v0
	v_mov_b32_e32 v47, v0
	v_mov_b32_e32 v52, v0
	v_mov_b32_e32 v53, v0
	v_mov_b32_e32 v54, v0
	v_mov_b32_e32 v55, v0
	v_mov_b32_e32 v8, v0
	v_mov_b32_e32 v9, v0
	v_mov_b32_e32 v10, v0
	v_mov_b32_e32 v11, v0
	s_waitcnt lgkmcnt(0)
	v_mov_b32_e32 v16, v0
	v_mov_b32_e32 v17, v0
	s_waitcnt lgkmcnt(0)
	v_mov_b32_e32 v18, v0
	v_mov_b32_e32 v19, v0
	v_mov_b32_e32 v24, v0
	v_mov_b32_e32 v25, v0
	v_mov_b32_e32 v26, v0
	v_mov_b32_e32 v27, v0
	v_mov_b32_e32 v32, v0
	v_mov_b32_e32 v33, v0
	v_mov_b32_e32 v34, v0
	v_mov_b32_e32 v35, v0
	v_mov_b32_e32 v40, v0
	v_mov_b32_e32 v41, v0
	v_mov_b32_e32 v42, v0
	v_mov_b32_e32 v43, v0
	v_mov_b32_e32 v48, v0
	v_mov_b32_e32 v49, v0
	v_mov_b32_e32 v50, v0
	v_mov_b32_e32 v51, v0
	v_mov_b32_e32 v56, v0
	v_mov_b32_e32 v57, v0
	v_mov_b32_e32 v58, v0
	v_mov_b32_e32 v59, v0
	v_mov_b32_e32 v60, v0
	v_mov_b32_e32 v61, v0
	v_mov_b32_e32 v62, v0
	v_mov_b32_e32 v63, v0
	v_mov_b32_e32 v64, v0
	v_mov_b32_e32 v65, v0
	v_mov_b32_e32 v66, v0
	v_mov_b32_e32 v67, v0
	v_mov_b32_e32 v68, v0
	v_mov_b32_e32 v69, v0
	v_mov_b32_e32 v70, v0
	v_mov_b32_e32 v71, v0
	v_mov_b32_e32 v76, v0
	v_mov_b32_e32 v77, v0
	v_mov_b32_e32 v78, v0
	v_mov_b32_e32 v79, v0
	v_mov_b32_e32 v84, v0
	v_mov_b32_e32 v85, v0
	v_mov_b32_e32 v86, v0
	v_mov_b32_e32 v87, v0
	v_mov_b32_e32 v92, v0
	v_mov_b32_e32 v93, v0
	v_mov_b32_e32 v94, v0
	v_mov_b32_e32 v95, v0
	v_mov_b32_e32 v100, v0
	v_mov_b32_e32 v101, v0
	v_mov_b32_e32 v102, v0
	v_mov_b32_e32 v103, v0
	v_mov_b32_e32 v108, v0
	v_mov_b32_e32 v109, v0
	v_mov_b32_e32 v110, v0
	v_mov_b32_e32 v111, v0
	v_mov_b32_e32 v116, v0
	v_mov_b32_e32 v117, v0
	v_mov_b32_e32 v118, v0
	v_mov_b32_e32 v119, v0
	v_mov_b32_e32 v72, v0
	v_mov_b32_e32 v73, v0
	v_mov_b32_e32 v74, v0
	v_mov_b32_e32 v75, v0
	v_mov_b32_e32 v80, v0
	v_mov_b32_e32 v81, v0
	v_mov_b32_e32 v82, v0
	v_mov_b32_e32 v83, v0
	v_mov_b32_e32 v88, v0
	v_mov_b32_e32 v89, v0
	v_mov_b32_e32 v90, v0
	v_mov_b32_e32 v91, v0
	v_mov_b32_e32 v96, v0
	v_mov_b32_e32 v97, v0
	v_mov_b32_e32 v98, v0
	v_mov_b32_e32 v99, v0
	v_mov_b32_e32 v104, v0
	v_mov_b32_e32 v105, v0
	v_mov_b32_e32 v106, v0
	v_mov_b32_e32 v107, v0
	v_mov_b32_e32 v112, v0
	v_mov_b32_e32 v113, v0
	v_mov_b32_e32 v114, v0
	v_mov_b32_e32 v115, v0
	v_mov_b32_e32 v120, v0
	v_mov_b32_e32 v121, v0
	v_mov_b32_e32 v122, v0
	v_mov_b32_e32 v123, v0
	v_mov_b32_e32 v124, v0
	v_mov_b32_e32 v125, v0
	v_mov_b32_e32 v126, v0
	v_mov_b32_e32 v127, v0
	v_readlane_b32 vcc_lo, v246, 6
	s_nop 1
	s_cmp_ge_u32 vcc_lo, 4
	s_cbranch_scc0 .Lprio_204
	s_setprio 1
.Lprio_204:
.LBB0_204:
	ds_read_b128 v[132:135], v144
	ds_read_b128 v[150:153], v144 offset:1024
	ds_read_b128 v[154:157], v144 offset:2048
	ds_read_b128 v[158:161], v144 offset:3072
	ds_read_b128 v[162:165], v145
	ds_read_b128 v[166:169], v145 offset:1024
	ds_read_b128 v[170:173], v145 offset:2048
	ds_read_b128 v[174:177], v145 offset:3072
	s_add_i32 s14, s65, 0xfff80080
	s_cmp_eq_u32 s67, 28
	s_cselect_b32 s70, s63, s14
	s_cselect_b32 s69, s64, s66
	s_or_b32 s68, s70, 0x80
	s_mov_b32 m0, s47
	ds_read_b128 v[178:181], v146
	ds_read_b128 v[182:185], v146 offset:1024
	ds_read_b128 v[186:189], v146 offset:2048
	ds_read_b128 v[190:193], v146 offset:3072
	ds_read_b128 v[194:197], v146 offset:4096
	ds_read_b128 v[198:201], v146 offset:5120
	ds_read_b128 v[202:205], v146 offset:6144
	ds_read_b128 v[206:209], v146 offset:7168
	buffer_load_dwordx4 v138, s[8:11], s65 offen lds
	s_mov_b32 m0, s48
	s_nop 0
	buffer_load_dwordx4 v140, s[8:11], s65 offen lds
	s_waitcnt vmcnt(8)
	s_waitcnt lgkmcnt(0)
	s_barrier
; #define PG8_STAGE(bufoff, soff, voff) do { _Pragma("unroll") for (int _i = 0; _i < 2; ++_i) \
;         __builtin_amdgcn_raw_ptr_buffer_load_lds(rs_##voff, (PG8_LAS unsigned*)(lds + (bufoff) + ldsw + _i * 8192), 16, (int)(voff)[_i], (int)(soff), 0, 0); } while (0)
; #define PG8_LDA(dst, b, h) do { _Pragma("unroll") for (int m = 0; m < 4; ++m) _Pragma("unroll") for (int k = 0; k < 2; ++k) dst[m][k] = *(const PG8_LAS bf16x8*)(lds + PG8_SA(b, h) + aoff + m * 2048 + k * 1024); } while (0)
; #define PG8_MMA(ai, bj, At, Bt) do { __builtin_amdgcn_s_setprio(1); _Pragma("unroll") for (int m = 0; m < 4; ++m) _Pragma("unroll") for (int n = 0; n < 2; ++n) _Pragma("unroll") for (int k = 0; k < 2; ++k) \
;         acc[ai][bj][m][n] = __builtin_amdgcn_mfma_f32_16x16x32_bf16(Bt[n][k], At[m][k], acc[ai][bj][m][n], 0, 0, 0); __builtin_amdgcn_s_setprio(0); } while (0)
; #define PG8_WAIT_V(n) asm volatile("s_waitcnt vmcnt(" #n ")" ::: "memory")
; #define PG8_WAIT_L(n) asm volatile("s_waitcnt lgkmcnt(" #n ")" ::: "memory")
; #define PG8_BAR __builtin_amdgcn_s_barrier()
; #define PG8_SCHED __builtin_amdgcn_sched_barrier(0)
; template <class Epi, class Sched, bool ALIGN_EPI = false, bool SP2 = false>
; __device__ __forceinline__ void gemm_phase(PG8_LAS unsigned char* lds, const Gemm g, const Sched& S, const Epi& E, const int wid  ) {
;     ...
;             PG8_WAIT_V(8); PG8_WAIT_L(0); PG8_BAR; PG8_MMA(0, 0, At, B0); PG8_MMA(0, 1, At, B1); PG8_BAR; PG8_SCHED;
;             PG8_LDA(At, 0, 1); PG8_STAGE(PG8_SB(0, 0), b2, voffB); PG8_STAGE(PG8_SB(0, 1), b2 + hstep, voffB); PG8_STAGE(PG8_SA(0, 0), a2, voffA);
;             PG8_WAIT_V(8); PG8_WAIT_L(0); PG8_BAR; PG8_MMA(1, 0, At, B0); PG8_MMA(1, 1, At, B1); PG8_BAR; PG8_SCHED;
	s_waitcnt lgkmcnt(7)
	v_mfma_f32_16x16x32_bf16 v[124:127], v[132:135], v[178:181], v[124:127]
	v_mfma_f32_16x16x32_bf16 v[120:123], v[154:157], v[178:181], v[120:123]
	s_waitcnt lgkmcnt(5)
	v_mfma_f32_16x16x32_bf16 v[112:115], v[132:135], v[186:189], v[112:115]
	v_mfma_f32_16x16x32_bf16 v[104:107], v[154:157], v[186:189], v[104:107]
	s_waitcnt lgkmcnt(3)
	v_mfma_f32_16x16x32_bf16 v[96:99], v[132:135], v[194:197], v[96:99]
	v_mfma_f32_16x16x32_bf16 v[88:91], v[154:157], v[194:197], v[88:91]
	s_waitcnt lgkmcnt(1)
	v_mfma_f32_16x16x32_bf16 v[80:83], v[132:135], v[202:205], v[80:83]
	v_mfma_f32_16x16x32_bf16 v[72:75], v[154:157], v[202:205], v[72:75]
	v_mfma_f32_16x16x32_bf16 v[124:127], v[150:153], v[182:185], v[124:127]
	v_mfma_f32_16x16x32_bf16 v[120:123], v[158:161], v[182:185], v[120:123]
	v_mfma_f32_16x16x32_bf16 v[112:115], v[150:153], v[190:193], v[112:115]
	v_mfma_f32_16x16x32_bf16 v[104:107], v[158:161], v[190:193], v[104:107]
	v_mfma_f32_16x16x32_bf16 v[96:99], v[150:153], v[198:201], v[96:99]
	v_mfma_f32_16x16x32_bf16 v[88:91], v[158:161], v[198:201], v[88:91]
	s_waitcnt lgkmcnt(0)
	v_mfma_f32_16x16x32_bf16 v[80:83], v[150:153], v[206:209], v[80:83]
	v_mfma_f32_16x16x32_bf16 v[72:75], v[158:161], v[206:209], v[72:75]
	v_mfma_f32_16x16x32_bf16 v[116:119], v[162:165], v[178:181], v[116:119]
	v_mfma_f32_16x16x32_bf16 v[108:111], v[170:173], v[178:181], v[108:111]
	v_mfma_f32_16x16x32_bf16 v[100:103], v[162:165], v[186:189], v[100:103]
	v_mfma_f32_16x16x32_bf16 v[92:95], v[170:173], v[186:189], v[92:95]
	v_mfma_f32_16x16x32_bf16 v[84:87], v[162:165], v[194:197], v[84:87]
	v_mfma_f32_16x16x32_bf16 v[76:79], v[170:173], v[194:197], v[76:79]
	v_mfma_f32_16x16x32_bf16 v[68:71], v[162:165], v[202:205], v[68:71]
	v_mfma_f32_16x16x32_bf16 v[64:67], v[170:173], v[202:205], v[64:67]
	v_mfma_f32_16x16x32_bf16 v[116:119], v[166:169], v[182:185], v[116:119]
	v_mfma_f32_16x16x32_bf16 v[108:111], v[174:177], v[182:185], v[108:111]
	v_mfma_f32_16x16x32_bf16 v[100:103], v[166:169], v[190:193], v[100:103]
	v_mfma_f32_16x16x32_bf16 v[92:95], v[174:177], v[190:193], v[92:95]
	v_mfma_f32_16x16x32_bf16 v[84:87], v[166:169], v[198:201], v[84:87]
	v_mfma_f32_16x16x32_bf16 v[76:79], v[174:177], v[198:201], v[76:79]
	v_mfma_f32_16x16x32_bf16 v[68:71], v[166:169], v[206:209], v[68:71]
	v_mfma_f32_16x16x32_bf16 v[64:67], v[174:177], v[206:209], v[64:67]
	s_barrier
	s_mov_b32 m0, s30
	s_mov_b32 s14, s10
	s_mov_b32 s15, s11
	ds_read_b128 v[178:181], v146 offset:16384
	ds_read_b128 v[182:185], v146 offset:17408
	ds_read_b128 v[186:189], v146 offset:18432
	ds_read_b128 v[190:193], v146 offset:19456
	ds_read_b128 v[194:197], v146 offset:20480
	ds_read_b128 v[198:201], v146 offset:21504
	ds_read_b128 v[202:205], v146 offset:22528
	ds_read_b128 v[206:209], v146 offset:23552
	buffer_load_dwordx4 v139, s[12:15], s69 offen lds
	s_mov_b32 m0, s31
	s_add_i32 s71, s69, 0x80000
	buffer_load_dwordx4 v141, s[12:15], s69 offen lds
	s_mov_b32 m0, s33
	s_nop 0
	buffer_load_dwordx4 v139, s[12:15], s71 offen lds
	s_mov_b32 m0, s34
	s_nop 0
	buffer_load_dwordx4 v141, s[12:15], s71 offen lds
	s_mov_b32 m0, s29
	s_nop 0
	buffer_load_dwordx4 v138, s[8:11], s70 offen lds
	s_mov_b32 m0, s35
	s_nop 0
	buffer_load_dwordx4 v140, s[8:11], s70 offen lds
	s_waitcnt vmcnt(8)
	s_waitcnt lgkmcnt(0)
	s_barrier
	s_waitcnt lgkmcnt(7)
	v_mfma_f32_16x16x32_bf16 v[60:63], v[132:135], v[178:181], v[60:63]
	v_mfma_f32_16x16x32_bf16 v[56:59], v[154:157], v[178:181], v[56:59]
	s_waitcnt lgkmcnt(5)
	v_mfma_f32_16x16x32_bf16 v[48:51], v[132:135], v[186:189], v[48:51]
	v_mfma_f32_16x16x32_bf16 v[40:43], v[154:157], v[186:189], v[40:43]
	s_waitcnt lgkmcnt(3)
	v_mfma_f32_16x16x32_bf16 v[32:35], v[132:135], v[194:197], v[32:35]
	v_mfma_f32_16x16x32_bf16 v[24:27], v[154:157], v[194:197], v[24:27]
	s_waitcnt lgkmcnt(1)
	v_mfma_f32_16x16x32_bf16 v[16:19], v[132:135], v[202:205], v[16:19]
	v_mfma_f32_16x16x32_bf16 v[8:11], v[154:157], v[202:205], v[8:11]
	v_mfma_f32_16x16x32_bf16 v[60:63], v[150:153], v[182:185], v[60:63]
	v_mfma_f32_16x16x32_bf16 v[56:59], v[158:161], v[182:185], v[56:59]
	v_mfma_f32_16x16x32_bf16 v[48:51], v[150:153], v[190:193], v[48:51]
	v_mfma_f32_16x16x32_bf16 v[40:43], v[158:161], v[190:193], v[40:43]
	v_mfma_f32_16x16x32_bf16 v[32:35], v[150:153], v[198:201], v[32:35]
	v_mfma_f32_16x16x32_bf16 v[24:27], v[158:161], v[198:201], v[24:27]
	s_waitcnt lgkmcnt(0)
	v_mfma_f32_16x16x32_bf16 v[16:19], v[150:153], v[206:209], v[16:19]
	v_mfma_f32_16x16x32_bf16 v[8:11], v[158:161], v[206:209], v[8:11]
	v_mfma_f32_16x16x32_bf16 v[52:55], v[162:165], v[178:181], v[52:55]
	v_mfma_f32_16x16x32_bf16 v[44:47], v[170:173], v[178:181], v[44:47]
	v_mfma_f32_16x16x32_bf16 v[36:39], v[162:165], v[186:189], v[36:39]
	v_mfma_f32_16x16x32_bf16 v[28:31], v[170:173], v[186:189], v[28:31]
	v_mfma_f32_16x16x32_bf16 v[20:23], v[162:165], v[194:197], v[20:23]
	v_mfma_f32_16x16x32_bf16 v[12:15], v[170:173], v[194:197], v[12:15]
	v_mfma_f32_16x16x32_bf16 v[4:7], v[162:165], v[202:205], v[4:7]
	v_mfma_f32_16x16x32_bf16 v[0:3], v[170:173], v[202:205], v[0:3]
	v_mfma_f32_16x16x32_bf16 v[52:55], v[166:169], v[182:185], v[52:55]
	v_mfma_f32_16x16x32_bf16 v[44:47], v[174:177], v[182:185], v[44:47]
	v_mfma_f32_16x16x32_bf16 v[36:39], v[166:169], v[190:193], v[36:39]
	v_mfma_f32_16x16x32_bf16 v[28:31], v[174:177], v[190:193], v[28:31]
	v_mfma_f32_16x16x32_bf16 v[20:23], v[166:169], v[198:201], v[20:23]
	v_mfma_f32_16x16x32_bf16 v[12:15], v[174:177], v[198:201], v[12:15]
	v_mfma_f32_16x16x32_bf16 v[4:7], v[166:169], v[206:209], v[4:7]
	v_mfma_f32_16x16x32_bf16 v[0:3], v[174:177], v[206:209], v[0:3]
	s_barrier
; #define PG8_STAGE(bufoff, soff, voff) do { _Pragma("unroll") for (int _i = 0; _i < 2; ++_i) \
;         __builtin_amdgcn_raw_ptr_buffer_load_lds(rs_##voff, (PG8_LAS unsigned*)(lds + (bufoff) + ldsw + _i * 8192), 16, (int)(voff)[_i], (int)(soff), 0, 0); } while (0)
; #define PG8_LDA(dst, b, h) do { _Pragma("unroll") for (int m = 0; m < 4; ++m) _Pragma("unroll") for (int k = 0; k < 2; ++k) dst[m][k] = *(const PG8_LAS bf16x8*)(lds + PG8_SA(b, h) + aoff + m * 2048 + k * 1024); } while (0)
; #define PG8_LDB(dst, b, h) do { _Pragma("unroll") for (int n = 0; n < 2; ++n) _Pragma("unroll") for (int k = 0; k < 2; ++k) dst[n][k] = *(const PG8_LAS bf16x8*)(lds + PG8_SB(b, h) + boff + n * 2048 + k * 1024); } while (0)
; #define PG8_MMA(ai, bj, At, Bt) do { __builtin_amdgcn_s_setprio(1); _Pragma("unroll") for (int m = 0; m < 4; ++m) _Pragma("unroll") for (int n = 0; n < 2; ++n) _Pragma("unroll") for (int k = 0; k < 2; ++k) \
;         acc[ai][bj][m][n] = __builtin_amdgcn_mfma_f32_16x16x32_bf16(Bt[n][k], At[m][k], acc[ai][bj][m][n], 0, 0, 0); __builtin_amdgcn_s_setprio(0); } while (0)
; #define PG8_WAIT_V(n) asm volatile("s_waitcnt vmcnt(" #n ")" ::: "memory")
; #define PG8_WAIT_L(n) asm volatile("s_waitcnt lgkmcnt(" #n ")" ::: "memory")
; #define PG8_BAR __builtin_amdgcn_s_barrier()
; #define PG8_SCHED __builtin_amdgcn_sched_barrier(0)
; template <class Epi, class Sched, bool ALIGN_EPI = false, bool SP2 = false>
; __device__ __forceinline__ void gemm_phase(PG8_LAS unsigned char* lds, const Gemm g, const Sched& S, const Epi& E, const int wid  ) {
;     ...
;             PG8_LDB(B0, 1, 0); PG8_LDB(B1, 1, 1); PG8_SCHED; PG8_LDA(At, 1, 0); PG8_STAGE(PG8_SA(0, 1), a2 + hstep, voffA);
;             PG8_WAIT_V(8); PG8_WAIT_L(0); PG8_BAR; PG8_MMA(0, 0, At, B0); PG8_MMA(0, 1, At, B1); PG8_BAR; PG8_SCHED;
;             PG8_LDA(At, 1, 1); PG8_STAGE(PG8_SB(1, 0), b3, voffB); PG8_STAGE(PG8_SB(1, 1), b3 + hstep, voffB); PG8_STAGE(PG8_SA(1, 0), a3, voffA);
;             PG8_WAIT_V(8); PG8_WAIT_L(0); PG8_BAR; PG8_MMA(1, 0, At, B0); PG8_MMA(1, 1, At, B1); PG8_BAR; PG8_SCHED;
	ds_read_b128 v[132:135], v147
	ds_read_b128 v[150:153], v147 offset:1024
	ds_read_b128 v[154:157], v147 offset:2048
	ds_read_b128 v[158:161], v147 offset:3072
	ds_read_b128 v[162:165], v148
	ds_read_b128 v[166:169], v148 offset:1024
	ds_read_b128 v[170:173], v148 offset:2048
	ds_read_b128 v[174:177], v148 offset:3072
	s_add_i32 s70, s70, 0x80000
	s_mov_b32 m0, s36
	ds_read_b128 v[178:181], v146 offset:32768
	ds_read_b128 v[182:185], v146 offset:33792
	ds_read_b128 v[186:189], v146 offset:34816
	ds_read_b128 v[190:193], v146 offset:35840
	ds_read_b128 v[194:197], v146 offset:36864
	ds_read_b128 v[198:201], v146 offset:37888
	ds_read_b128 v[202:205], v146 offset:38912
	ds_read_b128 v[206:209], v146 offset:39936
	buffer_load_dwordx4 v138, s[8:11], s70 offen lds
	s_mov_b32 m0, s37
	s_nop 0
	buffer_load_dwordx4 v140, s[8:11], s70 offen lds
	s_waitcnt vmcnt(8)
	s_waitcnt lgkmcnt(0)
	s_barrier
	s_waitcnt lgkmcnt(7)
	v_mfma_f32_16x16x32_bf16 v[124:127], v[132:135], v[178:181], v[124:127]
	v_mfma_f32_16x16x32_bf16 v[120:123], v[154:157], v[178:181], v[120:123]
	s_waitcnt lgkmcnt(5)
	v_mfma_f32_16x16x32_bf16 v[112:115], v[132:135], v[186:189], v[112:115]
	v_mfma_f32_16x16x32_bf16 v[104:107], v[154:157], v[186:189], v[104:107]
	s_waitcnt lgkmcnt(3)
	v_mfma_f32_16x16x32_bf16 v[96:99], v[132:135], v[194:197], v[96:99]
	v_mfma_f32_16x16x32_bf16 v[88:91], v[154:157], v[194:197], v[88:91]
	s_waitcnt lgkmcnt(1)
	v_mfma_f32_16x16x32_bf16 v[80:83], v[132:135], v[202:205], v[80:83]
	v_mfma_f32_16x16x32_bf16 v[72:75], v[154:157], v[202:205], v[72:75]
	v_mfma_f32_16x16x32_bf16 v[124:127], v[150:153], v[182:185], v[124:127]
	v_mfma_f32_16x16x32_bf16 v[120:123], v[158:161], v[182:185], v[120:123]
	v_mfma_f32_16x16x32_bf16 v[112:115], v[150:153], v[190:193], v[112:115]
	v_mfma_f32_16x16x32_bf16 v[104:107], v[158:161], v[190:193], v[104:107]
	v_mfma_f32_16x16x32_bf16 v[96:99], v[150:153], v[198:201], v[96:99]
	v_mfma_f32_16x16x32_bf16 v[88:91], v[158:161], v[198:201], v[88:91]
	s_waitcnt lgkmcnt(0)
	v_mfma_f32_16x16x32_bf16 v[80:83], v[150:153], v[206:209], v[80:83]
	v_mfma_f32_16x16x32_bf16 v[72:75], v[158:161], v[206:209], v[72:75]
	v_mfma_f32_16x16x32_bf16 v[116:119], v[162:165], v[178:181], v[116:119]
	v_mfma_f32_16x16x32_bf16 v[108:111], v[170:173], v[178:181], v[108:111]
	v_mfma_f32_16x16x32_bf16 v[100:103], v[162:165], v[186:189], v[100:103]
	v_mfma_f32_16x16x32_bf16 v[92:95], v[170:173], v[186:189], v[92:95]
	v_mfma_f32_16x16x32_bf16 v[84:87], v[162:165], v[194:197], v[84:87]
	v_mfma_f32_16x16x32_bf16 v[76:79], v[170:173], v[194:197], v[76:79]
	v_mfma_f32_16x16x32_bf16 v[68:71], v[162:165], v[202:205], v[68:71]
	v_mfma_f32_16x16x32_bf16 v[64:67], v[170:173], v[202:205], v[64:67]
	v_mfma_f32_16x16x32_bf16 v[116:119], v[166:169], v[182:185], v[116:119]
	v_mfma_f32_16x16x32_bf16 v[108:111], v[174:177], v[182:185], v[108:111]
	v_mfma_f32_16x16x32_bf16 v[100:103], v[166:169], v[190:193], v[100:103]
	v_mfma_f32_16x16x32_bf16 v[92:95], v[174:177], v[190:193], v[92:95]
	v_mfma_f32_16x16x32_bf16 v[84:87], v[166:169], v[198:201], v[84:87]
	v_mfma_f32_16x16x32_bf16 v[76:79], v[174:177], v[198:201], v[76:79]
	v_mfma_f32_16x16x32_bf16 v[68:71], v[166:169], v[206:209], v[68:71]
	v_mfma_f32_16x16x32_bf16 v[64:67], v[174:177], v[206:209], v[64:67]
	s_barrier
	s_mov_b32 m0, s40
	s_or_b32 s70, s69, 0x80
	ds_read_b128 v[178:181], v146 offset:49152
	ds_read_b128 v[182:185], v146 offset:50176
	ds_read_b128 v[186:189], v146 offset:51200
	ds_read_b128 v[190:193], v146 offset:52224
	ds_read_b128 v[194:197], v146 offset:53248
	ds_read_b128 v[198:201], v146 offset:54272
	ds_read_b128 v[202:205], v146 offset:55296
	ds_read_b128 v[206:209], v146 offset:56320
	buffer_load_dwordx4 v139, s[12:15], s70 offen lds
	s_mov_b32 m0, s41
	s_add_i32 s69, s69, 0x80080
	buffer_load_dwordx4 v141, s[12:15], s70 offen lds
	s_mov_b32 m0, s44
	s_nop 0
	buffer_load_dwordx4 v139, s[12:15], s69 offen lds
	s_mov_b32 m0, s45
	s_nop 0
	buffer_load_dwordx4 v141, s[12:15], s69 offen lds
	s_mov_b32 m0, s42
	s_nop 0
	buffer_load_dwordx4 v138, s[8:11], s68 offen lds
	s_mov_b32 m0, s43
	s_nop 0
	buffer_load_dwordx4 v140, s[8:11], s68 offen lds
	s_waitcnt vmcnt(8)
	s_waitcnt lgkmcnt(0)
	s_barrier
	s_waitcnt lgkmcnt(7)
	v_mfma_f32_16x16x32_bf16 v[60:63], v[132:135], v[178:181], v[60:63]
	v_mfma_f32_16x16x32_bf16 v[56:59], v[154:157], v[178:181], v[56:59]
	s_waitcnt lgkmcnt(5)
	v_mfma_f32_16x16x32_bf16 v[48:51], v[132:135], v[186:189], v[48:51]
	v_mfma_f32_16x16x32_bf16 v[40:43], v[154:157], v[186:189], v[40:43]
	s_waitcnt lgkmcnt(3)
	v_mfma_f32_16x16x32_bf16 v[32:35], v[132:135], v[194:197], v[32:35]
	v_mfma_f32_16x16x32_bf16 v[24:27], v[154:157], v[194:197], v[24:27]
	s_waitcnt lgkmcnt(1)
	v_mfma_f32_16x16x32_bf16 v[16:19], v[132:135], v[202:205], v[16:19]
	v_mfma_f32_16x16x32_bf16 v[8:11], v[154:157], v[202:205], v[8:11]
	v_mfma_f32_16x16x32_bf16 v[60:63], v[150:153], v[182:185], v[60:63]
	v_mfma_f32_16x16x32_bf16 v[56:59], v[158:161], v[182:185], v[56:59]
	v_mfma_f32_16x16x32_bf16 v[48:51], v[150:153], v[190:193], v[48:51]
	v_mfma_f32_16x16x32_bf16 v[40:43], v[158:161], v[190:193], v[40:43]
	v_mfma_f32_16x16x32_bf16 v[32:35], v[150:153], v[198:201], v[32:35]
	v_mfma_f32_16x16x32_bf16 v[24:27], v[158:161], v[198:201], v[24:27]
	s_waitcnt lgkmcnt(0)
	v_mfma_f32_16x16x32_bf16 v[16:19], v[150:153], v[206:209], v[16:19]
	v_mfma_f32_16x16x32_bf16 v[8:11], v[158:161], v[206:209], v[8:11]
	v_mfma_f32_16x16x32_bf16 v[52:55], v[162:165], v[178:181], v[52:55]
	v_mfma_f32_16x16x32_bf16 v[44:47], v[170:173], v[178:181], v[44:47]
	v_mfma_f32_16x16x32_bf16 v[36:39], v[162:165], v[186:189], v[36:39]
	v_mfma_f32_16x16x32_bf16 v[28:31], v[170:173], v[186:189], v[28:31]
	v_mfma_f32_16x16x32_bf16 v[20:23], v[162:165], v[194:197], v[20:23]
	v_mfma_f32_16x16x32_bf16 v[12:15], v[170:173], v[194:197], v[12:15]
	v_mfma_f32_16x16x32_bf16 v[4:7], v[162:165], v[202:205], v[4:7]
	v_mfma_f32_16x16x32_bf16 v[0:3], v[170:173], v[202:205], v[0:3]
	v_mfma_f32_16x16x32_bf16 v[52:55], v[166:169], v[182:185], v[52:55]
	v_mfma_f32_16x16x32_bf16 v[44:47], v[174:177], v[182:185], v[44:47]
	v_mfma_f32_16x16x32_bf16 v[36:39], v[166:169], v[190:193], v[36:39]
	v_mfma_f32_16x16x32_bf16 v[28:31], v[174:177], v[190:193], v[28:31]
	v_mfma_f32_16x16x32_bf16 v[20:23], v[166:169], v[198:201], v[20:23]
	v_mfma_f32_16x16x32_bf16 v[12:15], v[174:177], v[198:201], v[12:15]
	v_mfma_f32_16x16x32_bf16 v[4:7], v[166:169], v[206:209], v[4:7]
	v_mfma_f32_16x16x32_bf16 v[0:3], v[174:177], v[206:209], v[0:3]
	s_barrier
	s_add_i32 s67, s67, 2
	s_addk_i32 s65, 0x100
	s_addk_i32 s66, 0x100
	s_cmp_gt_u32 s67, 29
	s_cbranch_scc0 .LBB0_204
	s_setprio 0
	s_and_b64 vcc, exec, s[18:19]
	s_cbranch_vccz .LBB0_207
	s_barrier

; #define PG8_STAGE(bufoff, soff, voff) do { _Pragma("unroll") for (int _i = 0; _i < 2; ++_i) \
;         __builtin_amdgcn_raw_ptr_buffer_load_lds(rs_##voff, (PG8_LAS unsigned*)(lds + (bufoff) + ldsw + _i * 8192), 16, (int)(voff)[_i], (int)(soff), 0, 0); } while (0)
; #define PG8_LDA(dst, b, h) do { _Pragma("unroll") for (int m = 0; m < 4; ++m) _Pragma("unroll") for (int k = 0; k < 2; ++k) dst[m][k] = *(const PG8_LAS bf16x8*)(lds + PG8_SA(b, h) + aoff + m * 2048 + k * 1024); } while (0)
; #define PG8_LDB(dst, b, h) do { _Pragma("unroll") for (int n = 0; n < 2; ++n) _Pragma("unroll") for (int k = 0; k < 2; ++k) dst[n][k] = *(const PG8_LAS bf16x8*)(lds + PG8_SB(b, h) + boff + n * 2048 + k * 1024); } while (0)
; #define PG8_WAIT_V(n) asm volatile("s_waitcnt vmcnt(" #n ")" ::: "memory")
; #define PG8_WAIT_L(n) asm volatile("s_waitcnt lgkmcnt(" #n ")" ::: "memory")
; template <class Epi, class Sched, bool ALIGN_EPI = false, bool SP2 = false>
; __device__ __forceinline__ void gemm_phase(PG8_LAS unsigned char* lds, const Gemm g, const Sched& S, const Epi& E, const int wid  ) {
;     ...
;         const bool has_next = S.next(ui + 1, nxt); nxt.same = (has_next && nxt.pm == cur.pm) ? 1 : 0;
;         const unsigned nA = has_next ? (unsigned)g.asel(nxt.pn) * (unsigned)g.a_stride + (unsigned)nxt.pm * tstep : cA, nB = has_next ? (unsigned)nxt.pn * tstep : cB;
;         for (int t = 0; t < nt; t += 2) {
;             const bool last = (t == nt - 2);
;             const unsigned a1 = cA + (unsigned)(t + 1) * kstep;
;             const unsigned a2 = last ? nA : cA + (unsigned)(t + 2) * kstep, b2 = last ? nB : cB + (unsigned)(t + 2) * kstep;
;             const unsigned a3 = a2 + kstep, b3 = b2 + kstep;
;             if (last && has_next) S.a_ready(nxt);
;             if constexpr (SP2) {
;             PG8_LDB(B0, 0, 0); PG8_LDB(B1, 0, 1); PG8_SCHED; PG8_LDA(At, 0, 0); PG8_STAGE(PG8_SA(1, 1), a1 + hstep, voffA);
;             PG8_WAIT_V(8); PG8_WAIT_L(0); PG8_BAR; PG8_MMA(0, 0, At, B0); PG8_MMA(0, 1, At, B1); PG8_BAR; PG8_SCHED;
;     ...
; #pragma unroll
;         for (int a = 0; a < 2; ++a)
; #pragma unroll
;             for (int b = 0; b < 2; ++b)
; #pragma unroll
;                 for (int m = 0; m < 4; ++m)
; #pragma unroll
;                     for (int n = 0; n < 2; ++n) acc[a][b][m][n] = (f32x4){0.f, 0.f, 0.f, 0.f};
;         cur = nxt; cA = nA; cB = nB; ++ui;
.LBB0_563:
	s_lshl_b32 s50, s49, 20
	s_and_b64 s[0:1], s[4:5], exec
	s_cselect_b32 s0, s50, s54
	s_lshl_b32 s51, s48, 20
	s_and_b64 s[14:15], s[4:5], exec
	v_mov_b32_e32 v0, 0
	s_cselect_b32 s1, s51, s55
	s_add_i32 s54, s54, 0x80080
	s_addk_i32 s55, 0x100
	s_mov_b32 s58, -2
	s_waitcnt lgkmcnt(0)
	v_mov_b32_e32 v1, v0
	v_mov_b32_e32 v2, v0
	v_mov_b32_e32 v3, v0
	v_mov_b32_e32 v4, v0
	v_mov_b32_e32 v5, v0
	v_mov_b32_e32 v6, v0
	v_mov_b32_e32 v7, v0
	v_mov_b32_e32 v16, v0
	v_mov_b32_e32 v17, v0
	v_mov_b32_e32 v18, v0
	v_mov_b32_e32 v19, v0
	v_mov_b32_e32 v20, v0
	v_mov_b32_e32 v21, v0
	v_mov_b32_e32 v22, v0
	v_mov_b32_e32 v23, v0
	v_mov_b32_e32 v32, v0
	v_mov_b32_e32 v33, v0
	v_mov_b32_e32 v34, v0
	v_mov_b32_e32 v35, v0
	v_mov_b32_e32 v36, v0
	v_mov_b32_e32 v37, v0
	v_mov_b32_e32 v38, v0
	v_mov_b32_e32 v39, v0
	v_mov_b32_e32 v48, v0
	v_mov_b32_e32 v49, v0
	v_mov_b32_e32 v50, v0
	v_mov_b32_e32 v51, v0
	v_mov_b32_e32 v52, v0
	v_mov_b32_e32 v53, v0
	v_mov_b32_e32 v54, v0
	v_mov_b32_e32 v55, v0
	v_mov_b32_e32 v8, v0
	v_mov_b32_e32 v9, v0
	v_mov_b32_e32 v10, v0
	v_mov_b32_e32 v11, v0
	v_mov_b32_e32 v12, v0
	v_mov_b32_e32 v13, v0
	v_mov_b32_e32 v14, v0
	v_mov_b32_e32 v15, v0
	v_mov_b32_e32 v24, v0
	v_mov_b32_e32 v25, v0
	v_mov_b32_e32 v26, v0
	v_mov_b32_e32 v27, v0
	v_mov_b32_e32 v28, v0
	v_mov_b32_e32 v29, v0
	v_mov_b32_e32 v30, v0
	v_mov_b32_e32 v31, v0
	v_mov_b32_e32 v40, v0
	v_mov_b32_e32 v41, v0
	v_mov_b32_e32 v42, v0
	v_mov_b32_e32 v43, v0
	v_mov_b32_e32 v44, v0
	v_mov_b32_e32 v45, v0
	v_mov_b32_e32 v46, v0
	v_mov_b32_e32 v47, v0
	v_mov_b32_e32 v56, v0
	v_mov_b32_e32 v57, v0
	v_mov_b32_e32 v58, v0
	v_mov_b32_e32 v59, v0
	v_mov_b32_e32 v60, v0
	v_mov_b32_e32 v61, v0
	v_mov_b32_e32 v62, v0
	v_mov_b32_e32 v63, v0
	v_mov_b32_e32 v64, v0
	v_mov_b32_e32 v65, v0
	v_mov_b32_e32 v66, v0
	v_mov_b32_e32 v67, v0
	v_mov_b32_e32 v68, v0
	v_mov_b32_e32 v69, v0
	v_mov_b32_e32 v70, v0
	v_mov_b32_e32 v71, v0
	v_mov_b32_e32 v80, v0
	v_mov_b32_e32 v81, v0
	v_mov_b32_e32 v82, v0
	v_mov_b32_e32 v83, v0
	v_mov_b32_e32 v84, v0
	v_mov_b32_e32 v85, v0
	v_mov_b32_e32 v86, v0
	v_mov_b32_e32 v87, v0
	v_mov_b32_e32 v96, v0
	v_mov_b32_e32 v97, v0
	v_mov_b32_e32 v98, v0
	v_mov_b32_e32 v99, v0
	v_mov_b32_e32 v100, v0
	v_mov_b32_e32 v101, v0
	v_mov_b32_e32 v102, v0
	v_mov_b32_e32 v103, v0
	v_mov_b32_e32 v112, v0
	v_mov_b32_e32 v113, v0
	v_mov_b32_e32 v114, v0
	v_mov_b32_e32 v115, v0
	v_mov_b32_e32 v116, v0
	v_mov_b32_e32 v117, v0
	v_mov_b32_e32 v118, v0
	v_mov_b32_e32 v119, v0
	v_mov_b32_e32 v72, v0
	v_mov_b32_e32 v73, v0
	v_mov_b32_e32 v74, v0
	v_mov_b32_e32 v75, v0
	v_mov_b32_e32 v76, v0
	v_mov_b32_e32 v77, v0
	v_mov_b32_e32 v78, v0
	v_mov_b32_e32 v79, v0
	v_mov_b32_e32 v88, v0
	v_mov_b32_e32 v89, v0
	v_mov_b32_e32 v90, v0
	v_mov_b32_e32 v91, v0
	v_mov_b32_e32 v92, v0
	v_mov_b32_e32 v93, v0
	v_mov_b32_e32 v94, v0
	v_mov_b32_e32 v95, v0
	v_mov_b32_e32 v104, v0
	v_mov_b32_e32 v105, v0
	v_mov_b32_e32 v106, v0
	v_mov_b32_e32 v107, v0
	v_mov_b32_e32 v108, v0
	v_mov_b32_e32 v109, v0
	v_mov_b32_e32 v110, v0
	v_mov_b32_e32 v111, v0
	v_mov_b32_e32 v120, v0
	v_mov_b32_e32 v121, v0
	v_mov_b32_e32 v122, v0
	v_mov_b32_e32 v123, v0
	v_mov_b32_e32 v124, v0
	v_mov_b32_e32 v125, v0
	v_mov_b32_e32 v126, v0
	v_mov_b32_e32 v127, v0
	v_readlane_b32 vcc_lo, v246, 6
	s_nop 1
	s_cmp_ge_u32 vcc_lo, 4
	s_cbranch_scc0 .Lprio_564
	s_setprio 1
.Lprio_564:
.LBB0_564:
	ds_read_b128 v[132:135], v140
	ds_read_b128 v[146:149], v140 offset:1024
	ds_read_b128 v[150:153], v140 offset:2048
	ds_read_b128 v[154:157], v140 offset:3072
	ds_read_b128 v[158:161], v141
	ds_read_b128 v[162:165], v141 offset:1024
	ds_read_b128 v[166:169], v141 offset:2048
	ds_read_b128 v[170:173], v141 offset:3072
	s_add_i32 s14, s54, 0xfff80080
	s_cmp_eq_u32 s58, 28
	s_cselect_b32 s61, s0, s14
	s_cselect_b32 s60, s1, s55
	s_or_b32 s59, s61, 0x80
	s_mov_b32 m0, s43
	ds_read_b128 v[174:177], v142
	ds_read_b128 v[178:181], v142 offset:1024
	ds_read_b128 v[182:185], v142 offset:2048
	ds_read_b128 v[186:189], v142 offset:3072
	ds_read_b128 v[190:193], v142 offset:4096
	ds_read_b128 v[194:197], v142 offset:5120
	ds_read_b128 v[198:201], v142 offset:6144
	ds_read_b128 v[202:205], v142 offset:7168
	buffer_load_dwordx4 v136, s[8:11], s54 offen lds
	s_mov_b32 m0, s44
	s_nop 0
	buffer_load_dwordx4 v138, s[8:11], s54 offen lds
	s_waitcnt vmcnt(8)
	s_waitcnt lgkmcnt(0)
	s_barrier
	s_waitcnt lgkmcnt(7)
	v_mfma_f32_16x16x32_bf16 v[124:127], v[132:135], v[174:177], v[124:127]
	v_mfma_f32_16x16x32_bf16 v[120:123], v[150:153], v[174:177], v[120:123]
	s_waitcnt lgkmcnt(5)
	v_mfma_f32_16x16x32_bf16 v[108:111], v[132:135], v[182:185], v[108:111]
	v_mfma_f32_16x16x32_bf16 v[104:107], v[150:153], v[182:185], v[104:107]
	s_waitcnt lgkmcnt(3)
	v_mfma_f32_16x16x32_bf16 v[92:95], v[132:135], v[190:193], v[92:95]
	v_mfma_f32_16x16x32_bf16 v[88:91], v[150:153], v[190:193], v[88:91]
	s_waitcnt lgkmcnt(1)
	v_mfma_f32_16x16x32_bf16 v[76:79], v[132:135], v[198:201], v[76:79]
	v_mfma_f32_16x16x32_bf16 v[72:75], v[150:153], v[198:201], v[72:75]
	v_mfma_f32_16x16x32_bf16 v[124:127], v[146:149], v[178:181], v[124:127]
	v_mfma_f32_16x16x32_bf16 v[120:123], v[154:157], v[178:181], v[120:123]
	v_mfma_f32_16x16x32_bf16 v[108:111], v[146:149], v[186:189], v[108:111]
	v_mfma_f32_16x16x32_bf16 v[104:107], v[154:157], v[186:189], v[104:107]
	v_mfma_f32_16x16x32_bf16 v[92:95], v[146:149], v[194:197], v[92:95]
	v_mfma_f32_16x16x32_bf16 v[88:91], v[154:157], v[194:197], v[88:91]
	s_waitcnt lgkmcnt(0)
	v_mfma_f32_16x16x32_bf16 v[76:79], v[146:149], v[202:205], v[76:79]
	v_mfma_f32_16x16x32_bf16 v[72:75], v[154:157], v[202:205], v[72:75]
	v_mfma_f32_16x16x32_bf16 v[116:119], v[158:161], v[174:177], v[116:119]
	v_mfma_f32_16x16x32_bf16 v[112:115], v[166:169], v[174:177], v[112:115]
	v_mfma_f32_16x16x32_bf16 v[100:103], v[158:161], v[182:185], v[100:103]
	v_mfma_f32_16x16x32_bf16 v[96:99], v[166:169], v[182:185], v[96:99]
	v_mfma_f32_16x16x32_bf16 v[84:87], v[158:161], v[190:193], v[84:87]
	v_mfma_f32_16x16x32_bf16 v[80:83], v[166:169], v[190:193], v[80:83]
	v_mfma_f32_16x16x32_bf16 v[68:71], v[158:161], v[198:201], v[68:71]
	v_mfma_f32_16x16x32_bf16 v[64:67], v[166:169], v[198:201], v[64:67]
	v_mfma_f32_16x16x32_bf16 v[116:119], v[162:165], v[178:181], v[116:119]
	v_mfma_f32_16x16x32_bf16 v[112:115], v[170:173], v[178:181], v[112:115]
	v_mfma_f32_16x16x32_bf16 v[100:103], v[162:165], v[186:189], v[100:103]
	v_mfma_f32_16x16x32_bf16 v[96:99], v[170:173], v[186:189], v[96:99]
	v_mfma_f32_16x16x32_bf16 v[84:87], v[162:165], v[194:197], v[84:87]
	v_mfma_f32_16x16x32_bf16 v[80:83], v[170:173], v[194:197], v[80:83]
	v_mfma_f32_16x16x32_bf16 v[68:71], v[162:165], v[202:205], v[68:71]
	v_mfma_f32_16x16x32_bf16 v[64:67], v[170:173], v[202:205], v[64:67]
	s_barrier
; #define PG8_STAGE(bufoff, soff, voff) do { _Pragma("unroll") for (int _i = 0; _i < 2; ++_i) \
;         __builtin_amdgcn_raw_ptr_buffer_load_lds(rs_##voff, (PG8_LAS unsigned*)(lds + (bufoff) + ldsw + _i * 8192), 16, (int)(voff)[_i], (int)(soff), 0, 0); } while (0)
; #define PG8_LDA(dst, b, h) do { _Pragma("unroll") for (int m = 0; m < 4; ++m) _Pragma("unroll") for (int k = 0; k < 2; ++k) dst[m][k] = *(const PG8_LAS bf16x8*)(lds + PG8_SA(b, h) + aoff + m * 2048 + k * 1024); } while (0)
; #define PG8_LDB(dst, b, h) do { _Pragma("unroll") for (int n = 0; n < 2; ++n) _Pragma("unroll") for (int k = 0; k < 2; ++k) dst[n][k] = *(const PG8_LAS bf16x8*)(lds + PG8_SB(b, h) + boff + n * 2048 + k * 1024); } while (0)
; #define PG8_MMA(ai, bj, At, Bt) do { __builtin_amdgcn_s_setprio(1); _Pragma("unroll") for (int m = 0; m < 4; ++m) _Pragma("unroll") for (int n = 0; n < 2; ++n) _Pragma("unroll") for (int k = 0; k < 2; ++k) \
;         acc[ai][bj][m][n] = __builtin_amdgcn_mfma_f32_16x16x32_bf16(Bt[n][k], At[m][k], acc[ai][bj][m][n], 0, 0, 0); __builtin_amdgcn_s_setprio(0); } while (0)
; #define PG8_WAIT_V(n) asm volatile("s_waitcnt vmcnt(" #n ")" ::: "memory")
; #define PG8_WAIT_L(n) asm volatile("s_waitcnt lgkmcnt(" #n ")" ::: "memory")
; #define PG8_BAR __builtin_amdgcn_s_barrier()
; #define PG8_SCHED __builtin_amdgcn_sched_barrier(0)
; template <class Epi, class Sched, bool ALIGN_EPI = false, bool SP2 = false>
; __device__ __forceinline__ void gemm_phase(PG8_LAS unsigned char* lds, const Gemm g, const Sched& S, const Epi& E, const int wid  ) {
;     ...
;             PG8_LDA(At, 0, 1); PG8_STAGE(PG8_SB(0, 0), b2, voffB); PG8_STAGE(PG8_SB(0, 1), b2 + hstep, voffB); PG8_STAGE(PG8_SA(0, 0), a2, voffA);
;             PG8_WAIT_V(8); PG8_WAIT_L(0); PG8_BAR; PG8_MMA(1, 0, At, B0); PG8_MMA(1, 1, At, B1); PG8_BAR; PG8_SCHED;
;             PG8_LDB(B0, 1, 0); PG8_LDB(B1, 1, 1); PG8_SCHED; PG8_LDA(At, 1, 0); PG8_STAGE(PG8_SA(0, 1), a2 + hstep, voffA);
;             PG8_WAIT_V(8); PG8_WAIT_L(0); PG8_BAR; PG8_MMA(0, 0, At, B0); PG8_MMA(0, 1, At, B1); PG8_BAR; PG8_SCHED;
	s_mov_b32 m0, s26
	s_mov_b32 s14, s10
	s_mov_b32 s15, s11
	ds_read_b128 v[174:177], v142 offset:16384
	ds_read_b128 v[178:181], v142 offset:17408
	ds_read_b128 v[182:185], v142 offset:18432
	ds_read_b128 v[186:189], v142 offset:19456
	ds_read_b128 v[190:193], v142 offset:20480
	ds_read_b128 v[194:197], v142 offset:21504
	ds_read_b128 v[198:201], v142 offset:22528
	ds_read_b128 v[202:205], v142 offset:23552
	buffer_load_dwordx4 v137, s[12:15], s60 offen lds
	s_mov_b32 m0, s27
	s_add_i32 s62, s60, 0x80000
	buffer_load_dwordx4 v139, s[12:15], s60 offen lds
	s_mov_b32 m0, s28
	s_nop 0
	buffer_load_dwordx4 v137, s[12:15], s62 offen lds
	s_mov_b32 m0, s29
	s_nop 0
	buffer_load_dwordx4 v139, s[12:15], s62 offen lds
	s_mov_b32 m0, s3
	s_nop 0
	buffer_load_dwordx4 v136, s[8:11], s61 offen lds
	s_mov_b32 m0, s30
	s_nop 0
	buffer_load_dwordx4 v138, s[8:11], s61 offen lds
	s_waitcnt vmcnt(8)
	s_waitcnt lgkmcnt(0)
	s_barrier
	s_waitcnt lgkmcnt(7)
	v_mfma_f32_16x16x32_bf16 v[60:63], v[132:135], v[174:177], v[60:63]
	v_mfma_f32_16x16x32_bf16 v[56:59], v[150:153], v[174:177], v[56:59]
	s_waitcnt lgkmcnt(5)
	v_mfma_f32_16x16x32_bf16 v[44:47], v[132:135], v[182:185], v[44:47]
	v_mfma_f32_16x16x32_bf16 v[40:43], v[150:153], v[182:185], v[40:43]
	s_waitcnt lgkmcnt(3)
	v_mfma_f32_16x16x32_bf16 v[28:31], v[132:135], v[190:193], v[28:31]
	v_mfma_f32_16x16x32_bf16 v[24:27], v[150:153], v[190:193], v[24:27]
	s_waitcnt lgkmcnt(1)
	v_mfma_f32_16x16x32_bf16 v[12:15], v[132:135], v[198:201], v[12:15]
	v_mfma_f32_16x16x32_bf16 v[8:11], v[150:153], v[198:201], v[8:11]
	v_mfma_f32_16x16x32_bf16 v[60:63], v[146:149], v[178:181], v[60:63]
	v_mfma_f32_16x16x32_bf16 v[56:59], v[154:157], v[178:181], v[56:59]
	v_mfma_f32_16x16x32_bf16 v[44:47], v[146:149], v[186:189], v[44:47]
	v_mfma_f32_16x16x32_bf16 v[40:43], v[154:157], v[186:189], v[40:43]
	v_mfma_f32_16x16x32_bf16 v[28:31], v[146:149], v[194:197], v[28:31]
	v_mfma_f32_16x16x32_bf16 v[24:27], v[154:157], v[194:197], v[24:27]
	s_waitcnt lgkmcnt(0)
	v_mfma_f32_16x16x32_bf16 v[12:15], v[146:149], v[202:205], v[12:15]
	v_mfma_f32_16x16x32_bf16 v[8:11], v[154:157], v[202:205], v[8:11]
	v_mfma_f32_16x16x32_bf16 v[52:55], v[158:161], v[174:177], v[52:55]
	v_mfma_f32_16x16x32_bf16 v[48:51], v[166:169], v[174:177], v[48:51]
	v_mfma_f32_16x16x32_bf16 v[36:39], v[158:161], v[182:185], v[36:39]
	v_mfma_f32_16x16x32_bf16 v[32:35], v[166:169], v[182:185], v[32:35]
	v_mfma_f32_16x16x32_bf16 v[20:23], v[158:161], v[190:193], v[20:23]
	v_mfma_f32_16x16x32_bf16 v[16:19], v[166:169], v[190:193], v[16:19]
	v_mfma_f32_16x16x32_bf16 v[4:7], v[158:161], v[198:201], v[4:7]
	v_mfma_f32_16x16x32_bf16 v[0:3], v[166:169], v[198:201], v[0:3]
	v_mfma_f32_16x16x32_bf16 v[52:55], v[162:165], v[178:181], v[52:55]
	v_mfma_f32_16x16x32_bf16 v[48:51], v[170:173], v[178:181], v[48:51]
	v_mfma_f32_16x16x32_bf16 v[36:39], v[162:165], v[186:189], v[36:39]
	v_mfma_f32_16x16x32_bf16 v[32:35], v[170:173], v[186:189], v[32:35]
	v_mfma_f32_16x16x32_bf16 v[20:23], v[162:165], v[194:197], v[20:23]
	v_mfma_f32_16x16x32_bf16 v[16:19], v[170:173], v[194:197], v[16:19]
	v_mfma_f32_16x16x32_bf16 v[4:7], v[162:165], v[202:205], v[4:7]
	v_mfma_f32_16x16x32_bf16 v[0:3], v[170:173], v[202:205], v[0:3]
	s_barrier
	ds_read_b128 v[132:135], v143
	ds_read_b128 v[146:149], v143 offset:1024
	ds_read_b128 v[150:153], v143 offset:2048
	ds_read_b128 v[154:157], v143 offset:3072
	ds_read_b128 v[158:161], v144
	ds_read_b128 v[162:165], v144 offset:1024
	ds_read_b128 v[166:169], v144 offset:2048
	ds_read_b128 v[170:173], v144 offset:3072
	s_add_i32 s61, s61, 0x80000
	s_mov_b32 m0, s31
	ds_read_b128 v[174:177], v142 offset:32768
	ds_read_b128 v[178:181], v142 offset:33792
	ds_read_b128 v[182:185], v142 offset:34816
	ds_read_b128 v[186:189], v142 offset:35840
	ds_read_b128 v[190:193], v142 offset:36864
	ds_read_b128 v[194:197], v142 offset:37888
	ds_read_b128 v[198:201], v142 offset:38912
	ds_read_b128 v[202:205], v142 offset:39936
	buffer_load_dwordx4 v136, s[8:11], s61 offen lds
	s_mov_b32 m0, s33
	s_nop 0
	buffer_load_dwordx4 v138, s[8:11], s61 offen lds
	s_waitcnt vmcnt(8)
	s_waitcnt lgkmcnt(0)
	s_barrier
; #define PG8_STAGE(bufoff, soff, voff) do { _Pragma("unroll") for (int _i = 0; _i < 2; ++_i) \
;         __builtin_amdgcn_raw_ptr_buffer_load_lds(rs_##voff, (PG8_LAS unsigned*)(lds + (bufoff) + ldsw + _i * 8192), 16, (int)(voff)[_i], (int)(soff), 0, 0); } while (0)
; #define PG8_LDA(dst, b, h) do { _Pragma("unroll") for (int m = 0; m < 4; ++m) _Pragma("unroll") for (int k = 0; k < 2; ++k) dst[m][k] = *(const PG8_LAS bf16x8*)(lds + PG8_SA(b, h) + aoff + m * 2048 + k * 1024); } while (0)
; #define PG8_MMA(ai, bj, At, Bt) do { __builtin_amdgcn_s_setprio(1); _Pragma("unroll") for (int m = 0; m < 4; ++m) _Pragma("unroll") for (int n = 0; n < 2; ++n) _Pragma("unroll") for (int k = 0; k < 2; ++k) \
;         acc[ai][bj][m][n] = __builtin_amdgcn_mfma_f32_16x16x32_bf16(Bt[n][k], At[m][k], acc[ai][bj][m][n], 0, 0, 0); __builtin_amdgcn_s_setprio(0); } while (0)
; #define PG8_WAIT_V(n) asm volatile("s_waitcnt vmcnt(" #n ")" ::: "memory")
; #define PG8_WAIT_L(n) asm volatile("s_waitcnt lgkmcnt(" #n ")" ::: "memory")
; #define PG8_BAR __builtin_amdgcn_s_barrier()
; #define PG8_SCHED __builtin_amdgcn_sched_barrier(0)
; template <class Epi, class Sched, bool ALIGN_EPI = false, bool SP2 = false>
; __device__ __forceinline__ void gemm_phase(PG8_LAS unsigned char* lds, const Gemm g, const Sched& S, const Epi& E, const int wid  ) {
;     ...
;             PG8_WAIT_V(8); PG8_WAIT_L(0); PG8_BAR; PG8_MMA(0, 0, At, B0); PG8_MMA(0, 1, At, B1); PG8_BAR; PG8_SCHED;
;             PG8_LDA(At, 1, 1); PG8_STAGE(PG8_SB(1, 0), b3, voffB); PG8_STAGE(PG8_SB(1, 1), b3 + hstep, voffB); PG8_STAGE(PG8_SA(1, 0), a3, voffA);
;             PG8_WAIT_V(8); PG8_WAIT_L(0); PG8_BAR; PG8_MMA(1, 0, At, B0); PG8_MMA(1, 1, At, B1); PG8_BAR; PG8_SCHED;
	s_waitcnt lgkmcnt(7)
	v_mfma_f32_16x16x32_bf16 v[124:127], v[132:135], v[174:177], v[124:127]
	v_mfma_f32_16x16x32_bf16 v[120:123], v[150:153], v[174:177], v[120:123]
	s_waitcnt lgkmcnt(5)
	v_mfma_f32_16x16x32_bf16 v[108:111], v[132:135], v[182:185], v[108:111]
	v_mfma_f32_16x16x32_bf16 v[104:107], v[150:153], v[182:185], v[104:107]
	s_waitcnt lgkmcnt(3)
	v_mfma_f32_16x16x32_bf16 v[92:95], v[132:135], v[190:193], v[92:95]
	v_mfma_f32_16x16x32_bf16 v[88:91], v[150:153], v[190:193], v[88:91]
	s_waitcnt lgkmcnt(1)
	v_mfma_f32_16x16x32_bf16 v[76:79], v[132:135], v[198:201], v[76:79]
	v_mfma_f32_16x16x32_bf16 v[72:75], v[150:153], v[198:201], v[72:75]
	v_mfma_f32_16x16x32_bf16 v[124:127], v[146:149], v[178:181], v[124:127]
	v_mfma_f32_16x16x32_bf16 v[120:123], v[154:157], v[178:181], v[120:123]
	v_mfma_f32_16x16x32_bf16 v[108:111], v[146:149], v[186:189], v[108:111]
	v_mfma_f32_16x16x32_bf16 v[104:107], v[154:157], v[186:189], v[104:107]
	v_mfma_f32_16x16x32_bf16 v[92:95], v[146:149], v[194:197], v[92:95]
	v_mfma_f32_16x16x32_bf16 v[88:91], v[154:157], v[194:197], v[88:91]
	s_waitcnt lgkmcnt(0)
	v_mfma_f32_16x16x32_bf16 v[76:79], v[146:149], v[202:205], v[76:79]
	v_mfma_f32_16x16x32_bf16 v[72:75], v[154:157], v[202:205], v[72:75]
	v_mfma_f32_16x16x32_bf16 v[116:119], v[158:161], v[174:177], v[116:119]
	v_mfma_f32_16x16x32_bf16 v[112:115], v[166:169], v[174:177], v[112:115]
	v_mfma_f32_16x16x32_bf16 v[100:103], v[158:161], v[182:185], v[100:103]
	v_mfma_f32_16x16x32_bf16 v[96:99], v[166:169], v[182:185], v[96:99]
	v_mfma_f32_16x16x32_bf16 v[84:87], v[158:161], v[190:193], v[84:87]
	v_mfma_f32_16x16x32_bf16 v[80:83], v[166:169], v[190:193], v[80:83]
	v_mfma_f32_16x16x32_bf16 v[68:71], v[158:161], v[198:201], v[68:71]
	v_mfma_f32_16x16x32_bf16 v[64:67], v[166:169], v[198:201], v[64:67]
	v_mfma_f32_16x16x32_bf16 v[116:119], v[162:165], v[178:181], v[116:119]
	v_mfma_f32_16x16x32_bf16 v[112:115], v[170:173], v[178:181], v[112:115]
	v_mfma_f32_16x16x32_bf16 v[100:103], v[162:165], v[186:189], v[100:103]
	v_mfma_f32_16x16x32_bf16 v[96:99], v[170:173], v[186:189], v[96:99]
	v_mfma_f32_16x16x32_bf16 v[84:87], v[162:165], v[194:197], v[84:87]
	v_mfma_f32_16x16x32_bf16 v[80:83], v[170:173], v[194:197], v[80:83]
	v_mfma_f32_16x16x32_bf16 v[68:71], v[162:165], v[202:205], v[68:71]
	v_mfma_f32_16x16x32_bf16 v[64:67], v[170:173], v[202:205], v[64:67]
	s_barrier
	s_mov_b32 m0, s34
	s_or_b32 s61, s60, 0x80
	ds_read_b128 v[174:177], v142 offset:49152
	ds_read_b128 v[178:181], v142 offset:50176
	ds_read_b128 v[182:185], v142 offset:51200
	ds_read_b128 v[186:189], v142 offset:52224
	ds_read_b128 v[190:193], v142 offset:53248
	ds_read_b128 v[194:197], v142 offset:54272
	ds_read_b128 v[198:201], v142 offset:55296
	ds_read_b128 v[202:205], v142 offset:56320
	buffer_load_dwordx4 v137, s[12:15], s61 offen lds
	s_mov_b32 m0, s35
	s_add_i32 s60, s60, 0x80080
	buffer_load_dwordx4 v139, s[12:15], s61 offen lds
	s_mov_b32 m0, s38
	s_nop 0
	buffer_load_dwordx4 v137, s[12:15], s60 offen lds
	s_mov_b32 m0, s39
	s_nop 0
	buffer_load_dwordx4 v139, s[12:15], s60 offen lds
	s_mov_b32 m0, s36
	s_nop 0
	buffer_load_dwordx4 v136, s[8:11], s59 offen lds
	s_mov_b32 m0, s37
	s_nop 0
	buffer_load_dwordx4 v138, s[8:11], s59 offen lds
	s_waitcnt vmcnt(8)
	s_waitcnt lgkmcnt(0)
	s_barrier
	s_waitcnt lgkmcnt(7)
	v_mfma_f32_16x16x32_bf16 v[60:63], v[132:135], v[174:177], v[60:63]
	v_mfma_f32_16x16x32_bf16 v[56:59], v[150:153], v[174:177], v[56:59]
	s_waitcnt lgkmcnt(5)
	v_mfma_f32_16x16x32_bf16 v[44:47], v[132:135], v[182:185], v[44:47]
	v_mfma_f32_16x16x32_bf16 v[40:43], v[150:153], v[182:185], v[40:43]
	s_waitcnt lgkmcnt(3)
	v_mfma_f32_16x16x32_bf16 v[28:31], v[132:135], v[190:193], v[28:31]
	v_mfma_f32_16x16x32_bf16 v[24:27], v[150:153], v[190:193], v[24:27]
	s_waitcnt lgkmcnt(1)
	v_mfma_f32_16x16x32_bf16 v[12:15], v[132:135], v[198:201], v[12:15]
	v_mfma_f32_16x16x32_bf16 v[8:11], v[150:153], v[198:201], v[8:11]
	v_mfma_f32_16x16x32_bf16 v[60:63], v[146:149], v[178:181], v[60:63]
	v_mfma_f32_16x16x32_bf16 v[56:59], v[154:157], v[178:181], v[56:59]
	v_mfma_f32_16x16x32_bf16 v[44:47], v[146:149], v[186:189], v[44:47]
	v_mfma_f32_16x16x32_bf16 v[40:43], v[154:157], v[186:189], v[40:43]
	v_mfma_f32_16x16x32_bf16 v[28:31], v[146:149], v[194:197], v[28:31]
	v_mfma_f32_16x16x32_bf16 v[24:27], v[154:157], v[194:197], v[24:27]
	s_waitcnt lgkmcnt(0)
	v_mfma_f32_16x16x32_bf16 v[12:15], v[146:149], v[202:205], v[12:15]
	v_mfma_f32_16x16x32_bf16 v[8:11], v[154:157], v[202:205], v[8:11]
	v_mfma_f32_16x16x32_bf16 v[52:55], v[158:161], v[174:177], v[52:55]
	v_mfma_f32_16x16x32_bf16 v[48:51], v[166:169], v[174:177], v[48:51]
	v_mfma_f32_16x16x32_bf16 v[36:39], v[158:161], v[182:185], v[36:39]
	v_mfma_f32_16x16x32_bf16 v[32:35], v[166:169], v[182:185], v[32:35]
	v_mfma_f32_16x16x32_bf16 v[20:23], v[158:161], v[190:193], v[20:23]
	v_mfma_f32_16x16x32_bf16 v[16:19], v[166:169], v[190:193], v[16:19]
	v_mfma_f32_16x16x32_bf16 v[4:7], v[158:161], v[198:201], v[4:7]
	v_mfma_f32_16x16x32_bf16 v[0:3], v[166:169], v[198:201], v[0:3]
	v_mfma_f32_16x16x32_bf16 v[52:55], v[162:165], v[178:181], v[52:55]
	v_mfma_f32_16x16x32_bf16 v[48:51], v[170:173], v[178:181], v[48:51]
	v_mfma_f32_16x16x32_bf16 v[36:39], v[162:165], v[186:189], v[36:39]
	v_mfma_f32_16x16x32_bf16 v[32:35], v[170:173], v[186:189], v[32:35]
	v_mfma_f32_16x16x32_bf16 v[20:23], v[162:165], v[194:197], v[20:23]
	v_mfma_f32_16x16x32_bf16 v[16:19], v[170:173], v[194:197], v[16:19]
	v_mfma_f32_16x16x32_bf16 v[4:7], v[162:165], v[202:205], v[4:7]
	v_mfma_f32_16x16x32_bf16 v[0:3], v[170:173], v[202:205], v[0:3]
	s_barrier
	s_add_i32 s58, s58, 2
	s_addk_i32 s54, 0x100
	s_addk_i32 s55, 0x100
	s_cmp_gt_u32 s58, 29
	s_cbranch_scc0 .LBB0_564
	s_setprio 0
	s_and_b64 vcc, exec, s[24:25]
	s_cbranch_vccz .LBB0_567
	s_barrier

; #define PG8_STAGE(bufoff, soff, voff) do { _Pragma("unroll") for (int _i = 0; _i < 2; ++_i) \
;         __builtin_amdgcn_raw_ptr_buffer_load_lds(rs_##voff, (PG8_LAS unsigned*)(lds + (bufoff) + ldsw + _i * 8192), 16, (int)(voff)[_i], (int)(soff), 0, 0); } while (0)
; #define PG8_LDA(dst, b, h) do { _Pragma("unroll") for (int m = 0; m < 4; ++m) _Pragma("unroll") for (int k = 0; k < 2; ++k) dst[m][k] = *(const PG8_LAS bf16x8*)(lds + PG8_SA(b, h) + aoff + m * 2048 + k * 1024); } while (0)
; #define PG8_LDB(dst, b, h) do { _Pragma("unroll") for (int n = 0; n < 2; ++n) _Pragma("unroll") for (int k = 0; k < 2; ++k) dst[n][k] = *(const PG8_LAS bf16x8*)(lds + PG8_SB(b, h) + boff + n * 2048 + k * 1024); } while (0)
; #define PG8_SCHED __builtin_amdgcn_sched_barrier(0)
; template <class Epi, class Sched, bool ALIGN_EPI = false, bool SP2 = false>
; __device__ __forceinline__ void gemm_phase(PG8_LAS unsigned char* lds, const Gemm g, const Sched& S, const Epi& E, const int wid  ) {
;     ...
;         const bool has_next = S.next(ui + 1, nxt); nxt.same = (has_next && nxt.pm == cur.pm) ? 1 : 0;
;         const unsigned nA = has_next ? (unsigned)g.asel(nxt.pn) * (unsigned)g.a_stride + (unsigned)nxt.pm * tstep : cA, nB = has_next ? (unsigned)nxt.pn * tstep : cB;
;         for (int t = 0; t < nt; t += 2) {
;             const bool last = (t == nt - 2);
;             const unsigned a1 = cA + (unsigned)(t + 1) * kstep;
;             const unsigned a2 = last ? nA : cA + (unsigned)(t + 2) * kstep, b2 = last ? nB : cB + (unsigned)(t + 2) * kstep;
;             const unsigned a3 = a2 + kstep, b3 = b2 + kstep;
;             if (last && has_next) S.a_ready(nxt);
;             if constexpr (SP2) {
;             PG8_LDB(B0, 0, 0); PG8_LDB(B1, 0, 1); PG8_SCHED; PG8_LDA(At, 0, 0); PG8_STAGE(PG8_SA(1, 1), a1 + hstep, voffA);
;     ...
; #pragma unroll
;         for (int a = 0; a < 2; ++a)
; #pragma unroll
;             for (int b = 0; b < 2; ++b)
; #pragma unroll
;                 for (int m = 0; m < 4; ++m)
; #pragma unroll
;                     for (int n = 0; n < 2; ++n) acc[a][b][m][n] = (f32x4){0.f, 0.f, 0.f, 0.f};
;         cur = nxt; cA = nA; cB = nB; ++ui;
.LBB0_657:
	s_lshl_b32 s91, s90, 20
	s_and_b64 s[6:7], s[4:5], exec
	s_cselect_b32 s6, s91, s8
	s_lshl_b32 s92, s89, 20
	s_and_b64 s[18:19], s[4:5], exec
	v_mov_b32_e32 v56, 0
	s_cselect_b32 s7, s92, s9
	s_add_i32 s8, s8, 0x80080
	s_addk_i32 s9, 0x100
	s_mov_b32 s46, -2
	v_mov_b32_e32 v57, v56
	v_mov_b32_e32 v58, v56
	v_mov_b32_e32 v59, v56
	v_mov_b32_e32 v60, v56
	v_mov_b32_e32 v61, v56
	v_mov_b32_e32 v62, v56
	v_mov_b32_e32 v63, v56
	v_mov_b32_e32 v64, v56
	v_mov_b32_e32 v65, v56
	v_mov_b32_e32 v66, v56
	v_mov_b32_e32 v67, v56
	v_mov_b32_e32 v68, v56
	v_mov_b32_e32 v69, v56
	v_mov_b32_e32 v70, v56
	v_mov_b32_e32 v71, v56
	v_mov_b32_e32 v72, v56
	v_mov_b32_e32 v73, v56
	v_mov_b32_e32 v74, v56
	v_mov_b32_e32 v75, v56
	v_mov_b32_e32 v80, v56
	v_mov_b32_e32 v81, v56
	v_mov_b32_e32 v82, v56
	v_mov_b32_e32 v83, v56
	v_mov_b32_e32 v0, v56
	v_mov_b32_e32 v1, v56
	s_waitcnt lgkmcnt(7)
	v_mov_b32_e32 v2, v56
	v_mov_b32_e32 v3, v56
	s_waitcnt lgkmcnt(6)
	v_mov_b32_e32 v4, v56
	v_mov_b32_e32 v5, v56
	s_waitcnt lgkmcnt(5)
	v_mov_b32_e32 v6, v56
	v_mov_b32_e32 v7, v56
	v_mov_b32_e32 v48, v56
	v_mov_b32_e32 v49, v56
	v_mov_b32_e32 v50, v56
	v_mov_b32_e32 v51, v56
	v_mov_b32_e32 v92, v56
	v_mov_b32_e32 v93, v56
	v_mov_b32_e32 v94, v56
	v_mov_b32_e32 v95, v56
	v_mov_b32_e32 v76, v56
	v_mov_b32_e32 v77, v56
	v_mov_b32_e32 v78, v56
	v_mov_b32_e32 v79, v56
	v_mov_b32_e32 v84, v56
	v_mov_b32_e32 v85, v56
	v_mov_b32_e32 v86, v56
	v_mov_b32_e32 v87, v56
	v_mov_b32_e32 v88, v56
	v_mov_b32_e32 v89, v56
	v_mov_b32_e32 v90, v56
	v_mov_b32_e32 v91, v56
	v_mov_b32_e32 v96, v56
	v_mov_b32_e32 v97, v56
	v_mov_b32_e32 v98, v56
	v_mov_b32_e32 v99, v56
	v_mov_b32_e32 v100, v56
	v_mov_b32_e32 v101, v56
	v_mov_b32_e32 v102, v56
	v_mov_b32_e32 v103, v56
	v_mov_b32_e32 v104, v56
	v_mov_b32_e32 v105, v56
	v_mov_b32_e32 v106, v56
	v_mov_b32_e32 v107, v56
	v_mov_b32_e32 v108, v56
	v_mov_b32_e32 v109, v56
	v_mov_b32_e32 v110, v56
	v_mov_b32_e32 v111, v56
	v_mov_b32_e32 v112, v56
	v_mov_b32_e32 v113, v56
	v_mov_b32_e32 v114, v56
	v_mov_b32_e32 v115, v56
	v_mov_b32_e32 v116, v56
	v_mov_b32_e32 v117, v56
	v_mov_b32_e32 v118, v56
	v_mov_b32_e32 v119, v56
	v_mov_b32_e32 v124, v56
	v_mov_b32_e32 v125, v56
	v_mov_b32_e32 v126, v56
	v_mov_b32_e32 v127, v56
	v_mov_b32_e32 v128, v56
	v_mov_b32_e32 v129, v56
	v_mov_b32_e32 v130, v56
	v_mov_b32_e32 v131, v56
	v_mov_b32_e32 v136, v56
	v_mov_b32_e32 v137, v56
	v_mov_b32_e32 v138, v56
	v_mov_b32_e32 v139, v56
	s_waitcnt lgkmcnt(4)
	v_mov_b32_e32 v8, v56
	v_mov_b32_e32 v9, v56
	s_waitcnt lgkmcnt(3)
	v_mov_b32_e32 v10, v56
	v_mov_b32_e32 v11, v56
	s_waitcnt lgkmcnt(2)
	v_mov_b32_e32 v12, v56
	v_mov_b32_e32 v13, v56
	s_waitcnt lgkmcnt(1)
	v_mov_b32_e32 v14, v56
	v_mov_b32_e32 v15, v56
	v_mov_b32_e32 v120, v56
	v_mov_b32_e32 v121, v56
	v_mov_b32_e32 v122, v56
	v_mov_b32_e32 v123, v56
	v_mov_b32_e32 v156, v56
	v_mov_b32_e32 v157, v56
	v_mov_b32_e32 v158, v56
	v_mov_b32_e32 v159, v56
	v_mov_b32_e32 v132, v56
	v_mov_b32_e32 v133, v56
	v_mov_b32_e32 v134, v56
	v_mov_b32_e32 v135, v56
	v_mov_b32_e32 v140, v56
	v_mov_b32_e32 v141, v56
	v_mov_b32_e32 v142, v56
	v_mov_b32_e32 v143, v56
	v_mov_b32_e32 v144, v56
	v_mov_b32_e32 v145, v56
	v_mov_b32_e32 v146, v56
	v_mov_b32_e32 v147, v56
	v_mov_b32_e32 v148, v56
	v_mov_b32_e32 v149, v56
	v_mov_b32_e32 v150, v56
	v_mov_b32_e32 v151, v56
	v_mov_b32_e32 v52, v56
	v_mov_b32_e32 v53, v56
	v_mov_b32_e32 v54, v56
	v_mov_b32_e32 v55, v56
	v_mov_b32_e32 v152, v56
	v_mov_b32_e32 v153, v56
	v_mov_b32_e32 v154, v56
	v_mov_b32_e32 v155, v56
	v_readlane_b32 vcc_lo, v246, 6
	s_nop 1
	s_cmp_ge_u32 vcc_lo, 4
	s_cbranch_scc0 .Lprio_658
	s_setprio 1
.Lprio_658:
.LBB0_658:
	s_waitcnt lgkmcnt(0)
	ds_read_b128 v[16:19], v188
	ds_read_b128 v[20:23], v188 offset:1024
	ds_read_b128 v[24:27], v188 offset:2048
	ds_read_b128 v[28:31], v188 offset:3072
	ds_read_b128 v[32:35], v189
	ds_read_b128 v[36:39], v189 offset:1024
	ds_read_b128 v[40:43], v189 offset:2048
	ds_read_b128 v[44:47], v189 offset:3072
	s_add_i32 s18, s8, 0xfff80080
	s_cmp_eq_u32 s46, 28
	s_cselect_b32 s94, s6, s18
	s_cselect_b32 s93, s7, s9
	s_or_b32 s47, s94, 0x80
	s_mov_b32 m0, s75
	ds_read_b128 v[160:163], v190
	ds_read_b128 v[170:173], v190 offset:1024
	ds_read_b128 v[174:177], v190 offset:2048
	ds_read_b128 v[178:181], v190 offset:3072
	ds_read_b128 v[194:197], v190 offset:4096
	ds_read_b128 v[198:201], v190 offset:5120
	ds_read_b128 v[202:205], v190 offset:6144
	ds_read_b128 v[206:209], v190 offset:7168
	buffer_load_dwordx4 v182, s[12:15], s8 offen lds
	s_mov_b32 m0, s77
	s_nop 0
	buffer_load_dwordx4 v184, s[12:15], s8 offen lds
	s_waitcnt vmcnt(8)
	s_waitcnt lgkmcnt(0)
	s_barrier
; #define PG8_STAGE(bufoff, soff, voff) do { _Pragma("unroll") for (int _i = 0; _i < 2; ++_i) \
;         __builtin_amdgcn_raw_ptr_buffer_load_lds(rs_##voff, (PG8_LAS unsigned*)(lds + (bufoff) + ldsw + _i * 8192), 16, (int)(voff)[_i], (int)(soff), 0, 0); } while (0)
; #define PG8_LDA(dst, b, h) do { _Pragma("unroll") for (int m = 0; m < 4; ++m) _Pragma("unroll") for (int k = 0; k < 2; ++k) dst[m][k] = *(const PG8_LAS bf16x8*)(lds + PG8_SA(b, h) + aoff + m * 2048 + k * 1024); } while (0)
; #define PG8_MMA(ai, bj, At, Bt) do { __builtin_amdgcn_s_setprio(1); _Pragma("unroll") for (int m = 0; m < 4; ++m) _Pragma("unroll") for (int n = 0; n < 2; ++n) _Pragma("unroll") for (int k = 0; k < 2; ++k) \
;         acc[ai][bj][m][n] = __builtin_amdgcn_mfma_f32_16x16x32_bf16(Bt[n][k], At[m][k], acc[ai][bj][m][n], 0, 0, 0); __builtin_amdgcn_s_setprio(0); } while (0)
; #define PG8_WAIT_V(n) asm volatile("s_waitcnt vmcnt(" #n ")" ::: "memory")
; #define PG8_WAIT_L(n) asm volatile("s_waitcnt lgkmcnt(" #n ")" ::: "memory")
; #define PG8_BAR __builtin_amdgcn_s_barrier()
; #define PG8_SCHED __builtin_amdgcn_sched_barrier(0)
; template <class Epi, class Sched, bool ALIGN_EPI = false, bool SP2 = false>
; __device__ __forceinline__ void gemm_phase(PG8_LAS unsigned char* lds, const Gemm g, const Sched& S, const Epi& E, const int wid  ) {
;     ...
;             PG8_WAIT_V(8); PG8_WAIT_L(0); PG8_BAR; PG8_MMA(0, 0, At, B0); PG8_MMA(0, 1, At, B1); PG8_BAR; PG8_SCHED;
;             PG8_LDA(At, 0, 1); PG8_STAGE(PG8_SB(0, 0), b2, voffB); PG8_STAGE(PG8_SB(0, 1), b2 + hstep, voffB); PG8_STAGE(PG8_SA(0, 0), a2, voffA);
;             PG8_WAIT_V(8); PG8_WAIT_L(0); PG8_BAR; PG8_MMA(1, 0, At, B0); PG8_MMA(1, 1, At, B1); PG8_BAR; PG8_SCHED;
	s_waitcnt lgkmcnt(7)
	v_mfma_f32_16x16x32_bf16 v[152:155], v[16:19], v[160:163], v[152:155]
	v_mfma_f32_16x16x32_bf16 v[52:55], v[24:27], v[160:163], v[52:55]
	s_waitcnt lgkmcnt(5)
	v_mfma_f32_16x16x32_bf16 v[148:151], v[16:19], v[174:177], v[148:151]
	v_mfma_f32_16x16x32_bf16 v[144:147], v[24:27], v[174:177], v[144:147]
	s_waitcnt lgkmcnt(3)
	v_mfma_f32_16x16x32_bf16 v[140:143], v[16:19], v[194:197], v[140:143]
	v_mfma_f32_16x16x32_bf16 v[132:135], v[24:27], v[194:197], v[132:135]
	s_waitcnt lgkmcnt(1)
	v_mfma_f32_16x16x32_bf16 v[156:159], v[16:19], v[202:205], v[156:159]
	v_mfma_f32_16x16x32_bf16 v[120:123], v[24:27], v[202:205], v[120:123]
	v_mfma_f32_16x16x32_bf16 v[152:155], v[20:23], v[170:173], v[152:155]
	v_mfma_f32_16x16x32_bf16 v[52:55], v[28:31], v[170:173], v[52:55]
	v_mfma_f32_16x16x32_bf16 v[148:151], v[20:23], v[178:181], v[148:151]
	v_mfma_f32_16x16x32_bf16 v[144:147], v[28:31], v[178:181], v[144:147]
	v_mfma_f32_16x16x32_bf16 v[140:143], v[20:23], v[198:201], v[140:143]
	v_mfma_f32_16x16x32_bf16 v[132:135], v[28:31], v[198:201], v[132:135]
	s_waitcnt lgkmcnt(0)
	v_mfma_f32_16x16x32_bf16 v[156:159], v[20:23], v[206:209], v[156:159]
	v_mfma_f32_16x16x32_bf16 v[120:123], v[28:31], v[206:209], v[120:123]
	v_mfma_f32_16x16x32_bf16 v[12:15], v[32:35], v[160:163], v[12:15]
	v_mfma_f32_16x16x32_bf16 v[8:11], v[40:43], v[160:163], v[8:11]
	v_mfma_f32_16x16x32_bf16 v[136:139], v[32:35], v[174:177], v[136:139]
	v_mfma_f32_16x16x32_bf16 v[128:131], v[40:43], v[174:177], v[128:131]
	v_mfma_f32_16x16x32_bf16 v[124:127], v[32:35], v[194:197], v[124:127]
	v_mfma_f32_16x16x32_bf16 v[116:119], v[40:43], v[194:197], v[116:119]
	v_mfma_f32_16x16x32_bf16 v[112:115], v[32:35], v[202:205], v[112:115]
	v_mfma_f32_16x16x32_bf16 v[108:111], v[40:43], v[202:205], v[108:111]
	v_mfma_f32_16x16x32_bf16 v[12:15], v[36:39], v[170:173], v[12:15]
	v_mfma_f32_16x16x32_bf16 v[8:11], v[44:47], v[170:173], v[8:11]
	v_mfma_f32_16x16x32_bf16 v[136:139], v[36:39], v[178:181], v[136:139]
	v_mfma_f32_16x16x32_bf16 v[128:131], v[44:47], v[178:181], v[128:131]
	v_mfma_f32_16x16x32_bf16 v[124:127], v[36:39], v[198:201], v[124:127]
	v_mfma_f32_16x16x32_bf16 v[116:119], v[44:47], v[198:201], v[116:119]
	v_mfma_f32_16x16x32_bf16 v[112:115], v[36:39], v[206:209], v[112:115]
	v_mfma_f32_16x16x32_bf16 v[108:111], v[44:47], v[206:209], v[108:111]
	s_barrier
	s_mov_b32 m0, s33
	s_mov_b32 s18, s14
	s_mov_b32 s19, s15
	ds_read_b128 v[160:163], v190 offset:16384
	ds_read_b128 v[170:173], v190 offset:17408
	ds_read_b128 v[174:177], v190 offset:18432
	ds_read_b128 v[178:181], v190 offset:19456
	ds_read_b128 v[194:197], v190 offset:20480
	ds_read_b128 v[198:201], v190 offset:21504
	ds_read_b128 v[202:205], v190 offset:22528
	ds_read_b128 v[206:209], v190 offset:23552
	buffer_load_dwordx4 v183, s[16:19], s93 offen lds
	s_mov_b32 m0, s50
	s_add_i32 s95, s93, 0x80000
	buffer_load_dwordx4 v185, s[16:19], s93 offen lds
	s_mov_b32 m0, s51
	s_nop 0
	buffer_load_dwordx4 v183, s[16:19], s95 offen lds
	s_mov_b32 m0, s53
	s_nop 0
	buffer_load_dwordx4 v185, s[16:19], s95 offen lds
	s_mov_b32 m0, s3
	s_nop 0
	buffer_load_dwordx4 v182, s[12:15], s94 offen lds
	s_mov_b32 m0, s54
	s_nop 0
	buffer_load_dwordx4 v184, s[12:15], s94 offen lds
	s_waitcnt vmcnt(8)
	s_waitcnt lgkmcnt(0)
	s_barrier
	s_waitcnt lgkmcnt(7)
	v_mfma_f32_16x16x32_bf16 v[104:107], v[16:19], v[160:163], v[104:107]
	v_mfma_f32_16x16x32_bf16 v[100:103], v[24:27], v[160:163], v[100:103]
	s_waitcnt lgkmcnt(5)
	v_mfma_f32_16x16x32_bf16 v[96:99], v[16:19], v[174:177], v[96:99]
	v_mfma_f32_16x16x32_bf16 v[88:91], v[24:27], v[174:177], v[88:91]
	s_waitcnt lgkmcnt(3)
	v_mfma_f32_16x16x32_bf16 v[84:87], v[16:19], v[194:197], v[84:87]
	v_mfma_f32_16x16x32_bf16 v[76:79], v[24:27], v[194:197], v[76:79]
	s_waitcnt lgkmcnt(1)
	v_mfma_f32_16x16x32_bf16 v[16:19], v[16:19], v[202:205], v[92:95]
	v_mfma_f32_16x16x32_bf16 v[104:107], v[20:23], v[170:173], v[104:107]
	v_mfma_f32_16x16x32_bf16 v[100:103], v[28:31], v[170:173], v[100:103]
	v_mfma_f32_16x16x32_bf16 v[96:99], v[20:23], v[178:181], v[96:99]
	v_mfma_f32_16x16x32_bf16 v[88:91], v[28:31], v[178:181], v[88:91]
	v_mfma_f32_16x16x32_bf16 v[84:87], v[20:23], v[198:201], v[84:87]
	v_mfma_f32_16x16x32_bf16 v[76:79], v[28:31], v[198:201], v[76:79]
	s_waitcnt lgkmcnt(0)
	v_mfma_f32_16x16x32_bf16 v[16:19], v[20:23], v[206:209], v[16:19]
	v_mfma_f32_16x16x32_bf16 v[20:23], v[24:27], v[202:205], v[48:51]
	v_mfma_f32_16x16x32_bf16 v[20:23], v[28:31], v[206:209], v[20:23]
	v_mfma_f32_16x16x32_bf16 v[48:51], v[32:35], v[194:197], v[68:71]
	v_mfma_f32_16x16x32_bf16 v[4:7], v[32:35], v[160:163], v[4:7]
	v_mfma_f32_16x16x32_bf16 v[0:3], v[40:43], v[160:163], v[0:3]
	v_mfma_f32_16x16x32_bf16 v[24:27], v[32:35], v[174:177], v[80:83]
	v_mfma_f32_16x16x32_bf16 v[68:71], v[36:39], v[198:201], v[48:51]
	v_mfma_f32_16x16x32_bf16 v[48:51], v[40:43], v[194:197], v[64:67]
	v_mfma_f32_16x16x32_bf16 v[32:35], v[32:35], v[202:205], v[60:63]
	v_mfma_f32_16x16x32_bf16 v[4:7], v[36:39], v[170:173], v[4:7]
	v_mfma_f32_16x16x32_bf16 v[0:3], v[44:47], v[170:173], v[0:3]
	v_mfma_f32_16x16x32_bf16 v[24:27], v[36:39], v[178:181], v[24:27]
	v_mfma_f32_16x16x32_bf16 v[28:31], v[40:43], v[174:177], v[72:75]
	v_mfma_f32_16x16x32_bf16 v[64:67], v[44:47], v[198:201], v[48:51]
	v_mfma_f32_16x16x32_bf16 v[32:35], v[36:39], v[206:209], v[32:35]
	v_mfma_f32_16x16x32_bf16 v[36:39], v[40:43], v[202:205], v[56:59]
	v_mfma_f32_16x16x32_bf16 v[28:31], v[44:47], v[178:181], v[28:31]
	v_mfma_f32_16x16x32_bf16 v[36:39], v[44:47], v[206:209], v[36:39]
	s_barrier
; #define PG8_STAGE(bufoff, soff, voff) do { _Pragma("unroll") for (int _i = 0; _i < 2; ++_i) \
;         __builtin_amdgcn_raw_ptr_buffer_load_lds(rs_##voff, (PG8_LAS unsigned*)(lds + (bufoff) + ldsw + _i * 8192), 16, (int)(voff)[_i], (int)(soff), 0, 0); } while (0)
; #define PG8_LDA(dst, b, h) do { _Pragma("unroll") for (int m = 0; m < 4; ++m) _Pragma("unroll") for (int k = 0; k < 2; ++k) dst[m][k] = *(const PG8_LAS bf16x8*)(lds + PG8_SA(b, h) + aoff + m * 2048 + k * 1024); } while (0)
; #define PG8_LDB(dst, b, h) do { _Pragma("unroll") for (int n = 0; n < 2; ++n) _Pragma("unroll") for (int k = 0; k < 2; ++k) dst[n][k] = *(const PG8_LAS bf16x8*)(lds + PG8_SB(b, h) + boff + n * 2048 + k * 1024); } while (0)
; #define PG8_MMA(ai, bj, At, Bt) do { __builtin_amdgcn_s_setprio(1); _Pragma("unroll") for (int m = 0; m < 4; ++m) _Pragma("unroll") for (int n = 0; n < 2; ++n) _Pragma("unroll") for (int k = 0; k < 2; ++k) \
;         acc[ai][bj][m][n] = __builtin_amdgcn_mfma_f32_16x16x32_bf16(Bt[n][k], At[m][k], acc[ai][bj][m][n], 0, 0, 0); __builtin_amdgcn_s_setprio(0); } while (0)
; #define PG8_WAIT_V(n) asm volatile("s_waitcnt vmcnt(" #n ")" ::: "memory")
; #define PG8_WAIT_L(n) asm volatile("s_waitcnt lgkmcnt(" #n ")" ::: "memory")
; #define PG8_BAR __builtin_amdgcn_s_barrier()
; #define PG8_SCHED __builtin_amdgcn_sched_barrier(0)
; template <class Epi, class Sched, bool ALIGN_EPI = false, bool SP2 = false>
; __device__ __forceinline__ void gemm_phase(PG8_LAS unsigned char* lds, const Gemm g, const Sched& S, const Epi& E, const int wid  ) {
;     ...
;             PG8_LDB(B0, 1, 0); PG8_LDB(B1, 1, 1); PG8_SCHED; PG8_LDA(At, 1, 0); PG8_STAGE(PG8_SA(0, 1), a2 + hstep, voffA);
;             PG8_WAIT_V(8); PG8_WAIT_L(0); PG8_BAR; PG8_MMA(0, 0, At, B0); PG8_MMA(0, 1, At, B1); PG8_BAR; PG8_SCHED;
;             PG8_LDA(At, 1, 1); PG8_STAGE(PG8_SB(1, 0), b3, voffB); PG8_STAGE(PG8_SB(1, 1), b3 + hstep, voffB); PG8_STAGE(PG8_SA(1, 0), a3, voffA);
;             PG8_WAIT_V(8); PG8_WAIT_L(0); PG8_BAR; PG8_MMA(1, 0, At, B0); PG8_MMA(1, 1, At, B1); PG8_BAR; PG8_SCHED;
	ds_read_b128 v[40:43], v191
	ds_read_b128 v[44:47], v191 offset:1024
	ds_read_b128 v[48:51], v191 offset:2048
	ds_read_b128 v[56:59], v191 offset:3072
	ds_read_b128 v[60:63], v192
	ds_read_b128 v[160:163], v192 offset:1024
	ds_read_b128 v[170:173], v192 offset:2048
	ds_read_b128 v[174:177], v192 offset:3072
	s_add_i32 s94, s94, 0x80000
	s_mov_b32 m0, s55
	ds_read_b128 v[72:75], v190 offset:32768
	ds_read_b128 v[80:83], v190 offset:33792
	ds_read_b128 v[92:95], v190 offset:34816
	ds_read_b128 v[178:181], v190 offset:35840
	ds_read_b128 v[194:197], v190 offset:36864
	ds_read_b128 v[198:201], v190 offset:37888
	ds_read_b128 v[202:205], v190 offset:38912
	ds_read_b128 v[206:209], v190 offset:39936
	buffer_load_dwordx4 v182, s[12:15], s94 offen lds
	s_mov_b32 m0, s59
	s_nop 0
	buffer_load_dwordx4 v184, s[12:15], s94 offen lds
	s_waitcnt vmcnt(8)
	s_waitcnt lgkmcnt(0)
	s_barrier
	s_waitcnt lgkmcnt(7)
	v_mfma_f32_16x16x32_bf16 v[152:155], v[40:43], v[72:75], v[152:155]
	v_mfma_f32_16x16x32_bf16 v[52:55], v[48:51], v[72:75], v[52:55]
	s_waitcnt lgkmcnt(5)
	v_mfma_f32_16x16x32_bf16 v[148:151], v[40:43], v[92:95], v[148:151]
	v_mfma_f32_16x16x32_bf16 v[144:147], v[48:51], v[92:95], v[144:147]
	s_waitcnt lgkmcnt(3)
	v_mfma_f32_16x16x32_bf16 v[140:143], v[40:43], v[194:197], v[140:143]
	v_mfma_f32_16x16x32_bf16 v[132:135], v[48:51], v[194:197], v[132:135]
	s_waitcnt lgkmcnt(1)
	v_mfma_f32_16x16x32_bf16 v[156:159], v[40:43], v[202:205], v[156:159]
	v_mfma_f32_16x16x32_bf16 v[120:123], v[48:51], v[202:205], v[120:123]
	v_mfma_f32_16x16x32_bf16 v[152:155], v[44:47], v[80:83], v[152:155]
	v_mfma_f32_16x16x32_bf16 v[52:55], v[56:59], v[80:83], v[52:55]
	v_mfma_f32_16x16x32_bf16 v[148:151], v[44:47], v[178:181], v[148:151]
	v_mfma_f32_16x16x32_bf16 v[144:147], v[56:59], v[178:181], v[144:147]
	v_mfma_f32_16x16x32_bf16 v[140:143], v[44:47], v[198:201], v[140:143]
	v_mfma_f32_16x16x32_bf16 v[132:135], v[56:59], v[198:201], v[132:135]
	s_waitcnt lgkmcnt(0)
	v_mfma_f32_16x16x32_bf16 v[156:159], v[44:47], v[206:209], v[156:159]
	v_mfma_f32_16x16x32_bf16 v[120:123], v[56:59], v[206:209], v[120:123]
	v_mfma_f32_16x16x32_bf16 v[12:15], v[60:63], v[72:75], v[12:15]
	v_mfma_f32_16x16x32_bf16 v[8:11], v[170:173], v[72:75], v[8:11]
	v_mfma_f32_16x16x32_bf16 v[72:75], v[60:63], v[92:95], v[136:139]
	v_mfma_f32_16x16x32_bf16 v[136:139], v[160:163], v[178:181], v[72:75]
	v_mfma_f32_16x16x32_bf16 v[72:75], v[170:173], v[92:95], v[128:131]
	v_mfma_f32_16x16x32_bf16 v[128:131], v[174:177], v[178:181], v[72:75]
	v_mfma_f32_16x16x32_bf16 v[72:75], v[60:63], v[194:197], v[124:127]
	v_mfma_f32_16x16x32_bf16 v[124:127], v[160:163], v[198:201], v[72:75]
	v_mfma_f32_16x16x32_bf16 v[72:75], v[170:173], v[194:197], v[116:119]
	v_mfma_f32_16x16x32_bf16 v[116:119], v[174:177], v[198:201], v[72:75]
	v_mfma_f32_16x16x32_bf16 v[72:75], v[60:63], v[202:205], v[112:115]
	v_mfma_f32_16x16x32_bf16 v[112:115], v[160:163], v[206:209], v[72:75]
	v_mfma_f32_16x16x32_bf16 v[72:75], v[170:173], v[202:205], v[108:111]
	v_mfma_f32_16x16x32_bf16 v[12:15], v[160:163], v[80:83], v[12:15]
	v_mfma_f32_16x16x32_bf16 v[8:11], v[174:177], v[80:83], v[8:11]
	v_mfma_f32_16x16x32_bf16 v[108:111], v[174:177], v[206:209], v[72:75]
	s_barrier
	s_mov_b32 m0, s64
	s_or_b32 s94, s93, 0x80
	s_nop 0
	ds_read_b128 v[72:75], v190 offset:49152
	ds_read_b128 v[80:83], v190 offset:50176
	ds_read_b128 v[178:181], v190 offset:51200
	ds_read_b128 v[194:197], v190 offset:52224
	ds_read_b128 v[198:201], v190 offset:53248
	ds_read_b128 v[202:205], v190 offset:54272
	ds_read_b128 v[206:209], v190 offset:55296
	ds_read_b128 v[210:213], v190 offset:56320
	buffer_load_dwordx4 v183, s[16:19], s94 offen lds
	s_mov_b32 m0, s66
	s_add_i32 s93, s93, 0x80080
	buffer_load_dwordx4 v185, s[16:19], s94 offen lds
	s_mov_b32 m0, s69
	s_nop 0
	buffer_load_dwordx4 v183, s[16:19], s93 offen lds
	s_mov_b32 m0, s70
	s_nop 0
	buffer_load_dwordx4 v185, s[16:19], s93 offen lds
	s_mov_b32 m0, s67
	s_nop 0
	buffer_load_dwordx4 v182, s[12:15], s47 offen lds
	s_mov_b32 m0, s68
	s_nop 0
	buffer_load_dwordx4 v184, s[12:15], s47 offen lds
	s_waitcnt vmcnt(8)
	s_waitcnt lgkmcnt(0)
	s_barrier
	s_waitcnt lgkmcnt(7)
	v_mfma_f32_16x16x32_bf16 v[92:95], v[40:43], v[72:75], v[104:107]
	s_waitcnt lgkmcnt(6)
	v_mfma_f32_16x16x32_bf16 v[104:107], v[44:47], v[80:83], v[92:95]
	v_mfma_f32_16x16x32_bf16 v[92:95], v[48:51], v[72:75], v[100:103]
	v_mfma_f32_16x16x32_bf16 v[100:103], v[56:59], v[80:83], v[92:95]
	s_waitcnt lgkmcnt(5)
	v_mfma_f32_16x16x32_bf16 v[92:95], v[40:43], v[178:181], v[96:99]
	s_waitcnt lgkmcnt(1)
	v_mfma_f32_16x16x32_bf16 v[16:19], v[40:43], v[206:209], v[16:19]
	v_mfma_f32_16x16x32_bf16 v[96:99], v[44:47], v[194:197], v[92:95]
	v_mfma_f32_16x16x32_bf16 v[88:91], v[48:51], v[178:181], v[88:91]
	v_mfma_f32_16x16x32_bf16 v[84:87], v[40:43], v[198:201], v[84:87]
	v_mfma_f32_16x16x32_bf16 v[76:79], v[48:51], v[198:201], v[76:79]
	s_waitcnt lgkmcnt(0)
	v_mfma_f32_16x16x32_bf16 v[92:95], v[44:47], v[210:213], v[16:19]
	v_mfma_f32_16x16x32_bf16 v[16:19], v[48:51], v[206:209], v[20:23]
	v_mfma_f32_16x16x32_bf16 v[88:91], v[56:59], v[194:197], v[88:91]
	v_mfma_f32_16x16x32_bf16 v[84:87], v[44:47], v[202:205], v[84:87]
	v_mfma_f32_16x16x32_bf16 v[76:79], v[56:59], v[202:205], v[76:79]
	v_mfma_f32_16x16x32_bf16 v[48:51], v[56:59], v[210:213], v[16:19]
	v_mfma_f32_16x16x32_bf16 v[4:7], v[60:63], v[72:75], v[4:7]
	v_mfma_f32_16x16x32_bf16 v[0:3], v[170:173], v[72:75], v[0:3]
	v_mfma_f32_16x16x32_bf16 v[16:19], v[60:63], v[178:181], v[24:27]
	v_mfma_f32_16x16x32_bf16 v[4:7], v[160:163], v[80:83], v[4:7]
	v_mfma_f32_16x16x32_bf16 v[0:3], v[174:177], v[80:83], v[0:3]
	v_mfma_f32_16x16x32_bf16 v[80:83], v[160:163], v[194:197], v[16:19]
	v_mfma_f32_16x16x32_bf16 v[16:19], v[170:173], v[178:181], v[28:31]
	v_mfma_f32_16x16x32_bf16 v[72:75], v[174:177], v[194:197], v[16:19]
	v_mfma_f32_16x16x32_bf16 v[16:19], v[60:63], v[198:201], v[68:71]
	v_mfma_f32_16x16x32_bf16 v[68:71], v[160:163], v[202:205], v[16:19]
	v_mfma_f32_16x16x32_bf16 v[16:19], v[170:173], v[198:201], v[64:67]
	v_mfma_f32_16x16x32_bf16 v[64:67], v[174:177], v[202:205], v[16:19]
	v_mfma_f32_16x16x32_bf16 v[16:19], v[60:63], v[206:209], v[32:35]
	v_mfma_f32_16x16x32_bf16 v[60:63], v[160:163], v[210:213], v[16:19]
	v_mfma_f32_16x16x32_bf16 v[16:19], v[170:173], v[206:209], v[36:39]
	v_mfma_f32_16x16x32_bf16 v[56:59], v[174:177], v[210:213], v[16:19]
	s_barrier
	s_add_i32 s46, s46, 2
	s_addk_i32 s8, 0x100
	s_addk_i32 s9, 0x100
	s_cmp_gt_u32 s46, 29
	s_cbranch_scc0 .LBB0_658
	s_setprio 0
	s_and_b64 vcc, exec, s[26:27]
	s_cbranch_vccz .LBB0_661
	s_barrier

; #define PG8_STAGE(bufoff, soff, voff) do { _Pragma("unroll") for (int _i = 0; _i < 2; ++_i) \
;         __builtin_amdgcn_raw_ptr_buffer_load_lds(rs_##voff, (PG8_LAS unsigned*)(lds + (bufoff) + ldsw + _i * 8192), 16, (int)(voff)[_i], (int)(soff), 0, 0); } while (0)
; #define PG8_LDA(dst, b, h) do { _Pragma("unroll") for (int m = 0; m < 4; ++m) _Pragma("unroll") for (int k = 0; k < 2; ++k) dst[m][k] = *(const PG8_LAS bf16x8*)(lds + PG8_SA(b, h) + aoff + m * 2048 + k * 1024); } while (0)
; #define PG8_LDB(dst, b, h) do { _Pragma("unroll") for (int n = 0; n < 2; ++n) _Pragma("unroll") for (int k = 0; k < 2; ++k) dst[n][k] = *(const PG8_LAS bf16x8*)(lds + PG8_SB(b, h) + boff + n * 2048 + k * 1024); } while (0)
; #define PG8_WAIT_V(n) asm volatile("s_waitcnt vmcnt(" #n ")" ::: "memory")
; #define PG8_WAIT_L(n) asm volatile("s_waitcnt lgkmcnt(" #n ")" ::: "memory")
; template <class Epi, class Sched, bool ALIGN_EPI = false, bool SP2 = false>
; __device__ __forceinline__ void gemm_phase(PG8_LAS unsigned char* lds, const Gemm g, const Sched& S, const Epi& E, const int wid  ) {
;     ...
;         const bool has_next = S.next(ui + 1, nxt); nxt.same = (has_next && nxt.pm == cur.pm) ? 1 : 0;
;         const unsigned nA = has_next ? (unsigned)g.asel(nxt.pn) * (unsigned)g.a_stride + (unsigned)nxt.pm * tstep : cA, nB = has_next ? (unsigned)nxt.pn * tstep : cB;
;         for (int t = 0; t < nt; t += 2) {
;             const bool last = (t == nt - 2);
;             const unsigned a1 = cA + (unsigned)(t + 1) * kstep;
;             const unsigned a2 = last ? nA : cA + (unsigned)(t + 2) * kstep, b2 = last ? nB : cB + (unsigned)(t + 2) * kstep;
;             const unsigned a3 = a2 + kstep, b3 = b2 + kstep;
;             if (last && has_next) S.a_ready(nxt);
;             if constexpr (SP2) {
;             PG8_LDB(B0, 0, 0); PG8_LDB(B1, 0, 1); PG8_SCHED; PG8_LDA(At, 0, 0); PG8_STAGE(PG8_SA(1, 1), a1 + hstep, voffA);
;             PG8_WAIT_V(8); PG8_WAIT_L(0); PG8_BAR; PG8_MMA(0, 0, At, B0); PG8_MMA(0, 1, At, B1); PG8_BAR; PG8_SCHED;
;     ...
; #pragma unroll
;         for (int a = 0; a < 2; ++a)
; #pragma unroll
;             for (int b = 0; b < 2; ++b)
; #pragma unroll
;                 for (int m = 0; m < 4; ++m)
; #pragma unroll
;                     for (int n = 0; n < 2; ++n) acc[a][b][m][n] = (f32x4){0.f, 0.f, 0.f, 0.f};
;         cur = nxt; cA = nA; cB = nB; ++ui;
.LBB0_803:
	s_mul_i32 s50, s49, 0x2c0000
	s_and_b64 s[0:1], s[4:5], exec
	s_mul_i32 s51, s48, 0x2c0000
	v_mov_b32_e32 v0, 0
	s_cselect_b32 s0, s50, s54
	s_cselect_b32 s1, s51, s55
	s_add_i32 s54, s54, 0x160080
	s_addk_i32 s55, 0x100
	s_mov_b32 s58, -2
	s_waitcnt lgkmcnt(0)
	v_mov_b32_e32 v1, v0
	v_mov_b32_e32 v2, v0
	v_mov_b32_e32 v3, v0
	v_mov_b32_e32 v4, v0
	v_mov_b32_e32 v5, v0
	v_mov_b32_e32 v6, v0
	v_mov_b32_e32 v7, v0
	v_mov_b32_e32 v16, v0
	v_mov_b32_e32 v17, v0
	v_mov_b32_e32 v18, v0
	v_mov_b32_e32 v19, v0
	v_mov_b32_e32 v20, v0
	v_mov_b32_e32 v21, v0
	v_mov_b32_e32 v22, v0
	v_mov_b32_e32 v23, v0
	v_mov_b32_e32 v32, v0
	v_mov_b32_e32 v33, v0
	v_mov_b32_e32 v34, v0
	v_mov_b32_e32 v35, v0
	v_mov_b32_e32 v36, v0
	v_mov_b32_e32 v37, v0
	v_mov_b32_e32 v38, v0
	v_mov_b32_e32 v39, v0
	v_mov_b32_e32 v48, v0
	v_mov_b32_e32 v49, v0
	v_mov_b32_e32 v50, v0
	v_mov_b32_e32 v51, v0
	v_mov_b32_e32 v52, v0
	v_mov_b32_e32 v53, v0
	v_mov_b32_e32 v54, v0
	v_mov_b32_e32 v55, v0
	v_mov_b32_e32 v8, v0
	v_mov_b32_e32 v9, v0
	v_mov_b32_e32 v10, v0
	v_mov_b32_e32 v11, v0
	v_mov_b32_e32 v12, v0
	v_mov_b32_e32 v13, v0
	v_mov_b32_e32 v14, v0
	v_mov_b32_e32 v15, v0
	v_mov_b32_e32 v24, v0
	v_mov_b32_e32 v25, v0
	v_mov_b32_e32 v26, v0
	v_mov_b32_e32 v27, v0
	v_mov_b32_e32 v28, v0
	v_mov_b32_e32 v29, v0
	v_mov_b32_e32 v30, v0
	v_mov_b32_e32 v31, v0
	v_mov_b32_e32 v40, v0
	v_mov_b32_e32 v41, v0
	v_mov_b32_e32 v42, v0
	v_mov_b32_e32 v43, v0
	v_mov_b32_e32 v44, v0
	v_mov_b32_e32 v45, v0
	v_mov_b32_e32 v46, v0
	v_mov_b32_e32 v47, v0
	v_mov_b32_e32 v56, v0
	v_mov_b32_e32 v57, v0
	v_mov_b32_e32 v58, v0
	v_mov_b32_e32 v59, v0
	v_mov_b32_e32 v60, v0
	v_mov_b32_e32 v61, v0
	v_mov_b32_e32 v62, v0
	v_mov_b32_e32 v63, v0
	v_mov_b32_e32 v64, v0
	v_mov_b32_e32 v65, v0
	v_mov_b32_e32 v66, v0
	v_mov_b32_e32 v67, v0
	v_mov_b32_e32 v68, v0
	v_mov_b32_e32 v69, v0
	v_mov_b32_e32 v70, v0
	v_mov_b32_e32 v71, v0
	v_mov_b32_e32 v80, v0
	v_mov_b32_e32 v81, v0
	v_mov_b32_e32 v82, v0
	v_mov_b32_e32 v83, v0
	v_mov_b32_e32 v84, v0
	v_mov_b32_e32 v85, v0
	v_mov_b32_e32 v86, v0
	v_mov_b32_e32 v87, v0
	v_mov_b32_e32 v96, v0
	v_mov_b32_e32 v97, v0
	v_mov_b32_e32 v98, v0
	v_mov_b32_e32 v99, v0
	v_mov_b32_e32 v100, v0
	v_mov_b32_e32 v101, v0
	v_mov_b32_e32 v102, v0
	v_mov_b32_e32 v103, v0
	v_mov_b32_e32 v112, v0
	v_mov_b32_e32 v113, v0
	v_mov_b32_e32 v114, v0
	v_mov_b32_e32 v115, v0
	v_mov_b32_e32 v116, v0
	v_mov_b32_e32 v117, v0
	v_mov_b32_e32 v118, v0
	v_mov_b32_e32 v119, v0
	v_mov_b32_e32 v72, v0
	v_mov_b32_e32 v73, v0
	v_mov_b32_e32 v74, v0
	v_mov_b32_e32 v75, v0
	v_mov_b32_e32 v76, v0
	v_mov_b32_e32 v77, v0
	v_mov_b32_e32 v78, v0
	v_mov_b32_e32 v79, v0
	v_mov_b32_e32 v88, v0
	v_mov_b32_e32 v89, v0
	v_mov_b32_e32 v90, v0
	v_mov_b32_e32 v91, v0
	v_mov_b32_e32 v92, v0
	v_mov_b32_e32 v93, v0
	v_mov_b32_e32 v94, v0
	v_mov_b32_e32 v95, v0
	v_mov_b32_e32 v104, v0
	v_mov_b32_e32 v105, v0
	v_mov_b32_e32 v106, v0
	v_mov_b32_e32 v107, v0
	v_mov_b32_e32 v108, v0
	v_mov_b32_e32 v109, v0
	v_mov_b32_e32 v110, v0
	v_mov_b32_e32 v111, v0
	v_mov_b32_e32 v120, v0
	v_mov_b32_e32 v121, v0
	v_mov_b32_e32 v122, v0
	v_mov_b32_e32 v123, v0
	v_mov_b32_e32 v124, v0
	v_mov_b32_e32 v125, v0
	v_mov_b32_e32 v126, v0
	v_mov_b32_e32 v127, v0
	v_readlane_b32 vcc_lo, v246, 6
	s_nop 1
	s_cmp_ge_u32 vcc_lo, 4
	s_cbranch_scc0 .Lprio_804
	s_setprio 1
.Lprio_804:
.LBB0_804:
	ds_read_b128 v[132:135], v140
	ds_read_b128 v[146:149], v140 offset:1024
	ds_read_b128 v[150:153], v140 offset:2048
	ds_read_b128 v[154:157], v140 offset:3072
	ds_read_b128 v[158:161], v141
	ds_read_b128 v[162:165], v141 offset:1024
	ds_read_b128 v[166:169], v141 offset:2048
	ds_read_b128 v[170:173], v141 offset:3072
	s_add_i32 s14, s54, 0xffea0080
	s_cmpk_eq_i32 s58, 0x54
	s_cselect_b32 s61, s0, s14
	s_cselect_b32 s60, s1, s55
	s_or_b32 s59, s61, 0x80
	s_mov_b32 m0, s45
	ds_read_b128 v[174:177], v142
	ds_read_b128 v[178:181], v142 offset:1024
	ds_read_b128 v[182:185], v142 offset:2048
	ds_read_b128 v[186:189], v142 offset:3072
	ds_read_b128 v[190:193], v142 offset:4096
	ds_read_b128 v[194:197], v142 offset:5120
	ds_read_b128 v[198:201], v142 offset:6144
	ds_read_b128 v[202:205], v142 offset:7168
	buffer_load_dwordx4 v136, s[8:11], s54 offen lds
	s_mov_b32 m0, s46
	s_nop 0
	buffer_load_dwordx4 v138, s[8:11], s54 offen lds
	s_waitcnt vmcnt(8)
	s_waitcnt lgkmcnt(0)
	s_barrier
	s_waitcnt lgkmcnt(7)
	v_mfma_f32_16x16x32_bf16 v[124:127], v[132:135], v[174:177], v[124:127]
	v_mfma_f32_16x16x32_bf16 v[120:123], v[150:153], v[174:177], v[120:123]
	s_waitcnt lgkmcnt(5)
	v_mfma_f32_16x16x32_bf16 v[108:111], v[132:135], v[182:185], v[108:111]
	v_mfma_f32_16x16x32_bf16 v[104:107], v[150:153], v[182:185], v[104:107]
	s_waitcnt lgkmcnt(3)
	v_mfma_f32_16x16x32_bf16 v[92:95], v[132:135], v[190:193], v[92:95]
	v_mfma_f32_16x16x32_bf16 v[88:91], v[150:153], v[190:193], v[88:91]
	s_waitcnt lgkmcnt(1)
	v_mfma_f32_16x16x32_bf16 v[76:79], v[132:135], v[198:201], v[76:79]
	v_mfma_f32_16x16x32_bf16 v[72:75], v[150:153], v[198:201], v[72:75]
	v_mfma_f32_16x16x32_bf16 v[124:127], v[146:149], v[178:181], v[124:127]
	v_mfma_f32_16x16x32_bf16 v[120:123], v[154:157], v[178:181], v[120:123]
	v_mfma_f32_16x16x32_bf16 v[108:111], v[146:149], v[186:189], v[108:111]
	v_mfma_f32_16x16x32_bf16 v[104:107], v[154:157], v[186:189], v[104:107]
	v_mfma_f32_16x16x32_bf16 v[92:95], v[146:149], v[194:197], v[92:95]
	v_mfma_f32_16x16x32_bf16 v[88:91], v[154:157], v[194:197], v[88:91]
	s_waitcnt lgkmcnt(0)
	v_mfma_f32_16x16x32_bf16 v[76:79], v[146:149], v[202:205], v[76:79]
	v_mfma_f32_16x16x32_bf16 v[72:75], v[154:157], v[202:205], v[72:75]
	v_mfma_f32_16x16x32_bf16 v[116:119], v[158:161], v[174:177], v[116:119]
	v_mfma_f32_16x16x32_bf16 v[112:115], v[166:169], v[174:177], v[112:115]
	v_mfma_f32_16x16x32_bf16 v[100:103], v[158:161], v[182:185], v[100:103]
	v_mfma_f32_16x16x32_bf16 v[96:99], v[166:169], v[182:185], v[96:99]
	v_mfma_f32_16x16x32_bf16 v[84:87], v[158:161], v[190:193], v[84:87]
	v_mfma_f32_16x16x32_bf16 v[80:83], v[166:169], v[190:193], v[80:83]
	v_mfma_f32_16x16x32_bf16 v[68:71], v[158:161], v[198:201], v[68:71]
	v_mfma_f32_16x16x32_bf16 v[64:67], v[166:169], v[198:201], v[64:67]
	v_mfma_f32_16x16x32_bf16 v[116:119], v[162:165], v[178:181], v[116:119]
	v_mfma_f32_16x16x32_bf16 v[112:115], v[170:173], v[178:181], v[112:115]
	v_mfma_f32_16x16x32_bf16 v[100:103], v[162:165], v[186:189], v[100:103]
	v_mfma_f32_16x16x32_bf16 v[96:99], v[170:173], v[186:189], v[96:99]
	v_mfma_f32_16x16x32_bf16 v[84:87], v[162:165], v[194:197], v[84:87]
	v_mfma_f32_16x16x32_bf16 v[80:83], v[170:173], v[194:197], v[80:83]
	v_mfma_f32_16x16x32_bf16 v[68:71], v[162:165], v[202:205], v[68:71]
	v_mfma_f32_16x16x32_bf16 v[64:67], v[170:173], v[202:205], v[64:67]
	s_barrier
; #define PG8_STAGE(bufoff, soff, voff) do { _Pragma("unroll") for (int _i = 0; _i < 2; ++_i) \
;         __builtin_amdgcn_raw_ptr_buffer_load_lds(rs_##voff, (PG8_LAS unsigned*)(lds + (bufoff) + ldsw + _i * 8192), 16, (int)(voff)[_i], (int)(soff), 0, 0); } while (0)
; #define PG8_LDA(dst, b, h) do { _Pragma("unroll") for (int m = 0; m < 4; ++m) _Pragma("unroll") for (int k = 0; k < 2; ++k) dst[m][k] = *(const PG8_LAS bf16x8*)(lds + PG8_SA(b, h) + aoff + m * 2048 + k * 1024); } while (0)
; #define PG8_LDB(dst, b, h) do { _Pragma("unroll") for (int n = 0; n < 2; ++n) _Pragma("unroll") for (int k = 0; k < 2; ++k) dst[n][k] = *(const PG8_LAS bf16x8*)(lds + PG8_SB(b, h) + boff + n * 2048 + k * 1024); } while (0)
; #define PG8_MMA(ai, bj, At, Bt) do { __builtin_amdgcn_s_setprio(1); _Pragma("unroll") for (int m = 0; m < 4; ++m) _Pragma("unroll") for (int n = 0; n < 2; ++n) _Pragma("unroll") for (int k = 0; k < 2; ++k) \
;         acc[ai][bj][m][n] = __builtin_amdgcn_mfma_f32_16x16x32_bf16(Bt[n][k], At[m][k], acc[ai][bj][m][n], 0, 0, 0); __builtin_amdgcn_s_setprio(0); } while (0)
; #define PG8_WAIT_V(n) asm volatile("s_waitcnt vmcnt(" #n ")" ::: "memory")
; #define PG8_WAIT_L(n) asm volatile("s_waitcnt lgkmcnt(" #n ")" ::: "memory")
; #define PG8_BAR __builtin_amdgcn_s_barrier()
; #define PG8_SCHED __builtin_amdgcn_sched_barrier(0)
; template <class Epi, class Sched, bool ALIGN_EPI = false, bool SP2 = false>
; __device__ __forceinline__ void gemm_phase(PG8_LAS unsigned char* lds, const Gemm g, const Sched& S, const Epi& E, const int wid  ) {
;     ...
;             PG8_LDA(At, 0, 1); PG8_STAGE(PG8_SB(0, 0), b2, voffB); PG8_STAGE(PG8_SB(0, 1), b2 + hstep, voffB); PG8_STAGE(PG8_SA(0, 0), a2, voffA);
;             PG8_WAIT_V(8); PG8_WAIT_L(0); PG8_BAR; PG8_MMA(1, 0, At, B0); PG8_MMA(1, 1, At, B1); PG8_BAR; PG8_SCHED;
;             PG8_LDB(B0, 1, 0); PG8_LDB(B1, 1, 1); PG8_SCHED; PG8_LDA(At, 1, 0); PG8_STAGE(PG8_SA(0, 1), a2 + hstep, voffA);
;             PG8_WAIT_V(8); PG8_WAIT_L(0); PG8_BAR; PG8_MMA(0, 0, At, B0); PG8_MMA(0, 1, At, B1); PG8_BAR; PG8_SCHED;
	s_mov_b32 m0, s28
	s_mov_b32 s14, s10
	s_mov_b32 s15, s11
	ds_read_b128 v[174:177], v142 offset:16384
	ds_read_b128 v[178:181], v142 offset:17408
	ds_read_b128 v[182:185], v142 offset:18432
	ds_read_b128 v[186:189], v142 offset:19456
	ds_read_b128 v[190:193], v142 offset:20480
	ds_read_b128 v[194:197], v142 offset:21504
	ds_read_b128 v[198:201], v142 offset:22528
	ds_read_b128 v[202:205], v142 offset:23552
	buffer_load_dwordx4 v137, s[12:15], s60 offen lds
	s_mov_b32 m0, s29
	s_add_i32 s62, s60, 0x160000
	buffer_load_dwordx4 v139, s[12:15], s60 offen lds
	s_mov_b32 m0, s30
	s_nop 0
	buffer_load_dwordx4 v137, s[12:15], s62 offen lds
	s_mov_b32 m0, s31
	s_nop 0
	buffer_load_dwordx4 v139, s[12:15], s62 offen lds
	s_mov_b32 m0, s27
	s_nop 0
	buffer_load_dwordx4 v136, s[8:11], s61 offen lds
	s_mov_b32 m0, s33
	s_nop 0
	buffer_load_dwordx4 v138, s[8:11], s61 offen lds
	s_waitcnt vmcnt(8)
	s_waitcnt lgkmcnt(0)
	s_barrier
	s_waitcnt lgkmcnt(7)
	v_mfma_f32_16x16x32_bf16 v[60:63], v[132:135], v[174:177], v[60:63]
	v_mfma_f32_16x16x32_bf16 v[56:59], v[150:153], v[174:177], v[56:59]
	s_waitcnt lgkmcnt(5)
	v_mfma_f32_16x16x32_bf16 v[44:47], v[132:135], v[182:185], v[44:47]
	v_mfma_f32_16x16x32_bf16 v[40:43], v[150:153], v[182:185], v[40:43]
	s_waitcnt lgkmcnt(3)
	v_mfma_f32_16x16x32_bf16 v[28:31], v[132:135], v[190:193], v[28:31]
	v_mfma_f32_16x16x32_bf16 v[24:27], v[150:153], v[190:193], v[24:27]
	s_waitcnt lgkmcnt(1)
	v_mfma_f32_16x16x32_bf16 v[12:15], v[132:135], v[198:201], v[12:15]
	v_mfma_f32_16x16x32_bf16 v[8:11], v[150:153], v[198:201], v[8:11]
	v_mfma_f32_16x16x32_bf16 v[60:63], v[146:149], v[178:181], v[60:63]
	v_mfma_f32_16x16x32_bf16 v[56:59], v[154:157], v[178:181], v[56:59]
	v_mfma_f32_16x16x32_bf16 v[44:47], v[146:149], v[186:189], v[44:47]
	v_mfma_f32_16x16x32_bf16 v[40:43], v[154:157], v[186:189], v[40:43]
	v_mfma_f32_16x16x32_bf16 v[28:31], v[146:149], v[194:197], v[28:31]
	v_mfma_f32_16x16x32_bf16 v[24:27], v[154:157], v[194:197], v[24:27]
	s_waitcnt lgkmcnt(0)
	v_mfma_f32_16x16x32_bf16 v[12:15], v[146:149], v[202:205], v[12:15]
	v_mfma_f32_16x16x32_bf16 v[8:11], v[154:157], v[202:205], v[8:11]
	v_mfma_f32_16x16x32_bf16 v[52:55], v[158:161], v[174:177], v[52:55]
	v_mfma_f32_16x16x32_bf16 v[48:51], v[166:169], v[174:177], v[48:51]
	v_mfma_f32_16x16x32_bf16 v[36:39], v[158:161], v[182:185], v[36:39]
	v_mfma_f32_16x16x32_bf16 v[32:35], v[166:169], v[182:185], v[32:35]
	v_mfma_f32_16x16x32_bf16 v[20:23], v[158:161], v[190:193], v[20:23]
	v_mfma_f32_16x16x32_bf16 v[16:19], v[166:169], v[190:193], v[16:19]
	v_mfma_f32_16x16x32_bf16 v[4:7], v[158:161], v[198:201], v[4:7]
	v_mfma_f32_16x16x32_bf16 v[0:3], v[166:169], v[198:201], v[0:3]
	v_mfma_f32_16x16x32_bf16 v[52:55], v[162:165], v[178:181], v[52:55]
	v_mfma_f32_16x16x32_bf16 v[48:51], v[170:173], v[178:181], v[48:51]
	v_mfma_f32_16x16x32_bf16 v[36:39], v[162:165], v[186:189], v[36:39]
	v_mfma_f32_16x16x32_bf16 v[32:35], v[170:173], v[186:189], v[32:35]
	v_mfma_f32_16x16x32_bf16 v[20:23], v[162:165], v[194:197], v[20:23]
	v_mfma_f32_16x16x32_bf16 v[16:19], v[170:173], v[194:197], v[16:19]
	v_mfma_f32_16x16x32_bf16 v[4:7], v[162:165], v[202:205], v[4:7]
	v_mfma_f32_16x16x32_bf16 v[0:3], v[170:173], v[202:205], v[0:3]
	s_barrier
	ds_read_b128 v[132:135], v143
	ds_read_b128 v[146:149], v143 offset:1024
	ds_read_b128 v[150:153], v143 offset:2048
	ds_read_b128 v[154:157], v143 offset:3072
	ds_read_b128 v[158:161], v144
	ds_read_b128 v[162:165], v144 offset:1024
	ds_read_b128 v[166:169], v144 offset:2048
	ds_read_b128 v[170:173], v144 offset:3072
	s_add_i32 s61, s61, 0x160000
	s_mov_b32 m0, s34
	ds_read_b128 v[174:177], v142 offset:32768
	ds_read_b128 v[178:181], v142 offset:33792
	ds_read_b128 v[182:185], v142 offset:34816
	ds_read_b128 v[186:189], v142 offset:35840
	ds_read_b128 v[190:193], v142 offset:36864
	ds_read_b128 v[194:197], v142 offset:37888
	ds_read_b128 v[198:201], v142 offset:38912
	ds_read_b128 v[202:205], v142 offset:39936
	buffer_load_dwordx4 v136, s[8:11], s61 offen lds
	s_mov_b32 m0, s35
	s_nop 0
	buffer_load_dwordx4 v138, s[8:11], s61 offen lds
	s_waitcnt vmcnt(8)
	s_waitcnt lgkmcnt(0)
	s_barrier
; #define PG8_STAGE(bufoff, soff, voff) do { _Pragma("unroll") for (int _i = 0; _i < 2; ++_i) \
;         __builtin_amdgcn_raw_ptr_buffer_load_lds(rs_##voff, (PG8_LAS unsigned*)(lds + (bufoff) + ldsw + _i * 8192), 16, (int)(voff)[_i], (int)(soff), 0, 0); } while (0)
; #define PG8_LDA(dst, b, h) do { _Pragma("unroll") for (int m = 0; m < 4; ++m) _Pragma("unroll") for (int k = 0; k < 2; ++k) dst[m][k] = *(const PG8_LAS bf16x8*)(lds + PG8_SA(b, h) + aoff + m * 2048 + k * 1024); } while (0)
; #define PG8_MMA(ai, bj, At, Bt) do { __builtin_amdgcn_s_setprio(1); _Pragma("unroll") for (int m = 0; m < 4; ++m) _Pragma("unroll") for (int n = 0; n < 2; ++n) _Pragma("unroll") for (int k = 0; k < 2; ++k) \
;         acc[ai][bj][m][n] = __builtin_amdgcn_mfma_f32_16x16x32_bf16(Bt[n][k], At[m][k], acc[ai][bj][m][n], 0, 0, 0); __builtin_amdgcn_s_setprio(0); } while (0)
; #define PG8_WAIT_V(n) asm volatile("s_waitcnt vmcnt(" #n ")" ::: "memory")
; #define PG8_WAIT_L(n) asm volatile("s_waitcnt lgkmcnt(" #n ")" ::: "memory")
; #define PG8_BAR __builtin_amdgcn_s_barrier()
; #define PG8_SCHED __builtin_amdgcn_sched_barrier(0)
; template <class Epi, class Sched, bool ALIGN_EPI = false, bool SP2 = false>
; __device__ __forceinline__ void gemm_phase(PG8_LAS unsigned char* lds, const Gemm g, const Sched& S, const Epi& E, const int wid  ) {
;     ...
;             PG8_WAIT_V(8); PG8_WAIT_L(0); PG8_BAR; PG8_MMA(0, 0, At, B0); PG8_MMA(0, 1, At, B1); PG8_BAR; PG8_SCHED;
;             PG8_LDA(At, 1, 1); PG8_STAGE(PG8_SB(1, 0), b3, voffB); PG8_STAGE(PG8_SB(1, 1), b3 + hstep, voffB); PG8_STAGE(PG8_SA(1, 0), a3, voffA);
;             PG8_WAIT_V(8); PG8_WAIT_L(0); PG8_BAR; PG8_MMA(1, 0, At, B0); PG8_MMA(1, 1, At, B1); PG8_BAR; PG8_SCHED;
	s_waitcnt lgkmcnt(7)
	v_mfma_f32_16x16x32_bf16 v[124:127], v[132:135], v[174:177], v[124:127]
	v_mfma_f32_16x16x32_bf16 v[120:123], v[150:153], v[174:177], v[120:123]
	s_waitcnt lgkmcnt(5)
	v_mfma_f32_16x16x32_bf16 v[108:111], v[132:135], v[182:185], v[108:111]
	v_mfma_f32_16x16x32_bf16 v[104:107], v[150:153], v[182:185], v[104:107]
	s_waitcnt lgkmcnt(3)
	v_mfma_f32_16x16x32_bf16 v[92:95], v[132:135], v[190:193], v[92:95]
	v_mfma_f32_16x16x32_bf16 v[88:91], v[150:153], v[190:193], v[88:91]
	s_waitcnt lgkmcnt(1)
	v_mfma_f32_16x16x32_bf16 v[76:79], v[132:135], v[198:201], v[76:79]
	v_mfma_f32_16x16x32_bf16 v[72:75], v[150:153], v[198:201], v[72:75]
	v_mfma_f32_16x16x32_bf16 v[124:127], v[146:149], v[178:181], v[124:127]
	v_mfma_f32_16x16x32_bf16 v[120:123], v[154:157], v[178:181], v[120:123]
	v_mfma_f32_16x16x32_bf16 v[108:111], v[146:149], v[186:189], v[108:111]
	v_mfma_f32_16x16x32_bf16 v[104:107], v[154:157], v[186:189], v[104:107]
	v_mfma_f32_16x16x32_bf16 v[92:95], v[146:149], v[194:197], v[92:95]
	v_mfma_f32_16x16x32_bf16 v[88:91], v[154:157], v[194:197], v[88:91]
	s_waitcnt lgkmcnt(0)
	v_mfma_f32_16x16x32_bf16 v[76:79], v[146:149], v[202:205], v[76:79]
	v_mfma_f32_16x16x32_bf16 v[72:75], v[154:157], v[202:205], v[72:75]
	v_mfma_f32_16x16x32_bf16 v[116:119], v[158:161], v[174:177], v[116:119]
	v_mfma_f32_16x16x32_bf16 v[112:115], v[166:169], v[174:177], v[112:115]
	v_mfma_f32_16x16x32_bf16 v[100:103], v[158:161], v[182:185], v[100:103]
	v_mfma_f32_16x16x32_bf16 v[96:99], v[166:169], v[182:185], v[96:99]
	v_mfma_f32_16x16x32_bf16 v[84:87], v[158:161], v[190:193], v[84:87]
	v_mfma_f32_16x16x32_bf16 v[80:83], v[166:169], v[190:193], v[80:83]
	v_mfma_f32_16x16x32_bf16 v[68:71], v[158:161], v[198:201], v[68:71]
	v_mfma_f32_16x16x32_bf16 v[64:67], v[166:169], v[198:201], v[64:67]
	v_mfma_f32_16x16x32_bf16 v[116:119], v[162:165], v[178:181], v[116:119]
	v_mfma_f32_16x16x32_bf16 v[112:115], v[170:173], v[178:181], v[112:115]
	v_mfma_f32_16x16x32_bf16 v[100:103], v[162:165], v[186:189], v[100:103]
	v_mfma_f32_16x16x32_bf16 v[96:99], v[170:173], v[186:189], v[96:99]
	v_mfma_f32_16x16x32_bf16 v[84:87], v[162:165], v[194:197], v[84:87]
	v_mfma_f32_16x16x32_bf16 v[80:83], v[170:173], v[194:197], v[80:83]
	v_mfma_f32_16x16x32_bf16 v[68:71], v[162:165], v[202:205], v[68:71]
	v_mfma_f32_16x16x32_bf16 v[64:67], v[170:173], v[202:205], v[64:67]
	s_barrier
	s_mov_b32 m0, s36
	s_or_b32 s61, s60, 0x80
	ds_read_b128 v[174:177], v142 offset:49152
	ds_read_b128 v[178:181], v142 offset:50176
	ds_read_b128 v[182:185], v142 offset:51200
	ds_read_b128 v[186:189], v142 offset:52224
	ds_read_b128 v[190:193], v142 offset:53248
	ds_read_b128 v[194:197], v142 offset:54272
	ds_read_b128 v[198:201], v142 offset:55296
	ds_read_b128 v[202:205], v142 offset:56320
	buffer_load_dwordx4 v137, s[12:15], s61 offen lds
	s_mov_b32 m0, s37
	s_add_i32 s60, s60, 0x160080
	buffer_load_dwordx4 v139, s[12:15], s61 offen lds
	s_mov_b32 m0, s40
	s_nop 0
	buffer_load_dwordx4 v137, s[12:15], s60 offen lds
	s_mov_b32 m0, s41
	s_nop 0
	buffer_load_dwordx4 v139, s[12:15], s60 offen lds
	s_mov_b32 m0, s38
	s_nop 0
	buffer_load_dwordx4 v136, s[8:11], s59 offen lds
	s_mov_b32 m0, s39
	s_nop 0
	buffer_load_dwordx4 v138, s[8:11], s59 offen lds
	s_waitcnt vmcnt(8)
	s_waitcnt lgkmcnt(0)
	s_barrier
	s_waitcnt lgkmcnt(7)
	v_mfma_f32_16x16x32_bf16 v[60:63], v[132:135], v[174:177], v[60:63]
	v_mfma_f32_16x16x32_bf16 v[56:59], v[150:153], v[174:177], v[56:59]
	s_waitcnt lgkmcnt(5)
	v_mfma_f32_16x16x32_bf16 v[44:47], v[132:135], v[182:185], v[44:47]
	v_mfma_f32_16x16x32_bf16 v[40:43], v[150:153], v[182:185], v[40:43]
	s_waitcnt lgkmcnt(3)
	v_mfma_f32_16x16x32_bf16 v[28:31], v[132:135], v[190:193], v[28:31]
	v_mfma_f32_16x16x32_bf16 v[24:27], v[150:153], v[190:193], v[24:27]
	s_waitcnt lgkmcnt(1)
	v_mfma_f32_16x16x32_bf16 v[12:15], v[132:135], v[198:201], v[12:15]
	v_mfma_f32_16x16x32_bf16 v[8:11], v[150:153], v[198:201], v[8:11]
	v_mfma_f32_16x16x32_bf16 v[60:63], v[146:149], v[178:181], v[60:63]
	v_mfma_f32_16x16x32_bf16 v[56:59], v[154:157], v[178:181], v[56:59]
	v_mfma_f32_16x16x32_bf16 v[44:47], v[146:149], v[186:189], v[44:47]
	v_mfma_f32_16x16x32_bf16 v[40:43], v[154:157], v[186:189], v[40:43]
	v_mfma_f32_16x16x32_bf16 v[28:31], v[146:149], v[194:197], v[28:31]
	v_mfma_f32_16x16x32_bf16 v[24:27], v[154:157], v[194:197], v[24:27]
	s_waitcnt lgkmcnt(0)
	v_mfma_f32_16x16x32_bf16 v[12:15], v[146:149], v[202:205], v[12:15]
	v_mfma_f32_16x16x32_bf16 v[8:11], v[154:157], v[202:205], v[8:11]
	v_mfma_f32_16x16x32_bf16 v[52:55], v[158:161], v[174:177], v[52:55]
	v_mfma_f32_16x16x32_bf16 v[48:51], v[166:169], v[174:177], v[48:51]
	v_mfma_f32_16x16x32_bf16 v[36:39], v[158:161], v[182:185], v[36:39]
	v_mfma_f32_16x16x32_bf16 v[32:35], v[166:169], v[182:185], v[32:35]
	v_mfma_f32_16x16x32_bf16 v[20:23], v[158:161], v[190:193], v[20:23]
	v_mfma_f32_16x16x32_bf16 v[16:19], v[166:169], v[190:193], v[16:19]
	v_mfma_f32_16x16x32_bf16 v[4:7], v[158:161], v[198:201], v[4:7]
	v_mfma_f32_16x16x32_bf16 v[0:3], v[166:169], v[198:201], v[0:3]
	v_mfma_f32_16x16x32_bf16 v[52:55], v[162:165], v[178:181], v[52:55]
	v_mfma_f32_16x16x32_bf16 v[48:51], v[170:173], v[178:181], v[48:51]
	v_mfma_f32_16x16x32_bf16 v[36:39], v[162:165], v[186:189], v[36:39]
	v_mfma_f32_16x16x32_bf16 v[32:35], v[170:173], v[186:189], v[32:35]
	v_mfma_f32_16x16x32_bf16 v[20:23], v[162:165], v[194:197], v[20:23]
	v_mfma_f32_16x16x32_bf16 v[16:19], v[170:173], v[194:197], v[16:19]
	v_mfma_f32_16x16x32_bf16 v[4:7], v[162:165], v[202:205], v[4:7]
	v_mfma_f32_16x16x32_bf16 v[0:3], v[170:173], v[202:205], v[0:3]
	s_barrier
	s_add_i32 s58, s58, 2
	s_addk_i32 s54, 0x100
	s_addk_i32 s55, 0x100
	s_cmpk_gt_u32 s58, 0x55
	s_cbranch_scc0 .LBB0_804
	s_setprio 0
	s_and_b64 vcc, exec, s[24:25]
	s_cbranch_vccz .LBB0_807
	s_barrier

; #define PG8_STAGE(bufoff, soff, voff) do { _Pragma("unroll") for (int _i = 0; _i < 2; ++_i) \
;         __builtin_amdgcn_raw_ptr_buffer_load_lds(rs_##voff, (PG8_LAS unsigned*)(lds + (bufoff) + ldsw + _i * 8192), 16, (int)(voff)[_i], (int)(soff), 0, 0); } while (0)
; #define PG8_LDA(dst, b, h) do { _Pragma("unroll") for (int m = 0; m < 4; ++m) _Pragma("unroll") for (int k = 0; k < 2; ++k) dst[m][k] = *(const PG8_LAS bf16x8*)(lds + PG8_SA(b, h) + aoff + m * 2048 + k * 1024); } while (0)
; #define PG8_LDB(dst, b, h) do { _Pragma("unroll") for (int n = 0; n < 2; ++n) _Pragma("unroll") for (int k = 0; k < 2; ++k) dst[n][k] = *(const PG8_LAS bf16x8*)(lds + PG8_SB(b, h) + boff + n * 2048 + k * 1024); } while (0)
; #define PG8_MMA(ai, bj, At, Bt) do { __builtin_amdgcn_s_setprio(1); _Pragma("unroll") for (int m = 0; m < 4; ++m) _Pragma("unroll") for (int n = 0; n < 2; ++n) _Pragma("unroll") for (int k = 0; k < 2; ++k) \
;         acc[ai][bj][m][n] = __builtin_amdgcn_mfma_f32_16x16x32_bf16(Bt[n][k], At[m][k], acc[ai][bj][m][n], 0, 0, 0); __builtin_amdgcn_s_setprio(0); } while (0)
; #define PG8_WAIT_V(n) asm volatile("s_waitcnt vmcnt(" #n ")" ::: "memory")
; #define PG8_WAIT_L(n) asm volatile("s_waitcnt lgkmcnt(" #n ")" ::: "memory")
; #define PG8_BAR __builtin_amdgcn_s_barrier()
; #define PG8_SCHED __builtin_amdgcn_sched_barrier(0)
; template <class Epi, class Sched, bool ALIGN_EPI = false, bool SP2 = false>
; __device__ __forceinline__ void gemm_phase(PG8_LAS unsigned char* lds, const Gemm g, const Sched& S, const Epi& E, const int wid  ) {
;     ...
;             PG8_LDB(B0, 0, 0); PG8_LDB(B1, 0, 1); PG8_SCHED; PG8_LDA(At, 0, 0); PG8_STAGE(PG8_SA(1, 1), a1 + hstep, voffA);
;             PG8_WAIT_V(8); PG8_WAIT_L(0); PG8_BAR; PG8_MMA(0, 0, At, B0); PG8_MMA(0, 1, At, B1); PG8_BAR; PG8_SCHED;
;     ...
; #pragma unroll
;         for (int a = 0; a < 2; ++a)
; #pragma unroll
;             for (int b = 0; b < 2; ++b)
; #pragma unroll
;                 for (int m = 0; m < 4; ++m)
; #pragma unroll
;                     for (int n = 0; n < 2; ++n) acc[a][b][m][n] = (f32x4){0.f, 0.f, 0.f, 0.f};
;         cur = nxt; cA = nA; cB = nB; ++ui;
.LBB0_902:
	s_lshl_b32 s70, s69, 20
	s_and_b64 s[14:15], s[4:5], exec
	s_cselect_b32 s33, s70, s41
	s_lshl_b32 s71, s68, 20
	s_and_b64 s[14:15], s[4:5], exec
	v_mov_b32_e32 v0, 0
	s_cselect_b32 s40, s71, s74
	s_add_i32 s41, s41, 0x80080
	s_addk_i32 s74, 0x100
	s_mov_b32 s75, -2
	s_waitcnt lgkmcnt(0)
	v_mov_b32_e32 v1, v0
	v_mov_b32_e32 v2, v0
	v_mov_b32_e32 v3, v0
	v_mov_b32_e32 v4, v0
	v_mov_b32_e32 v5, v0
	s_waitcnt lgkmcnt(6)
	v_mov_b32_e32 v6, v0
	v_mov_b32_e32 v7, v0
	s_waitcnt lgkmcnt(1)
	v_mov_b32_e32 v16, v0
	v_mov_b32_e32 v17, v0
	s_waitcnt lgkmcnt(0)
	v_mov_b32_e32 v18, v0
	v_mov_b32_e32 v19, v0
	v_mov_b32_e32 v20, v0
	v_mov_b32_e32 v21, v0
	v_mov_b32_e32 v22, v0
	v_mov_b32_e32 v23, v0
	v_mov_b32_e32 v32, v0
	v_mov_b32_e32 v33, v0
	v_mov_b32_e32 v34, v0
	v_mov_b32_e32 v35, v0
	v_mov_b32_e32 v36, v0
	v_mov_b32_e32 v37, v0
	v_mov_b32_e32 v38, v0
	v_mov_b32_e32 v39, v0
	v_mov_b32_e32 v48, v0
	v_mov_b32_e32 v49, v0
	v_mov_b32_e32 v50, v0
	v_mov_b32_e32 v51, v0
	v_mov_b32_e32 v52, v0
	v_mov_b32_e32 v53, v0
	v_mov_b32_e32 v54, v0
	v_mov_b32_e32 v55, v0
	v_mov_b32_e32 v8, v0
	v_mov_b32_e32 v9, v0
	v_mov_b32_e32 v10, v0
	v_mov_b32_e32 v11, v0
	v_mov_b32_e32 v12, v0
	v_mov_b32_e32 v13, v0
	v_mov_b32_e32 v14, v0
	v_mov_b32_e32 v15, v0
	v_mov_b32_e32 v24, v0
	v_mov_b32_e32 v25, v0
	v_mov_b32_e32 v26, v0
	v_mov_b32_e32 v27, v0
	v_mov_b32_e32 v28, v0
	v_mov_b32_e32 v29, v0
	v_mov_b32_e32 v30, v0
	v_mov_b32_e32 v31, v0
	v_mov_b32_e32 v40, v0
	v_mov_b32_e32 v41, v0
	v_mov_b32_e32 v42, v0
	v_mov_b32_e32 v43, v0
	v_mov_b32_e32 v44, v0
	v_mov_b32_e32 v45, v0
	v_mov_b32_e32 v46, v0
	v_mov_b32_e32 v47, v0
	v_mov_b32_e32 v56, v0
	v_mov_b32_e32 v57, v0
	v_mov_b32_e32 v58, v0
	v_mov_b32_e32 v59, v0
	v_mov_b32_e32 v60, v0
	v_mov_b32_e32 v61, v0
	v_mov_b32_e32 v62, v0
	v_mov_b32_e32 v63, v0
	v_mov_b32_e32 v64, v0
	v_mov_b32_e32 v65, v0
	v_mov_b32_e32 v66, v0
	v_mov_b32_e32 v67, v0
	v_mov_b32_e32 v68, v0
	v_mov_b32_e32 v69, v0
	v_mov_b32_e32 v70, v0
	v_mov_b32_e32 v71, v0
	v_mov_b32_e32 v80, v0
	v_mov_b32_e32 v81, v0
	v_mov_b32_e32 v82, v0
	v_mov_b32_e32 v83, v0
	v_mov_b32_e32 v84, v0
	v_mov_b32_e32 v85, v0
	v_mov_b32_e32 v86, v0
	v_mov_b32_e32 v87, v0
	v_mov_b32_e32 v96, v0
	v_mov_b32_e32 v97, v0
	v_mov_b32_e32 v98, v0
	v_mov_b32_e32 v99, v0
	v_mov_b32_e32 v100, v0
	v_mov_b32_e32 v101, v0
	v_mov_b32_e32 v102, v0
	v_mov_b32_e32 v103, v0
	v_mov_b32_e32 v112, v0
	v_mov_b32_e32 v113, v0
	v_mov_b32_e32 v114, v0
	v_mov_b32_e32 v115, v0
	v_mov_b32_e32 v116, v0
	v_mov_b32_e32 v117, v0
	v_mov_b32_e32 v118, v0
	v_mov_b32_e32 v119, v0
	v_mov_b32_e32 v72, v0
	v_mov_b32_e32 v73, v0
	v_mov_b32_e32 v74, v0
	v_mov_b32_e32 v75, v0
	v_mov_b32_e32 v76, v0
	v_mov_b32_e32 v77, v0
	v_mov_b32_e32 v78, v0
	v_mov_b32_e32 v79, v0
	v_mov_b32_e32 v88, v0
	v_mov_b32_e32 v89, v0
	v_mov_b32_e32 v90, v0
	v_mov_b32_e32 v91, v0
	v_mov_b32_e32 v92, v0
	v_mov_b32_e32 v93, v0
	v_mov_b32_e32 v94, v0
	v_mov_b32_e32 v95, v0
	v_mov_b32_e32 v104, v0
	v_mov_b32_e32 v105, v0
	v_mov_b32_e32 v106, v0
	v_mov_b32_e32 v107, v0
	v_mov_b32_e32 v108, v0
	v_mov_b32_e32 v109, v0
	v_mov_b32_e32 v110, v0
	v_mov_b32_e32 v111, v0
	v_mov_b32_e32 v120, v0
	v_mov_b32_e32 v121, v0
	v_mov_b32_e32 v122, v0
	v_mov_b32_e32 v123, v0
	v_mov_b32_e32 v124, v0
	v_mov_b32_e32 v125, v0
	v_mov_b32_e32 v126, v0
	v_mov_b32_e32 v127, v0
	v_readlane_b32 vcc_lo, v246, 6
	s_nop 1
	s_cmp_ge_u32 vcc_lo, 4
	s_cbranch_scc0 .Lprio_903
	s_setprio 1
.Lprio_903:
.LBB0_903:
	ds_read_b128 v[132:135], v152
	ds_read_b128 v[136:139], v152 offset:1024
	ds_read_b128 v[140:143], v152 offset:2048
	ds_read_b128 v[158:161], v152 offset:3072
	ds_read_b128 v[162:165], v153
	ds_read_b128 v[166:169], v153 offset:1024
	ds_read_b128 v[170:173], v153 offset:2048
	ds_read_b128 v[174:177], v153 offset:3072
	s_add_i32 s14, s41, 0xfff80080
	s_cmp_eq_u32 s75, 28
	s_cselect_b32 s78, s33, s14
	s_cselect_b32 s77, s40, s74
	s_or_b32 s76, s78, 0x80
	s_mov_b32 m0, s60
	ds_read_b128 v[178:181], v154
	ds_read_b128 v[182:185], v154 offset:1024
	ds_read_b128 v[186:189], v154 offset:2048
	ds_read_b128 v[190:193], v154 offset:3072
	ds_read_b128 v[194:197], v154 offset:4096
	ds_read_b128 v[198:201], v154 offset:5120
	ds_read_b128 v[202:205], v154 offset:6144
	ds_read_b128 v[206:209], v154 offset:7168
	buffer_load_dwordx4 v146, s[8:11], s41 offen lds
	s_mov_b32 m0, s61
	s_nop 0
	buffer_load_dwordx4 v148, s[8:11], s41 offen lds
	s_waitcnt vmcnt(8)
	s_waitcnt lgkmcnt(0)
	s_barrier
	s_waitcnt lgkmcnt(7)
	v_mfma_f32_16x16x32_bf16 v[124:127], v[132:135], v[178:181], v[124:127]
	v_mfma_f32_16x16x32_bf16 v[120:123], v[140:143], v[178:181], v[120:123]
	s_waitcnt lgkmcnt(5)
	v_mfma_f32_16x16x32_bf16 v[108:111], v[132:135], v[186:189], v[108:111]
	v_mfma_f32_16x16x32_bf16 v[104:107], v[140:143], v[186:189], v[104:107]
	s_waitcnt lgkmcnt(3)
	v_mfma_f32_16x16x32_bf16 v[92:95], v[132:135], v[194:197], v[92:95]
	v_mfma_f32_16x16x32_bf16 v[88:91], v[140:143], v[194:197], v[88:91]
	s_waitcnt lgkmcnt(1)
	v_mfma_f32_16x16x32_bf16 v[76:79], v[132:135], v[202:205], v[76:79]
	v_mfma_f32_16x16x32_bf16 v[72:75], v[140:143], v[202:205], v[72:75]
	v_mfma_f32_16x16x32_bf16 v[124:127], v[136:139], v[182:185], v[124:127]
	v_mfma_f32_16x16x32_bf16 v[120:123], v[158:161], v[182:185], v[120:123]
	v_mfma_f32_16x16x32_bf16 v[108:111], v[136:139], v[190:193], v[108:111]
	v_mfma_f32_16x16x32_bf16 v[104:107], v[158:161], v[190:193], v[104:107]
	v_mfma_f32_16x16x32_bf16 v[92:95], v[136:139], v[198:201], v[92:95]
	v_mfma_f32_16x16x32_bf16 v[88:91], v[158:161], v[198:201], v[88:91]
	s_waitcnt lgkmcnt(0)
	v_mfma_f32_16x16x32_bf16 v[76:79], v[136:139], v[206:209], v[76:79]
	v_mfma_f32_16x16x32_bf16 v[72:75], v[158:161], v[206:209], v[72:75]
	v_mfma_f32_16x16x32_bf16 v[116:119], v[162:165], v[178:181], v[116:119]
	v_mfma_f32_16x16x32_bf16 v[112:115], v[170:173], v[178:181], v[112:115]
	v_mfma_f32_16x16x32_bf16 v[100:103], v[162:165], v[186:189], v[100:103]
	v_mfma_f32_16x16x32_bf16 v[96:99], v[170:173], v[186:189], v[96:99]
	v_mfma_f32_16x16x32_bf16 v[84:87], v[162:165], v[194:197], v[84:87]
	v_mfma_f32_16x16x32_bf16 v[80:83], v[170:173], v[194:197], v[80:83]
	v_mfma_f32_16x16x32_bf16 v[68:71], v[162:165], v[202:205], v[68:71]
	v_mfma_f32_16x16x32_bf16 v[64:67], v[170:173], v[202:205], v[64:67]
	v_mfma_f32_16x16x32_bf16 v[116:119], v[166:169], v[182:185], v[116:119]
	v_mfma_f32_16x16x32_bf16 v[112:115], v[174:177], v[182:185], v[112:115]
	v_mfma_f32_16x16x32_bf16 v[100:103], v[166:169], v[190:193], v[100:103]
	v_mfma_f32_16x16x32_bf16 v[96:99], v[174:177], v[190:193], v[96:99]
	v_mfma_f32_16x16x32_bf16 v[84:87], v[166:169], v[198:201], v[84:87]
	v_mfma_f32_16x16x32_bf16 v[80:83], v[174:177], v[198:201], v[80:83]
	v_mfma_f32_16x16x32_bf16 v[68:71], v[166:169], v[206:209], v[68:71]
	v_mfma_f32_16x16x32_bf16 v[64:67], v[174:177], v[206:209], v[64:67]
	s_barrier
; #define PG8_STAGE(bufoff, soff, voff) do { _Pragma("unroll") for (int _i = 0; _i < 2; ++_i) \
;         __builtin_amdgcn_raw_ptr_buffer_load_lds(rs_##voff, (PG8_LAS unsigned*)(lds + (bufoff) + ldsw + _i * 8192), 16, (int)(voff)[_i], (int)(soff), 0, 0); } while (0)
; #define PG8_LDA(dst, b, h) do { _Pragma("unroll") for (int m = 0; m < 4; ++m) _Pragma("unroll") for (int k = 0; k < 2; ++k) dst[m][k] = *(const PG8_LAS bf16x8*)(lds + PG8_SA(b, h) + aoff + m * 2048 + k * 1024); } while (0)
; #define PG8_LDB(dst, b, h) do { _Pragma("unroll") for (int n = 0; n < 2; ++n) _Pragma("unroll") for (int k = 0; k < 2; ++k) dst[n][k] = *(const PG8_LAS bf16x8*)(lds + PG8_SB(b, h) + boff + n * 2048 + k * 1024); } while (0)
; #define PG8_MMA(ai, bj, At, Bt) do { __builtin_amdgcn_s_setprio(1); _Pragma("unroll") for (int m = 0; m < 4; ++m) _Pragma("unroll") for (int n = 0; n < 2; ++n) _Pragma("unroll") for (int k = 0; k < 2; ++k) \
;         acc[ai][bj][m][n] = __builtin_amdgcn_mfma_f32_16x16x32_bf16(Bt[n][k], At[m][k], acc[ai][bj][m][n], 0, 0, 0); __builtin_amdgcn_s_setprio(0); } while (0)
; #define PG8_WAIT_V(n) asm volatile("s_waitcnt vmcnt(" #n ")" ::: "memory")
; #define PG8_WAIT_L(n) asm volatile("s_waitcnt lgkmcnt(" #n ")" ::: "memory")
; #define PG8_BAR __builtin_amdgcn_s_barrier()
; #define PG8_SCHED __builtin_amdgcn_sched_barrier(0)
; template <class Epi, class Sched, bool ALIGN_EPI = false, bool SP2 = false>
; __device__ __forceinline__ void gemm_phase(PG8_LAS unsigned char* lds, const Gemm g, const Sched& S, const Epi& E, const int wid  ) {
;     ...
;             PG8_WAIT_V(8); PG8_WAIT_L(0); PG8_BAR; PG8_MMA(0, 0, At, B0); PG8_MMA(0, 1, At, B1); PG8_BAR; PG8_SCHED;
;             PG8_LDA(At, 0, 1); PG8_STAGE(PG8_SB(0, 0), b2, voffB); PG8_STAGE(PG8_SB(0, 1), b2 + hstep, voffB); PG8_STAGE(PG8_SA(0, 0), a2, voffA);
;             PG8_WAIT_V(8); PG8_WAIT_L(0); PG8_BAR; PG8_MMA(1, 0, At, B0); PG8_MMA(1, 1, At, B1); PG8_BAR; PG8_SCHED;
;             PG8_LDB(B0, 1, 0); PG8_LDB(B1, 1, 1); PG8_SCHED; PG8_LDA(At, 1, 0); PG8_STAGE(PG8_SA(0, 1), a2 + hstep, voffA);
;             PG8_WAIT_V(8); PG8_WAIT_L(0); PG8_BAR; PG8_MMA(0, 0, At, B0); PG8_MMA(0, 1, At, B1); PG8_BAR; PG8_SCHED;
	s_mov_b32 m0, s35
	s_mov_b32 s14, s10
	s_mov_b32 s15, s11
	ds_read_b128 v[178:181], v154 offset:16384
	ds_read_b128 v[182:185], v154 offset:17408
	ds_read_b128 v[186:189], v154 offset:18432
	ds_read_b128 v[190:193], v154 offset:19456
	ds_read_b128 v[194:197], v154 offset:20480
	ds_read_b128 v[198:201], v154 offset:21504
	ds_read_b128 v[202:205], v154 offset:22528
	ds_read_b128 v[206:209], v154 offset:23552
	buffer_load_dwordx4 v147, s[12:15], s77 offen lds
	s_mov_b32 m0, s42
	s_add_i32 s79, s77, 0x80000
	buffer_load_dwordx4 v149, s[12:15], s77 offen lds
	s_mov_b32 m0, s43
	s_nop 0
	buffer_load_dwordx4 v147, s[12:15], s79 offen lds
	s_mov_b32 m0, s44
	s_nop 0
	buffer_load_dwordx4 v149, s[12:15], s79 offen lds
	s_mov_b32 m0, s34
	s_nop 0
	buffer_load_dwordx4 v146, s[8:11], s78 offen lds
	s_mov_b32 m0, s45
	s_nop 0
	buffer_load_dwordx4 v148, s[8:11], s78 offen lds
	s_waitcnt vmcnt(8)
	s_waitcnt lgkmcnt(0)
	s_barrier
	s_waitcnt lgkmcnt(7)
	v_mfma_f32_16x16x32_bf16 v[60:63], v[132:135], v[178:181], v[60:63]
	v_mfma_f32_16x16x32_bf16 v[56:59], v[140:143], v[178:181], v[56:59]
	s_waitcnt lgkmcnt(5)
	v_mfma_f32_16x16x32_bf16 v[44:47], v[132:135], v[186:189], v[44:47]
	v_mfma_f32_16x16x32_bf16 v[40:43], v[140:143], v[186:189], v[40:43]
	s_waitcnt lgkmcnt(3)
	v_mfma_f32_16x16x32_bf16 v[28:31], v[132:135], v[194:197], v[28:31]
	v_mfma_f32_16x16x32_bf16 v[24:27], v[140:143], v[194:197], v[24:27]
	s_waitcnt lgkmcnt(1)
	v_mfma_f32_16x16x32_bf16 v[12:15], v[132:135], v[202:205], v[12:15]
	v_mfma_f32_16x16x32_bf16 v[8:11], v[140:143], v[202:205], v[8:11]
	v_mfma_f32_16x16x32_bf16 v[60:63], v[136:139], v[182:185], v[60:63]
	v_mfma_f32_16x16x32_bf16 v[56:59], v[158:161], v[182:185], v[56:59]
	v_mfma_f32_16x16x32_bf16 v[44:47], v[136:139], v[190:193], v[44:47]
	v_mfma_f32_16x16x32_bf16 v[40:43], v[158:161], v[190:193], v[40:43]
	v_mfma_f32_16x16x32_bf16 v[28:31], v[136:139], v[198:201], v[28:31]
	v_mfma_f32_16x16x32_bf16 v[24:27], v[158:161], v[198:201], v[24:27]
	s_waitcnt lgkmcnt(0)
	v_mfma_f32_16x16x32_bf16 v[12:15], v[136:139], v[206:209], v[12:15]
	v_mfma_f32_16x16x32_bf16 v[8:11], v[158:161], v[206:209], v[8:11]
	v_mfma_f32_16x16x32_bf16 v[52:55], v[162:165], v[178:181], v[52:55]
	v_mfma_f32_16x16x32_bf16 v[48:51], v[170:173], v[178:181], v[48:51]
	v_mfma_f32_16x16x32_bf16 v[36:39], v[162:165], v[186:189], v[36:39]
	v_mfma_f32_16x16x32_bf16 v[32:35], v[170:173], v[186:189], v[32:35]
	v_mfma_f32_16x16x32_bf16 v[20:23], v[162:165], v[194:197], v[20:23]
	v_mfma_f32_16x16x32_bf16 v[16:19], v[170:173], v[194:197], v[16:19]
	v_mfma_f32_16x16x32_bf16 v[4:7], v[162:165], v[202:205], v[4:7]
	v_mfma_f32_16x16x32_bf16 v[0:3], v[170:173], v[202:205], v[0:3]
	v_mfma_f32_16x16x32_bf16 v[52:55], v[166:169], v[182:185], v[52:55]
	v_mfma_f32_16x16x32_bf16 v[48:51], v[174:177], v[182:185], v[48:51]
	v_mfma_f32_16x16x32_bf16 v[36:39], v[166:169], v[190:193], v[36:39]
	v_mfma_f32_16x16x32_bf16 v[32:35], v[174:177], v[190:193], v[32:35]
	v_mfma_f32_16x16x32_bf16 v[20:23], v[166:169], v[198:201], v[20:23]
	v_mfma_f32_16x16x32_bf16 v[16:19], v[174:177], v[198:201], v[16:19]
	v_mfma_f32_16x16x32_bf16 v[4:7], v[166:169], v[206:209], v[4:7]
	v_mfma_f32_16x16x32_bf16 v[0:3], v[174:177], v[206:209], v[0:3]
	s_barrier
	ds_read_b128 v[132:135], v155
	ds_read_b128 v[136:139], v155 offset:1024
	ds_read_b128 v[140:143], v155 offset:2048
	ds_read_b128 v[158:161], v155 offset:3072
	ds_read_b128 v[162:165], v156
	ds_read_b128 v[166:169], v156 offset:1024
	ds_read_b128 v[170:173], v156 offset:2048
	ds_read_b128 v[174:177], v156 offset:3072
	s_add_i32 s78, s78, 0x80000
	s_mov_b32 m0, s46
	ds_read_b128 v[178:181], v154 offset:32768
	ds_read_b128 v[182:185], v154 offset:33792
	ds_read_b128 v[186:189], v154 offset:34816
	ds_read_b128 v[190:193], v154 offset:35840
	ds_read_b128 v[194:197], v154 offset:36864
	ds_read_b128 v[198:201], v154 offset:37888
	ds_read_b128 v[202:205], v154 offset:38912
	ds_read_b128 v[206:209], v154 offset:39936
	buffer_load_dwordx4 v146, s[8:11], s78 offen lds
	s_mov_b32 m0, s48
	s_nop 0
	buffer_load_dwordx4 v148, s[8:11], s78 offen lds
	s_waitcnt vmcnt(8)
	s_waitcnt lgkmcnt(0)
	s_barrier
; #define PG8_STAGE(bufoff, soff, voff) do { _Pragma("unroll") for (int _i = 0; _i < 2; ++_i) \
;         __builtin_amdgcn_raw_ptr_buffer_load_lds(rs_##voff, (PG8_LAS unsigned*)(lds + (bufoff) + ldsw + _i * 8192), 16, (int)(voff)[_i], (int)(soff), 0, 0); } while (0)
; #define PG8_LDA(dst, b, h) do { _Pragma("unroll") for (int m = 0; m < 4; ++m) _Pragma("unroll") for (int k = 0; k < 2; ++k) dst[m][k] = *(const PG8_LAS bf16x8*)(lds + PG8_SA(b, h) + aoff + m * 2048 + k * 1024); } while (0)
; #define PG8_LDB(dst, b, h) do { _Pragma("unroll") for (int n = 0; n < 2; ++n) _Pragma("unroll") for (int k = 0; k < 2; ++k) dst[n][k] = *(const PG8_LAS bf16x8*)(lds + PG8_SB(b, h) + boff + n * 2048 + k * 1024); } while (0)
; template <class Epi, class Sched, bool ALIGN_EPI = false, bool SP2 = false>
; __device__ __forceinline__ void gemm_phase(PG8_LAS unsigned char* lds, const Gemm g, const Sched& S, const Epi& E, const int wid  ) {
;     ...
;         for (int t = 0; t < nt; t += 2) {
;             const bool last = (t == nt - 2);
;             const unsigned a1 = cA + (unsigned)(t + 1) * kstep;
;             const unsigned a2 = last ? nA : cA + (unsigned)(t + 2) * kstep, b2 = last ? nB : cB + (unsigned)(t + 2) * kstep;
;             const unsigned a3 = a2 + kstep, b3 = b2 + kstep;
;             if (last && has_next) S.a_ready(nxt);
;             if constexpr (SP2) {
;             PG8_LDB(B0, 0, 0); PG8_LDB(B1, 0, 1); PG8_SCHED; PG8_LDA(At, 0, 0); PG8_STAGE(PG8_SA(1, 1), a1 + hstep, voffA);
;             PG8_WAIT_V(8); PG8_WAIT_L(0); PG8_BAR; PG8_MMA(0, 0, At, B0); PG8_MMA(0, 1, At, B1); PG8_BAR; PG8_SCHED;
;             PG8_LDA(At, 0, 1); PG8_STAGE(PG8_SB(0, 0), b2, voffB); PG8_STAGE(PG8_SB(0, 1), b2 + hstep, voffB); PG8_STAGE(PG8_SA(0, 0), a2, voffA);
;             PG8_WAIT_V(8); PG8_WAIT_L(0); PG8_BAR; PG8_MMA(1, 0, At, B0); PG8_MMA(1, 1, At, B1); PG8_BAR; PG8_SCHED;
;             PG8_LDB(B0, 1, 0); PG8_LDB(B1, 1, 1); PG8_SCHED; PG8_LDA(At, 1, 0); PG8_STAGE(PG8_SA(0, 1), a2 + hstep, voffA);
;             PG8_WAIT_V(8); PG8_WAIT_L(0); PG8_BAR; PG8_MMA(0, 0, At, B0); PG8_MMA(0, 1, At, B1); PG8_BAR; PG8_SCHED;
;             PG8_LDA(At, 1, 1); PG8_STAGE(PG8_SB(1, 0), b3, voffB); PG8_STAGE(PG8_SB(1, 1), b3 + hstep, voffB); PG8_STAGE(PG8_SA(1, 0), a3, voffA);
;             PG8_WAIT_V(8); PG8_WAIT_L(0); PG8_BAR; PG8_MMA(1, 0, At, B0); PG8_MMA(1, 1, At, B1); PG8_BAR; PG8_SCHED;
	s_waitcnt lgkmcnt(7)
	v_mfma_f32_16x16x32_bf16 v[124:127], v[132:135], v[178:181], v[124:127]
	v_mfma_f32_16x16x32_bf16 v[120:123], v[140:143], v[178:181], v[120:123]
	s_waitcnt lgkmcnt(5)
	v_mfma_f32_16x16x32_bf16 v[108:111], v[132:135], v[186:189], v[108:111]
	v_mfma_f32_16x16x32_bf16 v[104:107], v[140:143], v[186:189], v[104:107]
	s_waitcnt lgkmcnt(3)
	v_mfma_f32_16x16x32_bf16 v[92:95], v[132:135], v[194:197], v[92:95]
	v_mfma_f32_16x16x32_bf16 v[88:91], v[140:143], v[194:197], v[88:91]
	s_waitcnt lgkmcnt(1)
	v_mfma_f32_16x16x32_bf16 v[76:79], v[132:135], v[202:205], v[76:79]
	v_mfma_f32_16x16x32_bf16 v[72:75], v[140:143], v[202:205], v[72:75]
	v_mfma_f32_16x16x32_bf16 v[124:127], v[136:139], v[182:185], v[124:127]
	v_mfma_f32_16x16x32_bf16 v[120:123], v[158:161], v[182:185], v[120:123]
	v_mfma_f32_16x16x32_bf16 v[108:111], v[136:139], v[190:193], v[108:111]
	v_mfma_f32_16x16x32_bf16 v[104:107], v[158:161], v[190:193], v[104:107]
	v_mfma_f32_16x16x32_bf16 v[92:95], v[136:139], v[198:201], v[92:95]
	v_mfma_f32_16x16x32_bf16 v[88:91], v[158:161], v[198:201], v[88:91]
	s_waitcnt lgkmcnt(0)
	v_mfma_f32_16x16x32_bf16 v[76:79], v[136:139], v[206:209], v[76:79]
	v_mfma_f32_16x16x32_bf16 v[72:75], v[158:161], v[206:209], v[72:75]
	v_mfma_f32_16x16x32_bf16 v[116:119], v[162:165], v[178:181], v[116:119]
	v_mfma_f32_16x16x32_bf16 v[112:115], v[170:173], v[178:181], v[112:115]
	v_mfma_f32_16x16x32_bf16 v[100:103], v[162:165], v[186:189], v[100:103]
	v_mfma_f32_16x16x32_bf16 v[96:99], v[170:173], v[186:189], v[96:99]
	v_mfma_f32_16x16x32_bf16 v[84:87], v[162:165], v[194:197], v[84:87]
	v_mfma_f32_16x16x32_bf16 v[80:83], v[170:173], v[194:197], v[80:83]
	v_mfma_f32_16x16x32_bf16 v[68:71], v[162:165], v[202:205], v[68:71]
	v_mfma_f32_16x16x32_bf16 v[64:67], v[170:173], v[202:205], v[64:67]
	v_mfma_f32_16x16x32_bf16 v[116:119], v[166:169], v[182:185], v[116:119]
	v_mfma_f32_16x16x32_bf16 v[112:115], v[174:177], v[182:185], v[112:115]
	v_mfma_f32_16x16x32_bf16 v[100:103], v[166:169], v[190:193], v[100:103]
	v_mfma_f32_16x16x32_bf16 v[96:99], v[174:177], v[190:193], v[96:99]
	v_mfma_f32_16x16x32_bf16 v[84:87], v[166:169], v[198:201], v[84:87]
	v_mfma_f32_16x16x32_bf16 v[80:83], v[174:177], v[198:201], v[80:83]
	v_mfma_f32_16x16x32_bf16 v[68:71], v[166:169], v[206:209], v[68:71]
	v_mfma_f32_16x16x32_bf16 v[64:67], v[174:177], v[206:209], v[64:67]
	s_barrier
	s_mov_b32 m0, s50
	s_or_b32 s78, s77, 0x80
	ds_read_b128 v[178:181], v154 offset:49152
	ds_read_b128 v[182:185], v154 offset:50176
	ds_read_b128 v[186:189], v154 offset:51200
	ds_read_b128 v[190:193], v154 offset:52224
	ds_read_b128 v[194:197], v154 offset:53248
	ds_read_b128 v[198:201], v154 offset:54272
	ds_read_b128 v[202:205], v154 offset:55296
	ds_read_b128 v[206:209], v154 offset:56320
	buffer_load_dwordx4 v147, s[12:15], s78 offen lds
	s_mov_b32 m0, s51
	s_add_i32 s77, s77, 0x80080
	buffer_load_dwordx4 v149, s[12:15], s78 offen lds
	s_mov_b32 m0, s55
	s_nop 0
	buffer_load_dwordx4 v147, s[12:15], s77 offen lds
	s_mov_b32 m0, s58
	s_nop 0
	buffer_load_dwordx4 v149, s[12:15], s77 offen lds
	s_mov_b32 m0, s53
	s_nop 0
	buffer_load_dwordx4 v146, s[8:11], s76 offen lds
	s_mov_b32 m0, s54
	s_nop 0
	buffer_load_dwordx4 v148, s[8:11], s76 offen lds
	s_waitcnt vmcnt(8)
	s_waitcnt lgkmcnt(0)
	s_barrier
	s_waitcnt lgkmcnt(7)
	v_mfma_f32_16x16x32_bf16 v[60:63], v[132:135], v[178:181], v[60:63]
	v_mfma_f32_16x16x32_bf16 v[56:59], v[140:143], v[178:181], v[56:59]
	s_waitcnt lgkmcnt(5)
	v_mfma_f32_16x16x32_bf16 v[44:47], v[132:135], v[186:189], v[44:47]
	v_mfma_f32_16x16x32_bf16 v[40:43], v[140:143], v[186:189], v[40:43]
	s_waitcnt lgkmcnt(3)
	v_mfma_f32_16x16x32_bf16 v[28:31], v[132:135], v[194:197], v[28:31]
	v_mfma_f32_16x16x32_bf16 v[24:27], v[140:143], v[194:197], v[24:27]
	s_waitcnt lgkmcnt(1)
	v_mfma_f32_16x16x32_bf16 v[12:15], v[132:135], v[202:205], v[12:15]
	v_mfma_f32_16x16x32_bf16 v[8:11], v[140:143], v[202:205], v[8:11]
	v_mfma_f32_16x16x32_bf16 v[60:63], v[136:139], v[182:185], v[60:63]
	v_mfma_f32_16x16x32_bf16 v[56:59], v[158:161], v[182:185], v[56:59]
	v_mfma_f32_16x16x32_bf16 v[44:47], v[136:139], v[190:193], v[44:47]
	v_mfma_f32_16x16x32_bf16 v[40:43], v[158:161], v[190:193], v[40:43]
	v_mfma_f32_16x16x32_bf16 v[28:31], v[136:139], v[198:201], v[28:31]
	v_mfma_f32_16x16x32_bf16 v[24:27], v[158:161], v[198:201], v[24:27]
	s_waitcnt lgkmcnt(0)
	v_mfma_f32_16x16x32_bf16 v[12:15], v[136:139], v[206:209], v[12:15]
	v_mfma_f32_16x16x32_bf16 v[8:11], v[158:161], v[206:209], v[8:11]
	v_mfma_f32_16x16x32_bf16 v[52:55], v[162:165], v[178:181], v[52:55]
	v_mfma_f32_16x16x32_bf16 v[48:51], v[170:173], v[178:181], v[48:51]
	v_mfma_f32_16x16x32_bf16 v[36:39], v[162:165], v[186:189], v[36:39]
	v_mfma_f32_16x16x32_bf16 v[32:35], v[170:173], v[186:189], v[32:35]
	v_mfma_f32_16x16x32_bf16 v[20:23], v[162:165], v[194:197], v[20:23]
	v_mfma_f32_16x16x32_bf16 v[16:19], v[170:173], v[194:197], v[16:19]
	v_mfma_f32_16x16x32_bf16 v[4:7], v[162:165], v[202:205], v[4:7]
	v_mfma_f32_16x16x32_bf16 v[0:3], v[170:173], v[202:205], v[0:3]
	v_mfma_f32_16x16x32_bf16 v[52:55], v[166:169], v[182:185], v[52:55]
	v_mfma_f32_16x16x32_bf16 v[48:51], v[174:177], v[182:185], v[48:51]
	v_mfma_f32_16x16x32_bf16 v[36:39], v[166:169], v[190:193], v[36:39]
	v_mfma_f32_16x16x32_bf16 v[32:35], v[174:177], v[190:193], v[32:35]
	v_mfma_f32_16x16x32_bf16 v[20:23], v[166:169], v[198:201], v[20:23]
	v_mfma_f32_16x16x32_bf16 v[16:19], v[174:177], v[198:201], v[16:19]
	v_mfma_f32_16x16x32_bf16 v[4:7], v[166:169], v[206:209], v[4:7]
	v_mfma_f32_16x16x32_bf16 v[0:3], v[174:177], v[206:209], v[0:3]
	s_barrier
	s_add_i32 s75, s75, 2
	s_addk_i32 s41, 0x100
	s_addk_i32 s74, 0x100
	s_cmp_gt_u32 s75, 29
	s_cbranch_scc0 .LBB0_903
	s_setprio 0
	s_and_b64 vcc, exec, s[26:27]
	s_cbranch_vccz .LBB0_906
	s_barrier

; #define PG8_STAGE(bufoff, soff, voff) do { _Pragma("unroll") for (int _i = 0; _i < 2; ++_i) \
;         __builtin_amdgcn_raw_ptr_buffer_load_lds(rs_##voff, (PG8_LAS unsigned*)(lds + (bufoff) + ldsw + _i * 8192), 16, (int)(voff)[_i], (int)(soff), 0, 0); } while (0)
; #define PG8_LDA(dst, b, h) do { _Pragma("unroll") for (int m = 0; m < 4; ++m) _Pragma("unroll") for (int k = 0; k < 2; ++k) dst[m][k] = *(const PG8_LAS bf16x8*)(lds + PG8_SA(b, h) + aoff + m * 2048 + k * 1024); } while (0)
; #define PG8_LDB(dst, b, h) do { _Pragma("unroll") for (int n = 0; n < 2; ++n) _Pragma("unroll") for (int k = 0; k < 2; ++k) dst[n][k] = *(const PG8_LAS bf16x8*)(lds + PG8_SB(b, h) + boff + n * 2048 + k * 1024); } while (0)
; #define PG8_MMA(ai, bj, At, Bt) do { __builtin_amdgcn_s_setprio(1); _Pragma("unroll") for (int m = 0; m < 4; ++m) _Pragma("unroll") for (int n = 0; n < 2; ++n) _Pragma("unroll") for (int k = 0; k < 2; ++k) \
;         acc[ai][bj][m][n] = __builtin_amdgcn_mfma_f32_16x16x32_bf16(Bt[n][k], At[m][k], acc[ai][bj][m][n], 0, 0, 0); __builtin_amdgcn_s_setprio(0); } while (0)
; #define PG8_WAIT_V(n) asm volatile("s_waitcnt vmcnt(" #n ")" ::: "memory")
; #define PG8_WAIT_L(n) asm volatile("s_waitcnt lgkmcnt(" #n ")" ::: "memory")
; #define PG8_BAR __builtin_amdgcn_s_barrier()
; #define PG8_SCHED __builtin_amdgcn_sched_barrier(0)
; template <class Epi, class Sched, bool ALIGN_EPI = false, bool SP2 = false>
; __device__ __forceinline__ void gemm_phase(PG8_LAS unsigned char* lds, const Gemm g, const Sched& S, const Epi& E, const int wid  ) {
;     ...
;             PG8_LDB(B0, 0, 0); PG8_LDB(B1, 0, 1); PG8_SCHED; PG8_LDA(At, 0, 0); PG8_STAGE(PG8_SA(1, 1), a1 + hstep, voffA);
;             PG8_WAIT_V(8); PG8_WAIT_L(0); PG8_BAR; PG8_MMA(0, 0, At, B0); PG8_MMA(0, 1, At, B1); PG8_BAR; PG8_SCHED;
;     ...
; #pragma unroll
;         for (int a = 0; a < 2; ++a)
; #pragma unroll
;             for (int b = 0; b < 2; ++b)
; #pragma unroll
;                 for (int m = 0; m < 4; ++m)
; #pragma unroll
;                     for (int n = 0; n < 2; ++n) acc[a][b][m][n] = (f32x4){0.f, 0.f, 0.f, 0.f};
;         cur = nxt; cA = nA; cB = nB; ++ui;
.LBB0_1075:
	s_lshl_b32 s58, s51, 20
	s_and_b64 s[0:1], s[0:1], exec
	v_mov_b32_e32 v0, 0
	s_cselect_b32 s0, s58, s16
	s_add_i32 s1, s20, 0x80080
	s_addk_i32 s16, 0x100
	s_mov_b32 s20, -2
	v_mov_b32_e32 v1, v0
	v_mov_b32_e32 v2, v0
	v_mov_b32_e32 v3, v0
	v_mov_b32_e32 v4, v0
	v_mov_b32_e32 v5, v0
	v_mov_b32_e32 v6, v0
	v_mov_b32_e32 v7, v0
	v_mov_b32_e32 v16, v0
	v_mov_b32_e32 v17, v0
	v_mov_b32_e32 v18, v0
	v_mov_b32_e32 v19, v0
	v_mov_b32_e32 v20, v0
	v_mov_b32_e32 v21, v0
	v_mov_b32_e32 v22, v0
	v_mov_b32_e32 v23, v0
	v_mov_b32_e32 v32, v0
	v_mov_b32_e32 v33, v0
	v_mov_b32_e32 v34, v0
	v_mov_b32_e32 v35, v0
	v_mov_b32_e32 v36, v0
	v_mov_b32_e32 v37, v0
	v_mov_b32_e32 v38, v0
	v_mov_b32_e32 v39, v0
	v_mov_b32_e32 v48, v0
	v_mov_b32_e32 v49, v0
	v_mov_b32_e32 v50, v0
	v_mov_b32_e32 v51, v0
	v_mov_b32_e32 v52, v0
	v_mov_b32_e32 v53, v0
	v_mov_b32_e32 v54, v0
	v_mov_b32_e32 v55, v0
	v_mov_b32_e32 v8, v0
	v_mov_b32_e32 v9, v0
	v_mov_b32_e32 v10, v0
	v_mov_b32_e32 v11, v0
	v_mov_b32_e32 v12, v0
	v_mov_b32_e32 v13, v0
	v_mov_b32_e32 v14, v0
	v_mov_b32_e32 v15, v0
	v_mov_b32_e32 v24, v0
	v_mov_b32_e32 v25, v0
	v_mov_b32_e32 v26, v0
	v_mov_b32_e32 v27, v0
	v_mov_b32_e32 v28, v0
	v_mov_b32_e32 v29, v0
	v_mov_b32_e32 v30, v0
	v_mov_b32_e32 v31, v0
	v_mov_b32_e32 v40, v0
	v_mov_b32_e32 v41, v0
	v_mov_b32_e32 v42, v0
	v_mov_b32_e32 v43, v0
	v_mov_b32_e32 v44, v0
	v_mov_b32_e32 v45, v0
	v_mov_b32_e32 v46, v0
	v_mov_b32_e32 v47, v0
	v_mov_b32_e32 v56, v0
	v_mov_b32_e32 v57, v0
	v_mov_b32_e32 v58, v0
	v_mov_b32_e32 v59, v0
	v_mov_b32_e32 v60, v0
	v_mov_b32_e32 v61, v0
	v_mov_b32_e32 v62, v0
	v_mov_b32_e32 v63, v0
	v_mov_b32_e32 v64, v0
	v_mov_b32_e32 v65, v0
	v_mov_b32_e32 v66, v0
	v_mov_b32_e32 v67, v0
	v_mov_b32_e32 v68, v0
	v_mov_b32_e32 v69, v0
	v_mov_b32_e32 v70, v0
	v_mov_b32_e32 v71, v0
	v_mov_b32_e32 v80, v0
	v_mov_b32_e32 v81, v0
	v_mov_b32_e32 v82, v0
	v_mov_b32_e32 v83, v0
	v_mov_b32_e32 v84, v0
	v_mov_b32_e32 v85, v0
	v_mov_b32_e32 v86, v0
	v_mov_b32_e32 v87, v0
	v_mov_b32_e32 v96, v0
	v_mov_b32_e32 v97, v0
	v_mov_b32_e32 v98, v0
	v_mov_b32_e32 v99, v0
	v_mov_b32_e32 v100, v0
	v_mov_b32_e32 v101, v0
	v_mov_b32_e32 v102, v0
	v_mov_b32_e32 v103, v0
	v_mov_b32_e32 v112, v0
	v_mov_b32_e32 v113, v0
	v_mov_b32_e32 v114, v0
	v_mov_b32_e32 v115, v0
	v_mov_b32_e32 v116, v0
	v_mov_b32_e32 v117, v0
	v_mov_b32_e32 v118, v0
	v_mov_b32_e32 v119, v0
	v_mov_b32_e32 v72, v0
	v_mov_b32_e32 v73, v0
	v_mov_b32_e32 v74, v0
	v_mov_b32_e32 v75, v0
	v_mov_b32_e32 v76, v0
	v_mov_b32_e32 v77, v0
	v_mov_b32_e32 v78, v0
	v_mov_b32_e32 v79, v0
	v_mov_b32_e32 v88, v0
	v_mov_b32_e32 v89, v0
	v_mov_b32_e32 v90, v0
	v_mov_b32_e32 v91, v0
	v_mov_b32_e32 v92, v0
	v_mov_b32_e32 v93, v0
	v_mov_b32_e32 v94, v0
	v_mov_b32_e32 v95, v0
	v_mov_b32_e32 v104, v0
	v_mov_b32_e32 v105, v0
	v_mov_b32_e32 v106, v0
	v_mov_b32_e32 v107, v0
	v_mov_b32_e32 v108, v0
	v_mov_b32_e32 v109, v0
	v_mov_b32_e32 v110, v0
	v_mov_b32_e32 v111, v0
	v_mov_b32_e32 v120, v0
	v_mov_b32_e32 v121, v0
	v_mov_b32_e32 v122, v0
	v_mov_b32_e32 v123, v0
	v_mov_b32_e32 v124, v0
	v_mov_b32_e32 v125, v0
	v_mov_b32_e32 v126, v0
	v_mov_b32_e32 v127, v0
	v_readlane_b32 vcc_lo, v246, 6
	s_nop 1
	s_cmp_ge_u32 vcc_lo, 4
	s_cbranch_scc0 .Lprio_1076
	s_setprio 1
.Lprio_1076:
.LBB0_1076:
	ds_read_b128 v[142:145], v136
	ds_read_b128 v[146:149], v136 offset:1024
	ds_read_b128 v[150:153], v136 offset:2048
	ds_read_b128 v[154:157], v136 offset:3072
	ds_read_b128 v[158:161], v137
	ds_read_b128 v[162:165], v137 offset:1024
	ds_read_b128 v[166:169], v137 offset:2048
	ds_read_b128 v[170:173], v137 offset:3072
	s_add_i32 s14, s1, 0xfff80080
	s_cmp_eq_u32 s20, 28
	s_cselect_b32 s54, s55, s14
	s_cselect_b32 s35, s0, s16
	s_add_i32 s21, s54, 0x80
	s_mov_b32 m0, s45
	ds_read_b128 v[174:177], v138
	ds_read_b128 v[178:181], v138 offset:1024
	ds_read_b128 v[182:185], v138 offset:2048
	ds_read_b128 v[186:189], v138 offset:3072
	ds_read_b128 v[190:193], v138 offset:4096
	ds_read_b128 v[194:197], v138 offset:5120
	ds_read_b128 v[198:201], v138 offset:6144
	ds_read_b128 v[202:205], v138 offset:7168
	buffer_load_dwordx4 v132, s[8:11], s1 offen lds
	s_mov_b32 m0, s46
	s_nop 0
	buffer_load_dwordx4 v134, s[8:11], s1 offen lds
	s_waitcnt vmcnt(8)
	s_waitcnt lgkmcnt(0)
	s_barrier
	s_waitcnt lgkmcnt(7)
	v_mfma_f32_16x16x32_bf16 v[124:127], v[142:145], v[174:177], v[124:127]
	v_mfma_f32_16x16x32_bf16 v[120:123], v[150:153], v[174:177], v[120:123]
	s_waitcnt lgkmcnt(5)
	v_mfma_f32_16x16x32_bf16 v[108:111], v[142:145], v[182:185], v[108:111]
	v_mfma_f32_16x16x32_bf16 v[104:107], v[150:153], v[182:185], v[104:107]
	s_waitcnt lgkmcnt(3)
	v_mfma_f32_16x16x32_bf16 v[92:95], v[142:145], v[190:193], v[92:95]
	v_mfma_f32_16x16x32_bf16 v[88:91], v[150:153], v[190:193], v[88:91]
	s_waitcnt lgkmcnt(1)
	v_mfma_f32_16x16x32_bf16 v[76:79], v[142:145], v[198:201], v[76:79]
	v_mfma_f32_16x16x32_bf16 v[72:75], v[150:153], v[198:201], v[72:75]
	v_mfma_f32_16x16x32_bf16 v[124:127], v[146:149], v[178:181], v[124:127]
	v_mfma_f32_16x16x32_bf16 v[120:123], v[154:157], v[178:181], v[120:123]
	v_mfma_f32_16x16x32_bf16 v[108:111], v[146:149], v[186:189], v[108:111]
	v_mfma_f32_16x16x32_bf16 v[104:107], v[154:157], v[186:189], v[104:107]
	v_mfma_f32_16x16x32_bf16 v[92:95], v[146:149], v[194:197], v[92:95]
	v_mfma_f32_16x16x32_bf16 v[88:91], v[154:157], v[194:197], v[88:91]
	s_waitcnt lgkmcnt(0)
	v_mfma_f32_16x16x32_bf16 v[76:79], v[146:149], v[202:205], v[76:79]
	v_mfma_f32_16x16x32_bf16 v[72:75], v[154:157], v[202:205], v[72:75]
	v_mfma_f32_16x16x32_bf16 v[116:119], v[158:161], v[174:177], v[116:119]
	v_mfma_f32_16x16x32_bf16 v[112:115], v[166:169], v[174:177], v[112:115]
	v_mfma_f32_16x16x32_bf16 v[100:103], v[158:161], v[182:185], v[100:103]
	v_mfma_f32_16x16x32_bf16 v[96:99], v[166:169], v[182:185], v[96:99]
	v_mfma_f32_16x16x32_bf16 v[84:87], v[158:161], v[190:193], v[84:87]
	v_mfma_f32_16x16x32_bf16 v[80:83], v[166:169], v[190:193], v[80:83]
	v_mfma_f32_16x16x32_bf16 v[68:71], v[158:161], v[198:201], v[68:71]
	v_mfma_f32_16x16x32_bf16 v[64:67], v[166:169], v[198:201], v[64:67]
	v_mfma_f32_16x16x32_bf16 v[116:119], v[162:165], v[178:181], v[116:119]
	v_mfma_f32_16x16x32_bf16 v[112:115], v[170:173], v[178:181], v[112:115]
	v_mfma_f32_16x16x32_bf16 v[100:103], v[162:165], v[186:189], v[100:103]
	v_mfma_f32_16x16x32_bf16 v[96:99], v[170:173], v[186:189], v[96:99]
	v_mfma_f32_16x16x32_bf16 v[84:87], v[162:165], v[194:197], v[84:87]
	v_mfma_f32_16x16x32_bf16 v[80:83], v[170:173], v[194:197], v[80:83]
	v_mfma_f32_16x16x32_bf16 v[68:71], v[162:165], v[202:205], v[68:71]
	v_mfma_f32_16x16x32_bf16 v[64:67], v[170:173], v[202:205], v[64:67]
	s_barrier
; #define PG8_STAGE(bufoff, soff, voff) do { _Pragma("unroll") for (int _i = 0; _i < 2; ++_i) \
;         __builtin_amdgcn_raw_ptr_buffer_load_lds(rs_##voff, (PG8_LAS unsigned*)(lds + (bufoff) + ldsw + _i * 8192), 16, (int)(voff)[_i], (int)(soff), 0, 0); } while (0)
; #define PG8_LDA(dst, b, h) do { _Pragma("unroll") for (int m = 0; m < 4; ++m) _Pragma("unroll") for (int k = 0; k < 2; ++k) dst[m][k] = *(const PG8_LAS bf16x8*)(lds + PG8_SA(b, h) + aoff + m * 2048 + k * 1024); } while (0)
; #define PG8_LDB(dst, b, h) do { _Pragma("unroll") for (int n = 0; n < 2; ++n) _Pragma("unroll") for (int k = 0; k < 2; ++k) dst[n][k] = *(const PG8_LAS bf16x8*)(lds + PG8_SB(b, h) + boff + n * 2048 + k * 1024); } while (0)
; #define PG8_MMA(ai, bj, At, Bt) do { __builtin_amdgcn_s_setprio(1); _Pragma("unroll") for (int m = 0; m < 4; ++m) _Pragma("unroll") for (int n = 0; n < 2; ++n) _Pragma("unroll") for (int k = 0; k < 2; ++k) \
;         acc[ai][bj][m][n] = __builtin_amdgcn_mfma_f32_16x16x32_bf16(Bt[n][k], At[m][k], acc[ai][bj][m][n], 0, 0, 0); __builtin_amdgcn_s_setprio(0); } while (0)
; #define PG8_WAIT_V(n) asm volatile("s_waitcnt vmcnt(" #n ")" ::: "memory")
; #define PG8_WAIT_L(n) asm volatile("s_waitcnt lgkmcnt(" #n ")" ::: "memory")
; #define PG8_BAR __builtin_amdgcn_s_barrier()
; #define PG8_SCHED __builtin_amdgcn_sched_barrier(0)
; template <class Epi, class Sched, bool ALIGN_EPI = false, bool SP2 = false>
; __device__ __forceinline__ void gemm_phase(PG8_LAS unsigned char* lds, const Gemm g, const Sched& S, const Epi& E, const int wid  ) {
;     ...
;             PG8_WAIT_V(8); PG8_WAIT_L(0); PG8_BAR; PG8_MMA(0, 0, At, B0); PG8_MMA(0, 1, At, B1); PG8_BAR; PG8_SCHED;
;             PG8_LDA(At, 0, 1); PG8_STAGE(PG8_SB(0, 0), b2, voffB); PG8_STAGE(PG8_SB(0, 1), b2 + hstep, voffB); PG8_STAGE(PG8_SA(0, 0), a2, voffA);
;             PG8_WAIT_V(8); PG8_WAIT_L(0); PG8_BAR; PG8_MMA(1, 0, At, B0); PG8_MMA(1, 1, At, B1); PG8_BAR; PG8_SCHED;
;             PG8_LDB(B0, 1, 0); PG8_LDB(B1, 1, 1); PG8_SCHED; PG8_LDA(At, 1, 0); PG8_STAGE(PG8_SA(0, 1), a2 + hstep, voffA);
;             PG8_WAIT_V(8); PG8_WAIT_L(0); PG8_BAR; PG8_MMA(0, 0, At, B0); PG8_MMA(0, 1, At, B1); PG8_BAR; PG8_SCHED;
	s_mov_b32 m0, s22
	s_mov_b32 s14, s10
	s_mov_b32 s15, s11
	ds_read_b128 v[174:177], v138 offset:16384
	ds_read_b128 v[178:181], v138 offset:17408
	ds_read_b128 v[182:185], v138 offset:18432
	ds_read_b128 v[186:189], v138 offset:19456
	ds_read_b128 v[190:193], v138 offset:20480
	ds_read_b128 v[194:197], v138 offset:21504
	ds_read_b128 v[198:201], v138 offset:22528
	ds_read_b128 v[202:205], v138 offset:23552
	buffer_load_dwordx4 v133, s[12:15], s35 offen lds
	s_mov_b32 m0, s23
	s_add_i32 s59, s35, 0x80000
	buffer_load_dwordx4 v135, s[12:15], s35 offen lds
	s_mov_b32 m0, s24
	s_nop 0
	buffer_load_dwordx4 v133, s[12:15], s59 offen lds
	s_mov_b32 m0, s25
	s_nop 0
	buffer_load_dwordx4 v135, s[12:15], s59 offen lds
	s_mov_b32 m0, s3
	s_nop 0
	buffer_load_dwordx4 v132, s[8:11], s54 offen lds
	s_mov_b32 m0, s26
	s_nop 0
	buffer_load_dwordx4 v134, s[8:11], s54 offen lds
	s_waitcnt vmcnt(8)
	s_waitcnt lgkmcnt(0)
	s_barrier
	s_waitcnt lgkmcnt(7)
	v_mfma_f32_16x16x32_bf16 v[60:63], v[142:145], v[174:177], v[60:63]
	v_mfma_f32_16x16x32_bf16 v[56:59], v[150:153], v[174:177], v[56:59]
	s_waitcnt lgkmcnt(5)
	v_mfma_f32_16x16x32_bf16 v[44:47], v[142:145], v[182:185], v[44:47]
	v_mfma_f32_16x16x32_bf16 v[40:43], v[150:153], v[182:185], v[40:43]
	s_waitcnt lgkmcnt(3)
	v_mfma_f32_16x16x32_bf16 v[28:31], v[142:145], v[190:193], v[28:31]
	v_mfma_f32_16x16x32_bf16 v[24:27], v[150:153], v[190:193], v[24:27]
	s_waitcnt lgkmcnt(1)
	v_mfma_f32_16x16x32_bf16 v[12:15], v[142:145], v[198:201], v[12:15]
	v_mfma_f32_16x16x32_bf16 v[8:11], v[150:153], v[198:201], v[8:11]
	v_mfma_f32_16x16x32_bf16 v[60:63], v[146:149], v[178:181], v[60:63]
	v_mfma_f32_16x16x32_bf16 v[56:59], v[154:157], v[178:181], v[56:59]
	v_mfma_f32_16x16x32_bf16 v[44:47], v[146:149], v[186:189], v[44:47]
	v_mfma_f32_16x16x32_bf16 v[40:43], v[154:157], v[186:189], v[40:43]
	v_mfma_f32_16x16x32_bf16 v[28:31], v[146:149], v[194:197], v[28:31]
	v_mfma_f32_16x16x32_bf16 v[24:27], v[154:157], v[194:197], v[24:27]
	s_waitcnt lgkmcnt(0)
	v_mfma_f32_16x16x32_bf16 v[12:15], v[146:149], v[202:205], v[12:15]
	v_mfma_f32_16x16x32_bf16 v[8:11], v[154:157], v[202:205], v[8:11]
	v_mfma_f32_16x16x32_bf16 v[52:55], v[158:161], v[174:177], v[52:55]
	v_mfma_f32_16x16x32_bf16 v[48:51], v[166:169], v[174:177], v[48:51]
	v_mfma_f32_16x16x32_bf16 v[36:39], v[158:161], v[182:185], v[36:39]
	v_mfma_f32_16x16x32_bf16 v[32:35], v[166:169], v[182:185], v[32:35]
	v_mfma_f32_16x16x32_bf16 v[20:23], v[158:161], v[190:193], v[20:23]
	v_mfma_f32_16x16x32_bf16 v[16:19], v[166:169], v[190:193], v[16:19]
	v_mfma_f32_16x16x32_bf16 v[4:7], v[158:161], v[198:201], v[4:7]
	v_mfma_f32_16x16x32_bf16 v[0:3], v[166:169], v[198:201], v[0:3]
	v_mfma_f32_16x16x32_bf16 v[52:55], v[162:165], v[178:181], v[52:55]
	v_mfma_f32_16x16x32_bf16 v[48:51], v[170:173], v[178:181], v[48:51]
	v_mfma_f32_16x16x32_bf16 v[36:39], v[162:165], v[186:189], v[36:39]
	v_mfma_f32_16x16x32_bf16 v[32:35], v[170:173], v[186:189], v[32:35]
	v_mfma_f32_16x16x32_bf16 v[20:23], v[162:165], v[194:197], v[20:23]
	v_mfma_f32_16x16x32_bf16 v[16:19], v[170:173], v[194:197], v[16:19]
	v_mfma_f32_16x16x32_bf16 v[4:7], v[162:165], v[202:205], v[4:7]
	v_mfma_f32_16x16x32_bf16 v[0:3], v[170:173], v[202:205], v[0:3]
	s_barrier
	ds_read_b128 v[142:145], v139
	ds_read_b128 v[146:149], v139 offset:1024
	ds_read_b128 v[150:153], v139 offset:2048
	ds_read_b128 v[154:157], v139 offset:3072
	ds_read_b128 v[158:161], v140
	ds_read_b128 v[162:165], v140 offset:1024
	ds_read_b128 v[166:169], v140 offset:2048
	ds_read_b128 v[170:173], v140 offset:3072
	s_add_i32 s54, s54, 0x80000
	s_mov_b32 m0, s27
	ds_read_b128 v[174:177], v138 offset:32768
	ds_read_b128 v[178:181], v138 offset:33792
	ds_read_b128 v[182:185], v138 offset:34816
	ds_read_b128 v[186:189], v138 offset:35840
	ds_read_b128 v[190:193], v138 offset:36864
	ds_read_b128 v[194:197], v138 offset:37888
	ds_read_b128 v[198:201], v138 offset:38912
	ds_read_b128 v[202:205], v138 offset:39936
	buffer_load_dwordx4 v132, s[8:11], s54 offen lds
	s_mov_b32 m0, s28
	s_nop 0
	buffer_load_dwordx4 v134, s[8:11], s54 offen lds
	s_waitcnt vmcnt(8)
	s_waitcnt lgkmcnt(0)
	s_barrier
; #define PG8_STAGE(bufoff, soff, voff) do { _Pragma("unroll") for (int _i = 0; _i < 2; ++_i) \
;         __builtin_amdgcn_raw_ptr_buffer_load_lds(rs_##voff, (PG8_LAS unsigned*)(lds + (bufoff) + ldsw + _i * 8192), 16, (int)(voff)[_i], (int)(soff), 0, 0); } while (0)
; #define PG8_LDA(dst, b, h) do { _Pragma("unroll") for (int m = 0; m < 4; ++m) _Pragma("unroll") for (int k = 0; k < 2; ++k) dst[m][k] = *(const PG8_LAS bf16x8*)(lds + PG8_SA(b, h) + aoff + m * 2048 + k * 1024); } while (0)
; #define PG8_LDB(dst, b, h) do { _Pragma("unroll") for (int n = 0; n < 2; ++n) _Pragma("unroll") for (int k = 0; k < 2; ++k) dst[n][k] = *(const PG8_LAS bf16x8*)(lds + PG8_SB(b, h) + boff + n * 2048 + k * 1024); } while (0)
; template <class Epi, class Sched, bool ALIGN_EPI = false, bool SP2 = false>
; __device__ __forceinline__ void gemm_phase(PG8_LAS unsigned char* lds, const Gemm g, const Sched& S, const Epi& E, const int wid  ) {
;     ...
;         for (int t = 0; t < nt; t += 2) {
;             const bool last = (t == nt - 2);
;             const unsigned a1 = cA + (unsigned)(t + 1) * kstep;
;             const unsigned a2 = last ? nA : cA + (unsigned)(t + 2) * kstep, b2 = last ? nB : cB + (unsigned)(t + 2) * kstep;
;             const unsigned a3 = a2 + kstep, b3 = b2 + kstep;
;             if (last && has_next) S.a_ready(nxt);
;             if constexpr (SP2) {
;             PG8_LDB(B0, 0, 0); PG8_LDB(B1, 0, 1); PG8_SCHED; PG8_LDA(At, 0, 0); PG8_STAGE(PG8_SA(1, 1), a1 + hstep, voffA);
;             PG8_WAIT_V(8); PG8_WAIT_L(0); PG8_BAR; PG8_MMA(0, 0, At, B0); PG8_MMA(0, 1, At, B1); PG8_BAR; PG8_SCHED;
;             PG8_LDA(At, 0, 1); PG8_STAGE(PG8_SB(0, 0), b2, voffB); PG8_STAGE(PG8_SB(0, 1), b2 + hstep, voffB); PG8_STAGE(PG8_SA(0, 0), a2, voffA);
;             PG8_WAIT_V(8); PG8_WAIT_L(0); PG8_BAR; PG8_MMA(1, 0, At, B0); PG8_MMA(1, 1, At, B1); PG8_BAR; PG8_SCHED;
;             PG8_LDB(B0, 1, 0); PG8_LDB(B1, 1, 1); PG8_SCHED; PG8_LDA(At, 1, 0); PG8_STAGE(PG8_SA(0, 1), a2 + hstep, voffA);
;             PG8_WAIT_V(8); PG8_WAIT_L(0); PG8_BAR; PG8_MMA(0, 0, At, B0); PG8_MMA(0, 1, At, B1); PG8_BAR; PG8_SCHED;
;             PG8_LDA(At, 1, 1); PG8_STAGE(PG8_SB(1, 0), b3, voffB); PG8_STAGE(PG8_SB(1, 1), b3 + hstep, voffB); PG8_STAGE(PG8_SA(1, 0), a3, voffA);
;             PG8_WAIT_V(8); PG8_WAIT_L(0); PG8_BAR; PG8_MMA(1, 0, At, B0); PG8_MMA(1, 1, At, B1); PG8_BAR; PG8_SCHED;
	s_waitcnt lgkmcnt(7)
	v_mfma_f32_16x16x32_bf16 v[124:127], v[142:145], v[174:177], v[124:127]
	v_mfma_f32_16x16x32_bf16 v[120:123], v[150:153], v[174:177], v[120:123]
	s_waitcnt lgkmcnt(5)
	v_mfma_f32_16x16x32_bf16 v[108:111], v[142:145], v[182:185], v[108:111]
	v_mfma_f32_16x16x32_bf16 v[104:107], v[150:153], v[182:185], v[104:107]
	s_waitcnt lgkmcnt(3)
	v_mfma_f32_16x16x32_bf16 v[92:95], v[142:145], v[190:193], v[92:95]
	v_mfma_f32_16x16x32_bf16 v[88:91], v[150:153], v[190:193], v[88:91]
	s_waitcnt lgkmcnt(1)
	v_mfma_f32_16x16x32_bf16 v[76:79], v[142:145], v[198:201], v[76:79]
	v_mfma_f32_16x16x32_bf16 v[72:75], v[150:153], v[198:201], v[72:75]
	v_mfma_f32_16x16x32_bf16 v[124:127], v[146:149], v[178:181], v[124:127]
	v_mfma_f32_16x16x32_bf16 v[120:123], v[154:157], v[178:181], v[120:123]
	v_mfma_f32_16x16x32_bf16 v[108:111], v[146:149], v[186:189], v[108:111]
	v_mfma_f32_16x16x32_bf16 v[104:107], v[154:157], v[186:189], v[104:107]
	v_mfma_f32_16x16x32_bf16 v[92:95], v[146:149], v[194:197], v[92:95]
	v_mfma_f32_16x16x32_bf16 v[88:91], v[154:157], v[194:197], v[88:91]
	s_waitcnt lgkmcnt(0)
	v_mfma_f32_16x16x32_bf16 v[76:79], v[146:149], v[202:205], v[76:79]
	v_mfma_f32_16x16x32_bf16 v[72:75], v[154:157], v[202:205], v[72:75]
	v_mfma_f32_16x16x32_bf16 v[116:119], v[158:161], v[174:177], v[116:119]
	v_mfma_f32_16x16x32_bf16 v[112:115], v[166:169], v[174:177], v[112:115]
	v_mfma_f32_16x16x32_bf16 v[100:103], v[158:161], v[182:185], v[100:103]
	v_mfma_f32_16x16x32_bf16 v[96:99], v[166:169], v[182:185], v[96:99]
	v_mfma_f32_16x16x32_bf16 v[84:87], v[158:161], v[190:193], v[84:87]
	v_mfma_f32_16x16x32_bf16 v[80:83], v[166:169], v[190:193], v[80:83]
	v_mfma_f32_16x16x32_bf16 v[68:71], v[158:161], v[198:201], v[68:71]
	v_mfma_f32_16x16x32_bf16 v[64:67], v[166:169], v[198:201], v[64:67]
	v_mfma_f32_16x16x32_bf16 v[116:119], v[162:165], v[178:181], v[116:119]
	v_mfma_f32_16x16x32_bf16 v[112:115], v[170:173], v[178:181], v[112:115]
	v_mfma_f32_16x16x32_bf16 v[100:103], v[162:165], v[186:189], v[100:103]
	v_mfma_f32_16x16x32_bf16 v[96:99], v[170:173], v[186:189], v[96:99]
	v_mfma_f32_16x16x32_bf16 v[84:87], v[162:165], v[194:197], v[84:87]
	v_mfma_f32_16x16x32_bf16 v[80:83], v[170:173], v[194:197], v[80:83]
	v_mfma_f32_16x16x32_bf16 v[68:71], v[162:165], v[202:205], v[68:71]
	v_mfma_f32_16x16x32_bf16 v[64:67], v[170:173], v[202:205], v[64:67]
	s_barrier
	s_mov_b32 m0, s37
	s_or_b32 s54, s35, 0x80
	ds_read_b128 v[174:177], v138 offset:49152
	ds_read_b128 v[178:181], v138 offset:50176
	ds_read_b128 v[182:185], v138 offset:51200
	ds_read_b128 v[186:189], v138 offset:52224
	ds_read_b128 v[190:193], v138 offset:53248
	ds_read_b128 v[194:197], v138 offset:54272
	ds_read_b128 v[198:201], v138 offset:55296
	ds_read_b128 v[202:205], v138 offset:56320
	buffer_load_dwordx4 v133, s[12:15], s54 offen lds
	s_mov_b32 m0, s38
	s_add_i32 s35, s35, 0x80080
	buffer_load_dwordx4 v135, s[12:15], s54 offen lds
	s_mov_b32 m0, s41
	s_nop 0
	buffer_load_dwordx4 v133, s[12:15], s35 offen lds
	s_mov_b32 m0, s42
	s_nop 0
	buffer_load_dwordx4 v135, s[12:15], s35 offen lds
	s_mov_b32 m0, s39
	s_nop 0
	buffer_load_dwordx4 v132, s[8:11], s21 offen lds
	s_mov_b32 m0, s40
	s_nop 0
	buffer_load_dwordx4 v134, s[8:11], s21 offen lds
	s_waitcnt vmcnt(8)
	s_waitcnt lgkmcnt(0)
	s_barrier
	s_waitcnt lgkmcnt(7)
	v_mfma_f32_16x16x32_bf16 v[60:63], v[142:145], v[174:177], v[60:63]
	v_mfma_f32_16x16x32_bf16 v[56:59], v[150:153], v[174:177], v[56:59]
	s_waitcnt lgkmcnt(5)
	v_mfma_f32_16x16x32_bf16 v[44:47], v[142:145], v[182:185], v[44:47]
	v_mfma_f32_16x16x32_bf16 v[40:43], v[150:153], v[182:185], v[40:43]
	s_waitcnt lgkmcnt(3)
	v_mfma_f32_16x16x32_bf16 v[28:31], v[142:145], v[190:193], v[28:31]
	v_mfma_f32_16x16x32_bf16 v[24:27], v[150:153], v[190:193], v[24:27]
	s_waitcnt lgkmcnt(1)
	v_mfma_f32_16x16x32_bf16 v[12:15], v[142:145], v[198:201], v[12:15]
	v_mfma_f32_16x16x32_bf16 v[8:11], v[150:153], v[198:201], v[8:11]
	v_mfma_f32_16x16x32_bf16 v[60:63], v[146:149], v[178:181], v[60:63]
	v_mfma_f32_16x16x32_bf16 v[56:59], v[154:157], v[178:181], v[56:59]
	v_mfma_f32_16x16x32_bf16 v[44:47], v[146:149], v[186:189], v[44:47]
	v_mfma_f32_16x16x32_bf16 v[40:43], v[154:157], v[186:189], v[40:43]
	v_mfma_f32_16x16x32_bf16 v[28:31], v[146:149], v[194:197], v[28:31]
	v_mfma_f32_16x16x32_bf16 v[24:27], v[154:157], v[194:197], v[24:27]
	s_waitcnt lgkmcnt(0)
	v_mfma_f32_16x16x32_bf16 v[12:15], v[146:149], v[202:205], v[12:15]
	v_mfma_f32_16x16x32_bf16 v[8:11], v[154:157], v[202:205], v[8:11]
	v_mfma_f32_16x16x32_bf16 v[52:55], v[158:161], v[174:177], v[52:55]
	v_mfma_f32_16x16x32_bf16 v[48:51], v[166:169], v[174:177], v[48:51]
	v_mfma_f32_16x16x32_bf16 v[36:39], v[158:161], v[182:185], v[36:39]
	v_mfma_f32_16x16x32_bf16 v[32:35], v[166:169], v[182:185], v[32:35]
	v_mfma_f32_16x16x32_bf16 v[20:23], v[158:161], v[190:193], v[20:23]
	v_mfma_f32_16x16x32_bf16 v[16:19], v[166:169], v[190:193], v[16:19]
	v_mfma_f32_16x16x32_bf16 v[4:7], v[158:161], v[198:201], v[4:7]
	v_mfma_f32_16x16x32_bf16 v[0:3], v[166:169], v[198:201], v[0:3]
	v_mfma_f32_16x16x32_bf16 v[52:55], v[162:165], v[178:181], v[52:55]
	v_mfma_f32_16x16x32_bf16 v[48:51], v[170:173], v[178:181], v[48:51]
	v_mfma_f32_16x16x32_bf16 v[36:39], v[162:165], v[186:189], v[36:39]
	v_mfma_f32_16x16x32_bf16 v[32:35], v[170:173], v[186:189], v[32:35]
	v_mfma_f32_16x16x32_bf16 v[20:23], v[162:165], v[194:197], v[20:23]
	v_mfma_f32_16x16x32_bf16 v[16:19], v[170:173], v[194:197], v[16:19]
	v_mfma_f32_16x16x32_bf16 v[4:7], v[162:165], v[202:205], v[4:7]
	v_mfma_f32_16x16x32_bf16 v[0:3], v[170:173], v[202:205], v[0:3]
	s_barrier
	s_add_i32 s20, s20, 2
	s_addk_i32 s1, 0x100
	s_addk_i32 s16, 0x100
	s_cmp_gt_u32 s20, 29
	s_cbranch_scc0 .LBB0_1076
	s_setprio 0
	s_and_b64 vcc, exec, s[18:19]
	s_cbranch_vccz .LBB0_1079
	s_barrier

; __device__ __forceinline__ int fresh_lane() { int l; asm volatile("v_mbcnt_lo_u32_b32 %0, -1, 0\n\tv_mbcnt_hi_u32_b32 %0, -1, %0" : "=v"(l)); return l; }
;     __device__ __forceinline__ void prefill(const Unit& u, int wr, int wc, int fr, int fq) const { float rs[2][4]; rows_rstd_c<false>(ssq, u.pm * BM + wr * 64 + fr, fr, fq, wr * 4 + wc, 0, tab, rs); }
;     __device__ __forceinline__ void prefill(const Unit& u, int wr, int wc, int fr, int fq) const { float rs[2][4]; rows_rstd_c<false>(ssq, u.pm * BM + wr * 64 + fr, fr, fq, wr * 4 + wc, 0, tab, rs); }
;     __device__ __forceinline__ void prefill(const Unit& u, int wr, int wc, int fr, int fq) const { float rs[2][4]; rows_rstd_c<false>(ssq, u.pm * BM + wr * 64 + fr, fr, fq, wr * 4 + wc, 0, tab, rs); }
; #define PG8_BAR __builtin_amdgcn_s_barrier()
; template <class Epi, class Sched, bool ALIGN_EPI = false, bool SP2 = false>
; __device__ __forceinline__ void gemm_phase(PG8_LAS unsigned char* lds, const Gemm g, const Sched& S, const Epi& E, const int wid  ) {
;     ...
; #pragma unroll
;         for (int a = 0; a < 2; ++a)
; #pragma unroll
;             for (int b = 0; b < 2; ++b)
; #pragma unroll
;                 for (int m = 0; m < 4; ++m)
; #pragma unroll
;                     for (int n = 0; n < 2; ++n) acc[a][b][m][n] = (f32x4){0.f, 0.f, 0.f, 0.f};
;         cur = nxt; cA = nA; cB = nB; ++ui;
;         if constexpr (Epi::PREFILL) { if (!cur.same) { const int l3 = fresh_lane(); E.prefill(cur, wr, wc, l3 & 15, l3 >> 4); cur.same = 1; } }
;         if constexpr (ALIGN_EPI) { if (wr == 1) PG8_BAR; }
.LBB0_1942:
	s_lshl_b32 s50, s49, 20
	s_and_b64 s[0:1], s[4:5], exec
	s_cselect_b32 s0, s50, s54
	s_lshl_b32 s51, s48, 20
	s_and_b64 s[14:15], s[4:5], exec
	v_mov_b32_e32 v0, 0
	s_cselect_b32 s1, s51, s55
	s_add_i32 s54, s54, 0x80080
	s_addk_i32 s55, 0x100
	s_mov_b32 s58, -2
	s_waitcnt lgkmcnt(0)
	v_mov_b32_e32 v1, v0
	v_mov_b32_e32 v2, v0
	v_mov_b32_e32 v3, v0
	v_mov_b32_e32 v4, v0
	v_mov_b32_e32 v5, v0
	v_mov_b32_e32 v6, v0
	v_mov_b32_e32 v7, v0
	v_mov_b32_e32 v16, v0
	v_mov_b32_e32 v17, v0
	v_mov_b32_e32 v18, v0
	v_mov_b32_e32 v19, v0
	s_waitcnt vmcnt(21)
	v_mov_b32_e32 v20, v0
	v_mov_b32_e32 v21, v0
	v_mov_b32_e32 v22, v0
	v_mov_b32_e32 v23, v0
	v_mov_b32_e32 v32, v0
	v_mov_b32_e32 v33, v0
	v_mov_b32_e32 v34, v0
	v_mov_b32_e32 v35, v0
	v_mov_b32_e32 v36, v0
	v_mov_b32_e32 v37, v0
	v_mov_b32_e32 v38, v0
	v_mov_b32_e32 v39, v0
	v_mov_b32_e32 v48, v0
	v_mov_b32_e32 v49, v0
	s_waitcnt vmcnt(16)
	v_mov_b32_e32 v50, v0
	v_mov_b32_e32 v51, v0
	v_mov_b32_e32 v52, v0
	v_mov_b32_e32 v53, v0
	v_mov_b32_e32 v54, v0
	v_mov_b32_e32 v55, v0
	v_mov_b32_e32 v8, v0
	v_mov_b32_e32 v9, v0
	v_mov_b32_e32 v10, v0
	v_mov_b32_e32 v11, v0
	v_mov_b32_e32 v12, v0
	v_mov_b32_e32 v13, v0
	v_mov_b32_e32 v14, v0
	v_mov_b32_e32 v15, v0
	v_mov_b32_e32 v24, v0
	v_mov_b32_e32 v25, v0
	v_mov_b32_e32 v26, v0
	v_mov_b32_e32 v27, v0
	v_mov_b32_e32 v28, v0
	v_mov_b32_e32 v29, v0
	v_mov_b32_e32 v30, v0
	v_mov_b32_e32 v31, v0
	v_mov_b32_e32 v40, v0
	v_mov_b32_e32 v41, v0
	v_mov_b32_e32 v42, v0
	v_mov_b32_e32 v43, v0
	v_mov_b32_e32 v44, v0
	v_mov_b32_e32 v45, v0
	v_mov_b32_e32 v46, v0
	v_mov_b32_e32 v47, v0
	v_mov_b32_e32 v56, v0
	v_mov_b32_e32 v57, v0
	v_mov_b32_e32 v58, v0
	v_mov_b32_e32 v59, v0
	v_mov_b32_e32 v60, v0
	v_mov_b32_e32 v61, v0
	v_mov_b32_e32 v62, v0
	v_mov_b32_e32 v63, v0
	v_mov_b32_e32 v64, v0
	v_mov_b32_e32 v65, v0
	s_waitcnt vmcnt(15)
	v_mov_b32_e32 v66, v0
	v_mov_b32_e32 v67, v0
	v_mov_b32_e32 v68, v0
	v_mov_b32_e32 v69, v0
	v_mov_b32_e32 v70, v0
	v_mov_b32_e32 v71, v0
	v_mov_b32_e32 v80, v0
	v_mov_b32_e32 v81, v0
	v_mov_b32_e32 v82, v0
	v_mov_b32_e32 v83, v0
	v_mov_b32_e32 v84, v0
	v_mov_b32_e32 v85, v0
	v_mov_b32_e32 v86, v0
	v_mov_b32_e32 v87, v0
	v_mov_b32_e32 v96, v0
	v_mov_b32_e32 v97, v0
	v_mov_b32_e32 v98, v0
	v_mov_b32_e32 v99, v0
	v_mov_b32_e32 v100, v0
	v_mov_b32_e32 v101, v0
	v_mov_b32_e32 v102, v0
	v_mov_b32_e32 v103, v0
	v_mov_b32_e32 v112, v0
	v_mov_b32_e32 v113, v0
	v_mov_b32_e32 v114, v0
	v_mov_b32_e32 v115, v0
	v_mov_b32_e32 v116, v0
	v_mov_b32_e32 v117, v0
	v_mov_b32_e32 v118, v0
	v_mov_b32_e32 v119, v0
	v_mov_b32_e32 v72, v0
	v_mov_b32_e32 v73, v0
	v_mov_b32_e32 v74, v0
	v_mov_b32_e32 v75, v0
	v_mov_b32_e32 v76, v0
	v_mov_b32_e32 v77, v0
	v_mov_b32_e32 v78, v0
	v_mov_b32_e32 v79, v0
	v_mov_b32_e32 v88, v0
	v_mov_b32_e32 v89, v0
	v_mov_b32_e32 v90, v0
	v_mov_b32_e32 v91, v0
	v_mov_b32_e32 v92, v0
	v_mov_b32_e32 v93, v0
	v_mov_b32_e32 v94, v0
	v_mov_b32_e32 v95, v0
	v_mov_b32_e32 v104, v0
	v_mov_b32_e32 v105, v0
	v_mov_b32_e32 v106, v0
	v_mov_b32_e32 v107, v0
	v_mov_b32_e32 v108, v0
	v_mov_b32_e32 v109, v0
	v_mov_b32_e32 v110, v0
	v_mov_b32_e32 v111, v0
	v_mov_b32_e32 v120, v0
	v_mov_b32_e32 v121, v0
	v_mov_b32_e32 v122, v0
	v_mov_b32_e32 v123, v0
	v_mov_b32_e32 v124, v0
	v_mov_b32_e32 v125, v0
	v_mov_b32_e32 v126, v0
	v_mov_b32_e32 v127, v0
	v_readlane_b32 vcc_lo, v246, 6
	s_nop 1
	s_cmp_ge_u32 vcc_lo, 4
	s_cbranch_scc0 .Lprio_1943
	s_setprio 1

; #define PG8_STAGE(bufoff, soff, voff) do { _Pragma("unroll") for (int _i = 0; _i < 2; ++_i) \
;         __builtin_amdgcn_raw_ptr_buffer_load_lds(rs_##voff, (PG8_LAS unsigned*)(lds + (bufoff) + ldsw + _i * 8192), 16, (int)(voff)[_i], (int)(soff), 0, 0); } while (0)
; #define PG8_LDA(dst, b, h) do { _Pragma("unroll") for (int m = 0; m < 4; ++m) _Pragma("unroll") for (int k = 0; k < 2; ++k) dst[m][k] = *(const PG8_LAS bf16x8*)(lds + PG8_SA(b, h) + aoff + m * 2048 + k * 1024); } while (0)
; #define PG8_LDB(dst, b, h) do { _Pragma("unroll") for (int n = 0; n < 2; ++n) _Pragma("unroll") for (int k = 0; k < 2; ++k) dst[n][k] = *(const PG8_LAS bf16x8*)(lds + PG8_SB(b, h) + boff + n * 2048 + k * 1024); } while (0)
; #define PG8_SCHED __builtin_amdgcn_sched_barrier(0)
; template <class Epi, class Sched, bool ALIGN_EPI = false, bool SP2 = false>
; __device__ __forceinline__ void gemm_phase(PG8_LAS unsigned char* lds, const Gemm g, const Sched& S, const Epi& E, const int wid  ) {
;     ...
;         for (int t = 0; t < nt; t += 2) {
;             const bool last = (t == nt - 2);
;             const unsigned a1 = cA + (unsigned)(t + 1) * kstep;
;             const unsigned a2 = last ? nA : cA + (unsigned)(t + 2) * kstep, b2 = last ? nB : cB + (unsigned)(t + 2) * kstep;
;             const unsigned a3 = a2 + kstep, b3 = b2 + kstep;
;             if (last && has_next) S.a_ready(nxt);
;             if constexpr (SP2) {
;             PG8_LDB(B0, 0, 0); PG8_LDB(B1, 0, 1); PG8_SCHED; PG8_LDA(At, 0, 0); PG8_STAGE(PG8_SA(1, 1), a1 + hstep, voffA);
;     ...
; #pragma unroll
;         for (int a = 0; a < 2; ++a)
; #pragma unroll
;             for (int b = 0; b < 2; ++b)
; #pragma unroll
;                 for (int m = 0; m < 4; ++m)
; #pragma unroll
;                     for (int n = 0; n < 2; ++n) acc[a][b][m][n] = (f32x4){0.f, 0.f, 0.f, 0.f};
;         cur = nxt; cA = nA; cB = nB; ++ui;
.LBB0_2036:
	s_lshl_b32 s90, s89, 20
	s_and_b64 s[6:7], s[4:5], exec
	s_cselect_b32 s6, s90, s48
	s_lshl_b32 s91, s88, 20
	s_and_b64 s[18:19], s[4:5], exec
	v_mov_b32_e32 v56, 0
	s_cselect_b32 s7, s91, s9
	s_add_i32 s8, s48, 0x80080
	s_addk_i32 s9, 0x100
	s_mov_b32 s48, -2
	v_mov_b32_e32 v57, v56
	v_mov_b32_e32 v58, v56
	v_mov_b32_e32 v59, v56
	v_mov_b32_e32 v60, v56
	v_mov_b32_e32 v61, v56
	v_mov_b32_e32 v62, v56
	v_mov_b32_e32 v63, v56
	v_mov_b32_e32 v64, v56
	v_mov_b32_e32 v65, v56
	v_mov_b32_e32 v66, v56
	v_mov_b32_e32 v67, v56
	v_mov_b32_e32 v68, v56
	v_mov_b32_e32 v69, v56
	v_mov_b32_e32 v70, v56
	v_mov_b32_e32 v71, v56
	v_mov_b32_e32 v72, v56
	v_mov_b32_e32 v73, v56
	v_mov_b32_e32 v74, v56
	v_mov_b32_e32 v75, v56
	v_mov_b32_e32 v80, v56
	v_mov_b32_e32 v81, v56
	v_mov_b32_e32 v82, v56
	v_mov_b32_e32 v83, v56
	v_mov_b32_e32 v0, v56
	v_mov_b32_e32 v1, v56
	s_waitcnt lgkmcnt(7)
	v_mov_b32_e32 v2, v56
	v_mov_b32_e32 v3, v56
	s_waitcnt lgkmcnt(6)
	v_mov_b32_e32 v4, v56
	v_mov_b32_e32 v5, v56
	s_waitcnt lgkmcnt(5)
	v_mov_b32_e32 v6, v56
	v_mov_b32_e32 v7, v56
	v_mov_b32_e32 v48, v56
	v_mov_b32_e32 v49, v56
	v_mov_b32_e32 v50, v56
	v_mov_b32_e32 v51, v56
	v_mov_b32_e32 v92, v56
	v_mov_b32_e32 v93, v56
	v_mov_b32_e32 v94, v56
	v_mov_b32_e32 v95, v56
	v_mov_b32_e32 v76, v56
	v_mov_b32_e32 v77, v56
	v_mov_b32_e32 v78, v56
	v_mov_b32_e32 v79, v56
	v_mov_b32_e32 v84, v56
	v_mov_b32_e32 v85, v56
	v_mov_b32_e32 v86, v56
	v_mov_b32_e32 v87, v56
	v_mov_b32_e32 v88, v56
	v_mov_b32_e32 v89, v56
	v_mov_b32_e32 v90, v56
	v_mov_b32_e32 v91, v56
	v_mov_b32_e32 v96, v56
	v_mov_b32_e32 v97, v56
	v_mov_b32_e32 v98, v56
	v_mov_b32_e32 v99, v56
	v_mov_b32_e32 v100, v56
	v_mov_b32_e32 v101, v56
	v_mov_b32_e32 v102, v56
	v_mov_b32_e32 v103, v56
	v_mov_b32_e32 v104, v56
	v_mov_b32_e32 v105, v56
	v_mov_b32_e32 v106, v56
	v_mov_b32_e32 v107, v56
	v_mov_b32_e32 v108, v56
	v_mov_b32_e32 v109, v56
	v_mov_b32_e32 v110, v56
	v_mov_b32_e32 v111, v56
	v_mov_b32_e32 v112, v56
	v_mov_b32_e32 v113, v56
	v_mov_b32_e32 v114, v56
	v_mov_b32_e32 v115, v56
	v_mov_b32_e32 v116, v56
	v_mov_b32_e32 v117, v56
	v_mov_b32_e32 v118, v56
	v_mov_b32_e32 v119, v56
	v_mov_b32_e32 v124, v56
	v_mov_b32_e32 v125, v56
	v_mov_b32_e32 v126, v56
	v_mov_b32_e32 v127, v56
	v_mov_b32_e32 v128, v56
	v_mov_b32_e32 v129, v56
	v_mov_b32_e32 v130, v56
	v_mov_b32_e32 v131, v56
	v_mov_b32_e32 v136, v56
	v_mov_b32_e32 v137, v56
	v_mov_b32_e32 v138, v56
	v_mov_b32_e32 v139, v56
	s_waitcnt lgkmcnt(4)
	v_mov_b32_e32 v8, v56
	v_mov_b32_e32 v9, v56
	s_waitcnt lgkmcnt(3)
	v_mov_b32_e32 v10, v56
	v_mov_b32_e32 v11, v56
	s_waitcnt lgkmcnt(2)
	v_mov_b32_e32 v12, v56
	v_mov_b32_e32 v13, v56
	s_waitcnt lgkmcnt(1)
	v_mov_b32_e32 v14, v56
	v_mov_b32_e32 v15, v56
	v_mov_b32_e32 v120, v56
	v_mov_b32_e32 v121, v56
	v_mov_b32_e32 v122, v56
	v_mov_b32_e32 v123, v56
	v_mov_b32_e32 v156, v56
	v_mov_b32_e32 v157, v56
	v_mov_b32_e32 v158, v56
	v_mov_b32_e32 v159, v56
	v_mov_b32_e32 v132, v56
	v_mov_b32_e32 v133, v56
	v_mov_b32_e32 v134, v56
	v_mov_b32_e32 v135, v56
	v_mov_b32_e32 v140, v56
	v_mov_b32_e32 v141, v56
	v_mov_b32_e32 v142, v56
	v_mov_b32_e32 v143, v56
	v_mov_b32_e32 v144, v56
	v_mov_b32_e32 v145, v56
	v_mov_b32_e32 v146, v56
	v_mov_b32_e32 v147, v56
	v_mov_b32_e32 v148, v56
	v_mov_b32_e32 v149, v56
	v_mov_b32_e32 v150, v56
	v_mov_b32_e32 v151, v56
	v_mov_b32_e32 v52, v56
	v_mov_b32_e32 v53, v56
	v_mov_b32_e32 v54, v56
	v_mov_b32_e32 v55, v56
	v_mov_b32_e32 v152, v56
	v_mov_b32_e32 v153, v56
	v_mov_b32_e32 v154, v56
	v_mov_b32_e32 v155, v56
	v_readlane_b32 vcc_lo, v246, 6
	s_nop 1
	s_cmp_ge_u32 vcc_lo, 4
	s_cbranch_scc0 .Lprio_2037
	s_setprio 1
.Lprio_2037:
.LBB0_2037:
	s_waitcnt lgkmcnt(0)
	ds_read_b128 v[16:19], v188
	ds_read_b128 v[20:23], v188 offset:1024
	ds_read_b128 v[24:27], v188 offset:2048
	ds_read_b128 v[28:31], v188 offset:3072
	ds_read_b128 v[32:35], v189
	ds_read_b128 v[36:39], v189 offset:1024
	ds_read_b128 v[40:43], v189 offset:2048
	ds_read_b128 v[44:47], v189 offset:3072
	s_add_i32 s18, s8, 0xfff80080
	s_cmp_eq_u32 s48, 28
	s_cselect_b32 s93, s6, s18
	s_cselect_b32 s92, s7, s9
	s_or_b32 s49, s93, 0x80
	s_mov_b32 m0, s74
	ds_read_b128 v[160:163], v190
	ds_read_b128 v[170:173], v190 offset:1024
	ds_read_b128 v[174:177], v190 offset:2048
	ds_read_b128 v[178:181], v190 offset:3072
	ds_read_b128 v[194:197], v190 offset:4096
	ds_read_b128 v[198:201], v190 offset:5120
	ds_read_b128 v[202:205], v190 offset:6144
	ds_read_b128 v[206:209], v190 offset:7168
	buffer_load_dwordx4 v182, s[12:15], s8 offen lds
	s_mov_b32 m0, s76
	s_nop 0
	buffer_load_dwordx4 v184, s[12:15], s8 offen lds
	s_waitcnt vmcnt(8)
	s_waitcnt lgkmcnt(0)
	s_barrier
; #define PG8_STAGE(bufoff, soff, voff) do { _Pragma("unroll") for (int _i = 0; _i < 2; ++_i) \
;         __builtin_amdgcn_raw_ptr_buffer_load_lds(rs_##voff, (PG8_LAS unsigned*)(lds + (bufoff) + ldsw + _i * 8192), 16, (int)(voff)[_i], (int)(soff), 0, 0); } while (0)
; #define PG8_LDA(dst, b, h) do { _Pragma("unroll") for (int m = 0; m < 4; ++m) _Pragma("unroll") for (int k = 0; k < 2; ++k) dst[m][k] = *(const PG8_LAS bf16x8*)(lds + PG8_SA(b, h) + aoff + m * 2048 + k * 1024); } while (0)
; #define PG8_LDB(dst, b, h) do { _Pragma("unroll") for (int n = 0; n < 2; ++n) _Pragma("unroll") for (int k = 0; k < 2; ++k) dst[n][k] = *(const PG8_LAS bf16x8*)(lds + PG8_SB(b, h) + boff + n * 2048 + k * 1024); } while (0)
; #define PG8_MMA(ai, bj, At, Bt) do { __builtin_amdgcn_s_setprio(1); _Pragma("unroll") for (int m = 0; m < 4; ++m) _Pragma("unroll") for (int n = 0; n < 2; ++n) _Pragma("unroll") for (int k = 0; k < 2; ++k) \
;         acc[ai][bj][m][n] = __builtin_amdgcn_mfma_f32_16x16x32_bf16(Bt[n][k], At[m][k], acc[ai][bj][m][n], 0, 0, 0); __builtin_amdgcn_s_setprio(0); } while (0)
; #define PG8_WAIT_V(n) asm volatile("s_waitcnt vmcnt(" #n ")" ::: "memory")
; #define PG8_WAIT_L(n) asm volatile("s_waitcnt lgkmcnt(" #n ")" ::: "memory")
; #define PG8_BAR __builtin_amdgcn_s_barrier()
; #define PG8_SCHED __builtin_amdgcn_sched_barrier(0)
; template <class Epi, class Sched, bool ALIGN_EPI = false, bool SP2 = false>
; __device__ __forceinline__ void gemm_phase(PG8_LAS unsigned char* lds, const Gemm g, const Sched& S, const Epi& E, const int wid  ) {
;     ...
;             PG8_LDB(B0, 0, 0); PG8_LDB(B1, 0, 1); PG8_SCHED; PG8_LDA(At, 0, 0); PG8_STAGE(PG8_SA(1, 1), a1 + hstep, voffA);
;             PG8_WAIT_V(8); PG8_WAIT_L(0); PG8_BAR; PG8_MMA(0, 0, At, B0); PG8_MMA(0, 1, At, B1); PG8_BAR; PG8_SCHED;
;             PG8_LDA(At, 0, 1); PG8_STAGE(PG8_SB(0, 0), b2, voffB); PG8_STAGE(PG8_SB(0, 1), b2 + hstep, voffB); PG8_STAGE(PG8_SA(0, 0), a2, voffA);
;             PG8_WAIT_V(8); PG8_WAIT_L(0); PG8_BAR; PG8_MMA(1, 0, At, B0); PG8_MMA(1, 1, At, B1); PG8_BAR; PG8_SCHED;
	s_waitcnt lgkmcnt(7)
	v_mfma_f32_16x16x32_bf16 v[152:155], v[16:19], v[160:163], v[152:155]
	v_mfma_f32_16x16x32_bf16 v[52:55], v[24:27], v[160:163], v[52:55]
	s_waitcnt lgkmcnt(5)
	v_mfma_f32_16x16x32_bf16 v[148:151], v[16:19], v[174:177], v[148:151]
	v_mfma_f32_16x16x32_bf16 v[144:147], v[24:27], v[174:177], v[144:147]
	s_waitcnt lgkmcnt(3)
	v_mfma_f32_16x16x32_bf16 v[140:143], v[16:19], v[194:197], v[140:143]
	v_mfma_f32_16x16x32_bf16 v[132:135], v[24:27], v[194:197], v[132:135]
	s_waitcnt lgkmcnt(1)
	v_mfma_f32_16x16x32_bf16 v[156:159], v[16:19], v[202:205], v[156:159]
	v_mfma_f32_16x16x32_bf16 v[120:123], v[24:27], v[202:205], v[120:123]
	v_mfma_f32_16x16x32_bf16 v[152:155], v[20:23], v[170:173], v[152:155]
	v_mfma_f32_16x16x32_bf16 v[52:55], v[28:31], v[170:173], v[52:55]
	v_mfma_f32_16x16x32_bf16 v[148:151], v[20:23], v[178:181], v[148:151]
	v_mfma_f32_16x16x32_bf16 v[144:147], v[28:31], v[178:181], v[144:147]
	v_mfma_f32_16x16x32_bf16 v[140:143], v[20:23], v[198:201], v[140:143]
	v_mfma_f32_16x16x32_bf16 v[132:135], v[28:31], v[198:201], v[132:135]
	s_waitcnt lgkmcnt(0)
	v_mfma_f32_16x16x32_bf16 v[156:159], v[20:23], v[206:209], v[156:159]
	v_mfma_f32_16x16x32_bf16 v[120:123], v[28:31], v[206:209], v[120:123]
	v_mfma_f32_16x16x32_bf16 v[12:15], v[32:35], v[160:163], v[12:15]
	v_mfma_f32_16x16x32_bf16 v[8:11], v[40:43], v[160:163], v[8:11]
	v_mfma_f32_16x16x32_bf16 v[136:139], v[32:35], v[174:177], v[136:139]
	v_mfma_f32_16x16x32_bf16 v[128:131], v[40:43], v[174:177], v[128:131]
	v_mfma_f32_16x16x32_bf16 v[124:127], v[32:35], v[194:197], v[124:127]
	v_mfma_f32_16x16x32_bf16 v[116:119], v[40:43], v[194:197], v[116:119]
	v_mfma_f32_16x16x32_bf16 v[112:115], v[32:35], v[202:205], v[112:115]
	v_mfma_f32_16x16x32_bf16 v[108:111], v[40:43], v[202:205], v[108:111]
	v_mfma_f32_16x16x32_bf16 v[12:15], v[36:39], v[170:173], v[12:15]
	v_mfma_f32_16x16x32_bf16 v[8:11], v[44:47], v[170:173], v[8:11]
	v_mfma_f32_16x16x32_bf16 v[136:139], v[36:39], v[178:181], v[136:139]
	v_mfma_f32_16x16x32_bf16 v[128:131], v[44:47], v[178:181], v[128:131]
	v_mfma_f32_16x16x32_bf16 v[124:127], v[36:39], v[198:201], v[124:127]
	v_mfma_f32_16x16x32_bf16 v[116:119], v[44:47], v[198:201], v[116:119]
	v_mfma_f32_16x16x32_bf16 v[112:115], v[36:39], v[206:209], v[112:115]
	v_mfma_f32_16x16x32_bf16 v[108:111], v[44:47], v[206:209], v[108:111]
	s_barrier
	s_mov_b32 m0, s34
	s_mov_b32 s18, s14
	s_mov_b32 s19, s15
	ds_read_b128 v[160:163], v190 offset:16384
	ds_read_b128 v[170:173], v190 offset:17408
	ds_read_b128 v[174:177], v190 offset:18432
	ds_read_b128 v[178:181], v190 offset:19456
	ds_read_b128 v[194:197], v190 offset:20480
	ds_read_b128 v[198:201], v190 offset:21504
	ds_read_b128 v[202:205], v190 offset:22528
	ds_read_b128 v[206:209], v190 offset:23552
	buffer_load_dwordx4 v183, s[16:19], s92 offen lds
	s_mov_b32 m0, s35
	s_add_i32 s94, s92, 0x80000
	buffer_load_dwordx4 v185, s[16:19], s92 offen lds
	s_mov_b32 m0, s50
	s_nop 0
	buffer_load_dwordx4 v183, s[16:19], s94 offen lds
	s_mov_b32 m0, s51
	s_nop 0
	buffer_load_dwordx4 v185, s[16:19], s94 offen lds
	s_mov_b32 m0, s33
	s_nop 0
	buffer_load_dwordx4 v182, s[12:15], s93 offen lds
	s_mov_b32 m0, s53
	s_nop 0
	buffer_load_dwordx4 v184, s[12:15], s93 offen lds
	s_waitcnt vmcnt(8)
	s_waitcnt lgkmcnt(0)
	s_barrier
	s_waitcnt lgkmcnt(7)
	v_mfma_f32_16x16x32_bf16 v[104:107], v[16:19], v[160:163], v[104:107]
	v_mfma_f32_16x16x32_bf16 v[100:103], v[24:27], v[160:163], v[100:103]
	s_waitcnt lgkmcnt(5)
	v_mfma_f32_16x16x32_bf16 v[96:99], v[16:19], v[174:177], v[96:99]
	v_mfma_f32_16x16x32_bf16 v[88:91], v[24:27], v[174:177], v[88:91]
	s_waitcnt lgkmcnt(3)
	v_mfma_f32_16x16x32_bf16 v[84:87], v[16:19], v[194:197], v[84:87]
	v_mfma_f32_16x16x32_bf16 v[76:79], v[24:27], v[194:197], v[76:79]
	s_waitcnt lgkmcnt(1)
	v_mfma_f32_16x16x32_bf16 v[16:19], v[16:19], v[202:205], v[92:95]
	v_mfma_f32_16x16x32_bf16 v[104:107], v[20:23], v[170:173], v[104:107]
	v_mfma_f32_16x16x32_bf16 v[100:103], v[28:31], v[170:173], v[100:103]
	v_mfma_f32_16x16x32_bf16 v[96:99], v[20:23], v[178:181], v[96:99]
	v_mfma_f32_16x16x32_bf16 v[88:91], v[28:31], v[178:181], v[88:91]
	v_mfma_f32_16x16x32_bf16 v[84:87], v[20:23], v[198:201], v[84:87]
	v_mfma_f32_16x16x32_bf16 v[76:79], v[28:31], v[198:201], v[76:79]
	s_waitcnt lgkmcnt(0)
	v_mfma_f32_16x16x32_bf16 v[16:19], v[20:23], v[206:209], v[16:19]
	v_mfma_f32_16x16x32_bf16 v[20:23], v[24:27], v[202:205], v[48:51]
	v_mfma_f32_16x16x32_bf16 v[20:23], v[28:31], v[206:209], v[20:23]
	v_mfma_f32_16x16x32_bf16 v[48:51], v[32:35], v[194:197], v[68:71]
	v_mfma_f32_16x16x32_bf16 v[4:7], v[32:35], v[160:163], v[4:7]
	v_mfma_f32_16x16x32_bf16 v[0:3], v[40:43], v[160:163], v[0:3]
	v_mfma_f32_16x16x32_bf16 v[24:27], v[32:35], v[174:177], v[80:83]
	v_mfma_f32_16x16x32_bf16 v[68:71], v[36:39], v[198:201], v[48:51]
	v_mfma_f32_16x16x32_bf16 v[48:51], v[40:43], v[194:197], v[64:67]
	v_mfma_f32_16x16x32_bf16 v[32:35], v[32:35], v[202:205], v[60:63]
	v_mfma_f32_16x16x32_bf16 v[4:7], v[36:39], v[170:173], v[4:7]
	v_mfma_f32_16x16x32_bf16 v[0:3], v[44:47], v[170:173], v[0:3]
	v_mfma_f32_16x16x32_bf16 v[24:27], v[36:39], v[178:181], v[24:27]
	v_mfma_f32_16x16x32_bf16 v[28:31], v[40:43], v[174:177], v[72:75]
	v_mfma_f32_16x16x32_bf16 v[64:67], v[44:47], v[198:201], v[48:51]
	v_mfma_f32_16x16x32_bf16 v[32:35], v[36:39], v[206:209], v[32:35]
	v_mfma_f32_16x16x32_bf16 v[36:39], v[40:43], v[202:205], v[56:59]
	v_mfma_f32_16x16x32_bf16 v[28:31], v[44:47], v[178:181], v[28:31]
	v_mfma_f32_16x16x32_bf16 v[36:39], v[44:47], v[206:209], v[36:39]
	s_barrier
; #define PG8_STAGE(bufoff, soff, voff) do { _Pragma("unroll") for (int _i = 0; _i < 2; ++_i) \
;         __builtin_amdgcn_raw_ptr_buffer_load_lds(rs_##voff, (PG8_LAS unsigned*)(lds + (bufoff) + ldsw + _i * 8192), 16, (int)(voff)[_i], (int)(soff), 0, 0); } while (0)
; #define PG8_LDA(dst, b, h) do { _Pragma("unroll") for (int m = 0; m < 4; ++m) _Pragma("unroll") for (int k = 0; k < 2; ++k) dst[m][k] = *(const PG8_LAS bf16x8*)(lds + PG8_SA(b, h) + aoff + m * 2048 + k * 1024); } while (0)
; #define PG8_LDB(dst, b, h) do { _Pragma("unroll") for (int n = 0; n < 2; ++n) _Pragma("unroll") for (int k = 0; k < 2; ++k) dst[n][k] = *(const PG8_LAS bf16x8*)(lds + PG8_SB(b, h) + boff + n * 2048 + k * 1024); } while (0)
; #define PG8_MMA(ai, bj, At, Bt) do { __builtin_amdgcn_s_setprio(1); _Pragma("unroll") for (int m = 0; m < 4; ++m) _Pragma("unroll") for (int n = 0; n < 2; ++n) _Pragma("unroll") for (int k = 0; k < 2; ++k) \
;         acc[ai][bj][m][n] = __builtin_amdgcn_mfma_f32_16x16x32_bf16(Bt[n][k], At[m][k], acc[ai][bj][m][n], 0, 0, 0); __builtin_amdgcn_s_setprio(0); } while (0)
; #define PG8_WAIT_V(n) asm volatile("s_waitcnt vmcnt(" #n ")" ::: "memory")
; #define PG8_WAIT_L(n) asm volatile("s_waitcnt lgkmcnt(" #n ")" ::: "memory")
; #define PG8_BAR __builtin_amdgcn_s_barrier()
; #define PG8_SCHED __builtin_amdgcn_sched_barrier(0)
; template <class Epi, class Sched, bool ALIGN_EPI = false, bool SP2 = false>
; __device__ __forceinline__ void gemm_phase(PG8_LAS unsigned char* lds, const Gemm g, const Sched& S, const Epi& E, const int wid  ) {
;     ...
;             PG8_WAIT_V(8); PG8_WAIT_L(0); PG8_BAR; PG8_MMA(1, 0, At, B0); PG8_MMA(1, 1, At, B1); PG8_BAR; PG8_SCHED;
;             PG8_LDB(B0, 1, 0); PG8_LDB(B1, 1, 1); PG8_SCHED; PG8_LDA(At, 1, 0); PG8_STAGE(PG8_SA(0, 1), a2 + hstep, voffA);
;             PG8_WAIT_V(8); PG8_WAIT_L(0); PG8_BAR; PG8_MMA(0, 0, At, B0); PG8_MMA(0, 1, At, B1); PG8_BAR; PG8_SCHED;
;             PG8_LDA(At, 1, 1); PG8_STAGE(PG8_SB(1, 0), b3, voffB); PG8_STAGE(PG8_SB(1, 1), b3 + hstep, voffB); PG8_STAGE(PG8_SA(1, 0), a3, voffA);
;             PG8_WAIT_V(8); PG8_WAIT_L(0); PG8_BAR; PG8_MMA(1, 0, At, B0); PG8_MMA(1, 1, At, B1); PG8_BAR; PG8_SCHED;
	ds_read_b128 v[40:43], v191
	ds_read_b128 v[44:47], v191 offset:1024
	ds_read_b128 v[48:51], v191 offset:2048
	ds_read_b128 v[56:59], v191 offset:3072
	ds_read_b128 v[60:63], v192
	ds_read_b128 v[160:163], v192 offset:1024
	ds_read_b128 v[170:173], v192 offset:2048
	ds_read_b128 v[174:177], v192 offset:3072
	s_add_i32 s93, s93, 0x80000
	s_mov_b32 m0, s54
	ds_read_b128 v[72:75], v190 offset:32768
	ds_read_b128 v[80:83], v190 offset:33792
	ds_read_b128 v[92:95], v190 offset:34816
	ds_read_b128 v[178:181], v190 offset:35840
	ds_read_b128 v[194:197], v190 offset:36864
	ds_read_b128 v[198:201], v190 offset:37888
	ds_read_b128 v[202:205], v190 offset:38912
	ds_read_b128 v[206:209], v190 offset:39936
	buffer_load_dwordx4 v182, s[12:15], s93 offen lds
	s_mov_b32 m0, s58
	s_nop 0
	buffer_load_dwordx4 v184, s[12:15], s93 offen lds
	s_waitcnt vmcnt(8)
	s_waitcnt lgkmcnt(0)
	s_barrier
	s_waitcnt lgkmcnt(7)
	v_mfma_f32_16x16x32_bf16 v[152:155], v[40:43], v[72:75], v[152:155]
	v_mfma_f32_16x16x32_bf16 v[52:55], v[48:51], v[72:75], v[52:55]
	s_waitcnt lgkmcnt(5)
	v_mfma_f32_16x16x32_bf16 v[148:151], v[40:43], v[92:95], v[148:151]
	v_mfma_f32_16x16x32_bf16 v[144:147], v[48:51], v[92:95], v[144:147]
	s_waitcnt lgkmcnt(3)
	v_mfma_f32_16x16x32_bf16 v[140:143], v[40:43], v[194:197], v[140:143]
	v_mfma_f32_16x16x32_bf16 v[132:135], v[48:51], v[194:197], v[132:135]
	s_waitcnt lgkmcnt(1)
	v_mfma_f32_16x16x32_bf16 v[156:159], v[40:43], v[202:205], v[156:159]
	v_mfma_f32_16x16x32_bf16 v[120:123], v[48:51], v[202:205], v[120:123]
	v_mfma_f32_16x16x32_bf16 v[152:155], v[44:47], v[80:83], v[152:155]
	v_mfma_f32_16x16x32_bf16 v[52:55], v[56:59], v[80:83], v[52:55]
	v_mfma_f32_16x16x32_bf16 v[148:151], v[44:47], v[178:181], v[148:151]
	v_mfma_f32_16x16x32_bf16 v[144:147], v[56:59], v[178:181], v[144:147]
	v_mfma_f32_16x16x32_bf16 v[140:143], v[44:47], v[198:201], v[140:143]
	v_mfma_f32_16x16x32_bf16 v[132:135], v[56:59], v[198:201], v[132:135]
	s_waitcnt lgkmcnt(0)
	v_mfma_f32_16x16x32_bf16 v[156:159], v[44:47], v[206:209], v[156:159]
	v_mfma_f32_16x16x32_bf16 v[120:123], v[56:59], v[206:209], v[120:123]
	v_mfma_f32_16x16x32_bf16 v[12:15], v[60:63], v[72:75], v[12:15]
	v_mfma_f32_16x16x32_bf16 v[8:11], v[170:173], v[72:75], v[8:11]
	v_mfma_f32_16x16x32_bf16 v[72:75], v[60:63], v[92:95], v[136:139]
	v_mfma_f32_16x16x32_bf16 v[136:139], v[160:163], v[178:181], v[72:75]
	v_mfma_f32_16x16x32_bf16 v[72:75], v[170:173], v[92:95], v[128:131]
	v_mfma_f32_16x16x32_bf16 v[128:131], v[174:177], v[178:181], v[72:75]
	v_mfma_f32_16x16x32_bf16 v[72:75], v[60:63], v[194:197], v[124:127]
	v_mfma_f32_16x16x32_bf16 v[124:127], v[160:163], v[198:201], v[72:75]
	v_mfma_f32_16x16x32_bf16 v[72:75], v[170:173], v[194:197], v[116:119]
	v_mfma_f32_16x16x32_bf16 v[116:119], v[174:177], v[198:201], v[72:75]
	v_mfma_f32_16x16x32_bf16 v[72:75], v[60:63], v[202:205], v[112:115]
	v_mfma_f32_16x16x32_bf16 v[112:115], v[160:163], v[206:209], v[72:75]
	v_mfma_f32_16x16x32_bf16 v[72:75], v[170:173], v[202:205], v[108:111]
	v_mfma_f32_16x16x32_bf16 v[12:15], v[160:163], v[80:83], v[12:15]
	v_mfma_f32_16x16x32_bf16 v[8:11], v[174:177], v[80:83], v[8:11]
	v_mfma_f32_16x16x32_bf16 v[108:111], v[174:177], v[206:209], v[72:75]
	s_barrier
	s_mov_b32 m0, s63
	s_or_b32 s93, s92, 0x80
	s_nop 0
	ds_read_b128 v[72:75], v190 offset:49152
	ds_read_b128 v[80:83], v190 offset:50176
	ds_read_b128 v[178:181], v190 offset:51200
	ds_read_b128 v[194:197], v190 offset:52224
	ds_read_b128 v[198:201], v190 offset:53248
	ds_read_b128 v[202:205], v190 offset:54272
	ds_read_b128 v[206:209], v190 offset:55296
	ds_read_b128 v[210:213], v190 offset:56320
	buffer_load_dwordx4 v183, s[16:19], s93 offen lds
	s_mov_b32 m0, s65
	s_add_i32 s92, s92, 0x80080
	buffer_load_dwordx4 v185, s[16:19], s93 offen lds
	s_mov_b32 m0, s68
	s_nop 0
	buffer_load_dwordx4 v183, s[16:19], s92 offen lds
	s_mov_b32 m0, s69
	s_nop 0
	buffer_load_dwordx4 v185, s[16:19], s92 offen lds
	s_mov_b32 m0, s66
	s_nop 0
	buffer_load_dwordx4 v182, s[12:15], s49 offen lds
	s_mov_b32 m0, s67
	s_nop 0
	buffer_load_dwordx4 v184, s[12:15], s49 offen lds
	s_waitcnt vmcnt(8)
	s_waitcnt lgkmcnt(0)
	s_barrier
	s_waitcnt lgkmcnt(7)
	v_mfma_f32_16x16x32_bf16 v[92:95], v[40:43], v[72:75], v[104:107]
	s_waitcnt lgkmcnt(6)
	v_mfma_f32_16x16x32_bf16 v[104:107], v[44:47], v[80:83], v[92:95]
	v_mfma_f32_16x16x32_bf16 v[92:95], v[48:51], v[72:75], v[100:103]
	v_mfma_f32_16x16x32_bf16 v[100:103], v[56:59], v[80:83], v[92:95]
	s_waitcnt lgkmcnt(5)
	v_mfma_f32_16x16x32_bf16 v[92:95], v[40:43], v[178:181], v[96:99]
	s_waitcnt lgkmcnt(1)
	v_mfma_f32_16x16x32_bf16 v[16:19], v[40:43], v[206:209], v[16:19]
	v_mfma_f32_16x16x32_bf16 v[96:99], v[44:47], v[194:197], v[92:95]
	v_mfma_f32_16x16x32_bf16 v[88:91], v[48:51], v[178:181], v[88:91]
	v_mfma_f32_16x16x32_bf16 v[84:87], v[40:43], v[198:201], v[84:87]
	v_mfma_f32_16x16x32_bf16 v[76:79], v[48:51], v[198:201], v[76:79]
	s_waitcnt lgkmcnt(0)
	v_mfma_f32_16x16x32_bf16 v[92:95], v[44:47], v[210:213], v[16:19]
	v_mfma_f32_16x16x32_bf16 v[16:19], v[48:51], v[206:209], v[20:23]
	v_mfma_f32_16x16x32_bf16 v[88:91], v[56:59], v[194:197], v[88:91]
	v_mfma_f32_16x16x32_bf16 v[84:87], v[44:47], v[202:205], v[84:87]
	v_mfma_f32_16x16x32_bf16 v[76:79], v[56:59], v[202:205], v[76:79]
	v_mfma_f32_16x16x32_bf16 v[48:51], v[56:59], v[210:213], v[16:19]
	v_mfma_f32_16x16x32_bf16 v[4:7], v[60:63], v[72:75], v[4:7]
	v_mfma_f32_16x16x32_bf16 v[0:3], v[170:173], v[72:75], v[0:3]
	v_mfma_f32_16x16x32_bf16 v[16:19], v[60:63], v[178:181], v[24:27]
	v_mfma_f32_16x16x32_bf16 v[4:7], v[160:163], v[80:83], v[4:7]
	v_mfma_f32_16x16x32_bf16 v[0:3], v[174:177], v[80:83], v[0:3]
	v_mfma_f32_16x16x32_bf16 v[80:83], v[160:163], v[194:197], v[16:19]
	v_mfma_f32_16x16x32_bf16 v[16:19], v[170:173], v[178:181], v[28:31]
	v_mfma_f32_16x16x32_bf16 v[72:75], v[174:177], v[194:197], v[16:19]
	v_mfma_f32_16x16x32_bf16 v[16:19], v[60:63], v[198:201], v[68:71]
	v_mfma_f32_16x16x32_bf16 v[68:71], v[160:163], v[202:205], v[16:19]
	v_mfma_f32_16x16x32_bf16 v[16:19], v[170:173], v[198:201], v[64:67]
	v_mfma_f32_16x16x32_bf16 v[64:67], v[174:177], v[202:205], v[16:19]
	v_mfma_f32_16x16x32_bf16 v[16:19], v[60:63], v[206:209], v[32:35]
	v_mfma_f32_16x16x32_bf16 v[60:63], v[160:163], v[210:213], v[16:19]
	v_mfma_f32_16x16x32_bf16 v[16:19], v[170:173], v[206:209], v[36:39]
	v_mfma_f32_16x16x32_bf16 v[56:59], v[174:177], v[210:213], v[16:19]
	s_barrier
	s_add_i32 s48, s48, 2
	s_addk_i32 s8, 0x100
	s_addk_i32 s9, 0x100
	s_cmp_gt_u32 s48, 29
	s_cbranch_scc0 .LBB0_2037
	s_setprio 0
	s_and_b64 vcc, exec, s[28:29]
	s_cbranch_vccz .LBB0_2040
	s_barrier

; #define PG8_STAGE(bufoff, soff, voff) do { _Pragma("unroll") for (int _i = 0; _i < 2; ++_i) \
;         __builtin_amdgcn_raw_ptr_buffer_load_lds(rs_##voff, (PG8_LAS unsigned*)(lds + (bufoff) + ldsw + _i * 8192), 16, (int)(voff)[_i], (int)(soff), 0, 0); } while (0)
; #define PG8_LDA(dst, b, h) do { _Pragma("unroll") for (int m = 0; m < 4; ++m) _Pragma("unroll") for (int k = 0; k < 2; ++k) dst[m][k] = *(const PG8_LAS bf16x8*)(lds + PG8_SA(b, h) + aoff + m * 2048 + k * 1024); } while (0)
; #define PG8_LDB(dst, b, h) do { _Pragma("unroll") for (int n = 0; n < 2; ++n) _Pragma("unroll") for (int k = 0; k < 2; ++k) dst[n][k] = *(const PG8_LAS bf16x8*)(lds + PG8_SB(b, h) + boff + n * 2048 + k * 1024); } while (0)
; #define PG8_MMA(ai, bj, At, Bt) do { __builtin_amdgcn_s_setprio(1); _Pragma("unroll") for (int m = 0; m < 4; ++m) _Pragma("unroll") for (int n = 0; n < 2; ++n) _Pragma("unroll") for (int k = 0; k < 2; ++k) \
;         acc[ai][bj][m][n] = __builtin_amdgcn_mfma_f32_16x16x32_bf16(Bt[n][k], At[m][k], acc[ai][bj][m][n], 0, 0, 0); __builtin_amdgcn_s_setprio(0); } while (0)
; #define PG8_WAIT_V(n) asm volatile("s_waitcnt vmcnt(" #n ")" ::: "memory")
; #define PG8_WAIT_L(n) asm volatile("s_waitcnt lgkmcnt(" #n ")" ::: "memory")
; #define PG8_BAR __builtin_amdgcn_s_barrier()
; #define PG8_SCHED __builtin_amdgcn_sched_barrier(0)
; template <class Epi, class Sched, bool ALIGN_EPI = false, bool SP2 = false>
; __device__ __forceinline__ void gemm_phase(PG8_LAS unsigned char* lds, const Gemm g, const Sched& S, const Epi& E, const int wid  ) {
;     ...
;             PG8_LDB(B0, 0, 0); PG8_LDB(B1, 0, 1); PG8_SCHED; PG8_LDA(At, 0, 0); PG8_STAGE(PG8_SA(1, 1), a1 + hstep, voffA);
;             PG8_WAIT_V(8); PG8_WAIT_L(0); PG8_BAR; PG8_MMA(0, 0, At, B0); PG8_MMA(0, 1, At, B1); PG8_BAR; PG8_SCHED;
;     ...
; #pragma unroll
;         for (int a = 0; a < 2; ++a)
; #pragma unroll
;             for (int b = 0; b < 2; ++b)
; #pragma unroll
;                 for (int m = 0; m < 4; ++m)
; #pragma unroll
;                     for (int n = 0; n < 2; ++n) acc[a][b][m][n] = (f32x4){0.f, 0.f, 0.f, 0.f};
;         cur = nxt; cA = nA; cB = nB; ++ui;
.LBB0_2379:
	s_mul_i32 s50, s49, 0x2c0000
	s_and_b64 s[0:1], s[4:5], exec
	s_mul_i32 s51, s48, 0x2c0000
	v_mov_b32_e32 v0, 0
	s_cselect_b32 s0, s50, s16
	s_cselect_b32 s1, s51, s55
	s_add_i32 s16, s16, 0x160080
	s_addk_i32 s55, 0x100
	s_mov_b32 s58, -2
	s_waitcnt lgkmcnt(0)
	v_mov_b32_e32 v1, v0
	v_mov_b32_e32 v2, v0
	v_mov_b32_e32 v3, v0
	v_mov_b32_e32 v4, v0
	v_mov_b32_e32 v5, v0
	v_mov_b32_e32 v6, v0
	v_mov_b32_e32 v7, v0
	v_mov_b32_e32 v16, v0
	v_mov_b32_e32 v17, v0
	v_mov_b32_e32 v18, v0
	v_mov_b32_e32 v19, v0
	v_mov_b32_e32 v20, v0
	v_mov_b32_e32 v21, v0
	v_mov_b32_e32 v22, v0
	v_mov_b32_e32 v23, v0
	v_mov_b32_e32 v32, v0
	v_mov_b32_e32 v33, v0
	v_mov_b32_e32 v34, v0
	v_mov_b32_e32 v35, v0
	v_mov_b32_e32 v36, v0
	v_mov_b32_e32 v37, v0
	v_mov_b32_e32 v38, v0
	v_mov_b32_e32 v39, v0
	v_mov_b32_e32 v48, v0
	v_mov_b32_e32 v49, v0
	v_mov_b32_e32 v50, v0
	v_mov_b32_e32 v51, v0
	v_mov_b32_e32 v52, v0
	v_mov_b32_e32 v53, v0
	v_mov_b32_e32 v54, v0
	v_mov_b32_e32 v55, v0
	v_mov_b32_e32 v8, v0
	v_mov_b32_e32 v9, v0
	v_mov_b32_e32 v10, v0
	v_mov_b32_e32 v11, v0
	v_mov_b32_e32 v12, v0
	v_mov_b32_e32 v13, v0
	v_mov_b32_e32 v14, v0
	v_mov_b32_e32 v15, v0
	v_mov_b32_e32 v24, v0
	v_mov_b32_e32 v25, v0
	v_mov_b32_e32 v26, v0
	v_mov_b32_e32 v27, v0
	v_mov_b32_e32 v28, v0
	v_mov_b32_e32 v29, v0
	v_mov_b32_e32 v30, v0
	v_mov_b32_e32 v31, v0
	v_mov_b32_e32 v40, v0
	v_mov_b32_e32 v41, v0
	v_mov_b32_e32 v42, v0
	v_mov_b32_e32 v43, v0
	v_mov_b32_e32 v44, v0
	v_mov_b32_e32 v45, v0
	v_mov_b32_e32 v46, v0
	v_mov_b32_e32 v47, v0
	v_mov_b32_e32 v56, v0
	v_mov_b32_e32 v57, v0
	v_mov_b32_e32 v58, v0
	v_mov_b32_e32 v59, v0
	v_mov_b32_e32 v60, v0
	v_mov_b32_e32 v61, v0
	v_mov_b32_e32 v62, v0
	v_mov_b32_e32 v63, v0
	v_mov_b32_e32 v64, v0
	v_mov_b32_e32 v65, v0
	s_waitcnt vmcnt(15)
	v_mov_b32_e32 v66, v0
	v_mov_b32_e32 v67, v0
	v_mov_b32_e32 v68, v0
	v_mov_b32_e32 v69, v0
	v_mov_b32_e32 v70, v0
	v_mov_b32_e32 v71, v0
	v_mov_b32_e32 v80, v0
	v_mov_b32_e32 v81, v0
	v_mov_b32_e32 v82, v0
	v_mov_b32_e32 v83, v0
	v_mov_b32_e32 v84, v0
	v_mov_b32_e32 v85, v0
	v_mov_b32_e32 v86, v0
	v_mov_b32_e32 v87, v0
	v_mov_b32_e32 v96, v0
	v_mov_b32_e32 v97, v0
	v_mov_b32_e32 v98, v0
	v_mov_b32_e32 v99, v0
	v_mov_b32_e32 v100, v0
	v_mov_b32_e32 v101, v0
	v_mov_b32_e32 v102, v0
	v_mov_b32_e32 v103, v0
	v_mov_b32_e32 v112, v0
	v_mov_b32_e32 v113, v0
	v_mov_b32_e32 v114, v0
	v_mov_b32_e32 v115, v0
	v_mov_b32_e32 v116, v0
	v_mov_b32_e32 v117, v0
	v_mov_b32_e32 v118, v0
	v_mov_b32_e32 v119, v0
	v_mov_b32_e32 v72, v0
	v_mov_b32_e32 v73, v0
	v_mov_b32_e32 v74, v0
	v_mov_b32_e32 v75, v0
	v_mov_b32_e32 v76, v0
	v_mov_b32_e32 v77, v0
	v_mov_b32_e32 v78, v0
	v_mov_b32_e32 v79, v0
	v_mov_b32_e32 v88, v0
	v_mov_b32_e32 v89, v0
	v_mov_b32_e32 v90, v0
	v_mov_b32_e32 v91, v0
	v_mov_b32_e32 v92, v0
	v_mov_b32_e32 v93, v0
	v_mov_b32_e32 v94, v0
	v_mov_b32_e32 v95, v0
	v_mov_b32_e32 v104, v0
	v_mov_b32_e32 v105, v0
	v_mov_b32_e32 v106, v0
	v_mov_b32_e32 v107, v0
	v_mov_b32_e32 v108, v0
	v_mov_b32_e32 v109, v0
	v_mov_b32_e32 v110, v0
	v_mov_b32_e32 v111, v0
	v_mov_b32_e32 v120, v0
	v_mov_b32_e32 v121, v0
	v_mov_b32_e32 v122, v0
	v_mov_b32_e32 v123, v0
	v_mov_b32_e32 v124, v0
	v_mov_b32_e32 v125, v0
	v_mov_b32_e32 v126, v0
	v_mov_b32_e32 v127, v0
	v_readlane_b32 vcc_lo, v246, 6
	s_nop 1
	s_cmp_ge_u32 vcc_lo, 4
	s_cbranch_scc0 .Lprio_2380
	s_setprio 1
.Lprio_2380:
.LBB0_2380:
	ds_read_b128 v[132:135], v140
	ds_read_b128 v[146:149], v140 offset:1024
	ds_read_b128 v[150:153], v140 offset:2048
	ds_read_b128 v[154:157], v140 offset:3072
	ds_read_b128 v[158:161], v141
	ds_read_b128 v[162:165], v141 offset:1024
	ds_read_b128 v[166:169], v141 offset:2048
	ds_read_b128 v[170:173], v141 offset:3072
	s_add_i32 s14, s16, 0xffea0080
	s_cmpk_eq_i32 s58, 0x54
	s_cselect_b32 s61, s0, s14
	s_cselect_b32 s60, s1, s55
	s_or_b32 s59, s61, 0x80
	s_mov_b32 m0, s45
	ds_read_b128 v[174:177], v142
	ds_read_b128 v[178:181], v142 offset:1024
	ds_read_b128 v[182:185], v142 offset:2048
	ds_read_b128 v[186:189], v142 offset:3072
	ds_read_b128 v[190:193], v142 offset:4096
	ds_read_b128 v[194:197], v142 offset:5120
	ds_read_b128 v[198:201], v142 offset:6144
	ds_read_b128 v[202:205], v142 offset:7168
	buffer_load_dwordx4 v136, s[8:11], s16 offen lds
	s_mov_b32 m0, s46
	s_nop 0
	buffer_load_dwordx4 v138, s[8:11], s16 offen lds
	s_waitcnt vmcnt(8)
	s_waitcnt lgkmcnt(0)
	s_barrier
	s_waitcnt lgkmcnt(7)
	v_mfma_f32_16x16x32_bf16 v[124:127], v[132:135], v[174:177], v[124:127]
	v_mfma_f32_16x16x32_bf16 v[120:123], v[150:153], v[174:177], v[120:123]
	s_waitcnt lgkmcnt(5)
	v_mfma_f32_16x16x32_bf16 v[108:111], v[132:135], v[182:185], v[108:111]
	v_mfma_f32_16x16x32_bf16 v[104:107], v[150:153], v[182:185], v[104:107]
	s_waitcnt lgkmcnt(3)
	v_mfma_f32_16x16x32_bf16 v[92:95], v[132:135], v[190:193], v[92:95]
	v_mfma_f32_16x16x32_bf16 v[88:91], v[150:153], v[190:193], v[88:91]
	s_waitcnt lgkmcnt(1)
	v_mfma_f32_16x16x32_bf16 v[76:79], v[132:135], v[198:201], v[76:79]
	v_mfma_f32_16x16x32_bf16 v[72:75], v[150:153], v[198:201], v[72:75]
	v_mfma_f32_16x16x32_bf16 v[124:127], v[146:149], v[178:181], v[124:127]
	v_mfma_f32_16x16x32_bf16 v[120:123], v[154:157], v[178:181], v[120:123]
	v_mfma_f32_16x16x32_bf16 v[108:111], v[146:149], v[186:189], v[108:111]
	v_mfma_f32_16x16x32_bf16 v[104:107], v[154:157], v[186:189], v[104:107]
	v_mfma_f32_16x16x32_bf16 v[92:95], v[146:149], v[194:197], v[92:95]
	v_mfma_f32_16x16x32_bf16 v[88:91], v[154:157], v[194:197], v[88:91]
	s_waitcnt lgkmcnt(0)
	v_mfma_f32_16x16x32_bf16 v[76:79], v[146:149], v[202:205], v[76:79]
	v_mfma_f32_16x16x32_bf16 v[72:75], v[154:157], v[202:205], v[72:75]
	v_mfma_f32_16x16x32_bf16 v[116:119], v[158:161], v[174:177], v[116:119]
	v_mfma_f32_16x16x32_bf16 v[112:115], v[166:169], v[174:177], v[112:115]
	v_mfma_f32_16x16x32_bf16 v[100:103], v[158:161], v[182:185], v[100:103]
	v_mfma_f32_16x16x32_bf16 v[96:99], v[166:169], v[182:185], v[96:99]
	v_mfma_f32_16x16x32_bf16 v[84:87], v[158:161], v[190:193], v[84:87]
	v_mfma_f32_16x16x32_bf16 v[80:83], v[166:169], v[190:193], v[80:83]
	v_mfma_f32_16x16x32_bf16 v[68:71], v[158:161], v[198:201], v[68:71]
	v_mfma_f32_16x16x32_bf16 v[64:67], v[166:169], v[198:201], v[64:67]
	v_mfma_f32_16x16x32_bf16 v[116:119], v[162:165], v[178:181], v[116:119]
	v_mfma_f32_16x16x32_bf16 v[112:115], v[170:173], v[178:181], v[112:115]
	v_mfma_f32_16x16x32_bf16 v[100:103], v[162:165], v[186:189], v[100:103]
	v_mfma_f32_16x16x32_bf16 v[96:99], v[170:173], v[186:189], v[96:99]
	v_mfma_f32_16x16x32_bf16 v[84:87], v[162:165], v[194:197], v[84:87]
	v_mfma_f32_16x16x32_bf16 v[80:83], v[170:173], v[194:197], v[80:83]
	v_mfma_f32_16x16x32_bf16 v[68:71], v[162:165], v[202:205], v[68:71]
	v_mfma_f32_16x16x32_bf16 v[64:67], v[170:173], v[202:205], v[64:67]
	s_barrier
; #define PG8_STAGE(bufoff, soff, voff) do { _Pragma("unroll") for (int _i = 0; _i < 2; ++_i) \
;         __builtin_amdgcn_raw_ptr_buffer_load_lds(rs_##voff, (PG8_LAS unsigned*)(lds + (bufoff) + ldsw + _i * 8192), 16, (int)(voff)[_i], (int)(soff), 0, 0); } while (0)
; #define PG8_LDA(dst, b, h) do { _Pragma("unroll") for (int m = 0; m < 4; ++m) _Pragma("unroll") for (int k = 0; k < 2; ++k) dst[m][k] = *(const PG8_LAS bf16x8*)(lds + PG8_SA(b, h) + aoff + m * 2048 + k * 1024); } while (0)
; #define PG8_LDB(dst, b, h) do { _Pragma("unroll") for (int n = 0; n < 2; ++n) _Pragma("unroll") for (int k = 0; k < 2; ++k) dst[n][k] = *(const PG8_LAS bf16x8*)(lds + PG8_SB(b, h) + boff + n * 2048 + k * 1024); } while (0)
; #define PG8_MMA(ai, bj, At, Bt) do { __builtin_amdgcn_s_setprio(1); _Pragma("unroll") for (int m = 0; m < 4; ++m) _Pragma("unroll") for (int n = 0; n < 2; ++n) _Pragma("unroll") for (int k = 0; k < 2; ++k) \
;         acc[ai][bj][m][n] = __builtin_amdgcn_mfma_f32_16x16x32_bf16(Bt[n][k], At[m][k], acc[ai][bj][m][n], 0, 0, 0); __builtin_amdgcn_s_setprio(0); } while (0)
; #define PG8_WAIT_V(n) asm volatile("s_waitcnt vmcnt(" #n ")" ::: "memory")
; #define PG8_WAIT_L(n) asm volatile("s_waitcnt lgkmcnt(" #n ")" ::: "memory")
; #define PG8_BAR __builtin_amdgcn_s_barrier()
; #define PG8_SCHED __builtin_amdgcn_sched_barrier(0)
; template <class Epi, class Sched, bool ALIGN_EPI = false, bool SP2 = false>
; __device__ __forceinline__ void gemm_phase(PG8_LAS unsigned char* lds, const Gemm g, const Sched& S, const Epi& E, const int wid  ) {
;     ...
;             PG8_WAIT_V(8); PG8_WAIT_L(0); PG8_BAR; PG8_MMA(0, 0, At, B0); PG8_MMA(0, 1, At, B1); PG8_BAR; PG8_SCHED;
;             PG8_LDA(At, 0, 1); PG8_STAGE(PG8_SB(0, 0), b2, voffB); PG8_STAGE(PG8_SB(0, 1), b2 + hstep, voffB); PG8_STAGE(PG8_SA(0, 0), a2, voffA);
;             PG8_WAIT_V(8); PG8_WAIT_L(0); PG8_BAR; PG8_MMA(1, 0, At, B0); PG8_MMA(1, 1, At, B1); PG8_BAR; PG8_SCHED;
;             PG8_LDB(B0, 1, 0); PG8_LDB(B1, 1, 1); PG8_SCHED; PG8_LDA(At, 1, 0); PG8_STAGE(PG8_SA(0, 1), a2 + hstep, voffA);
;             PG8_WAIT_V(8); PG8_WAIT_L(0); PG8_BAR; PG8_MMA(0, 0, At, B0); PG8_MMA(0, 1, At, B1); PG8_BAR; PG8_SCHED;
	s_mov_b32 m0, s28
	s_mov_b32 s14, s10
	s_mov_b32 s15, s11
	ds_read_b128 v[174:177], v142 offset:16384
	ds_read_b128 v[178:181], v142 offset:17408
	ds_read_b128 v[182:185], v142 offset:18432
	ds_read_b128 v[186:189], v142 offset:19456
	ds_read_b128 v[190:193], v142 offset:20480
	ds_read_b128 v[194:197], v142 offset:21504
	ds_read_b128 v[198:201], v142 offset:22528
	ds_read_b128 v[202:205], v142 offset:23552
	buffer_load_dwordx4 v137, s[12:15], s60 offen lds
	s_mov_b32 m0, s29
	s_add_i32 s62, s60, 0x160000
	buffer_load_dwordx4 v139, s[12:15], s60 offen lds
	s_mov_b32 m0, s30
	s_nop 0
	buffer_load_dwordx4 v137, s[12:15], s62 offen lds
	s_mov_b32 m0, s31
	s_nop 0
	buffer_load_dwordx4 v139, s[12:15], s62 offen lds
	s_mov_b32 m0, s27
	s_nop 0
	buffer_load_dwordx4 v136, s[8:11], s61 offen lds
	s_mov_b32 m0, s33
	s_nop 0
	buffer_load_dwordx4 v138, s[8:11], s61 offen lds
	s_waitcnt vmcnt(8)
	s_waitcnt lgkmcnt(0)
	s_barrier
	s_waitcnt lgkmcnt(7)
	v_mfma_f32_16x16x32_bf16 v[60:63], v[132:135], v[174:177], v[60:63]
	v_mfma_f32_16x16x32_bf16 v[56:59], v[150:153], v[174:177], v[56:59]
	s_waitcnt lgkmcnt(5)
	v_mfma_f32_16x16x32_bf16 v[44:47], v[132:135], v[182:185], v[44:47]
	v_mfma_f32_16x16x32_bf16 v[40:43], v[150:153], v[182:185], v[40:43]
	s_waitcnt lgkmcnt(3)
	v_mfma_f32_16x16x32_bf16 v[28:31], v[132:135], v[190:193], v[28:31]
	v_mfma_f32_16x16x32_bf16 v[24:27], v[150:153], v[190:193], v[24:27]
	s_waitcnt lgkmcnt(1)
	v_mfma_f32_16x16x32_bf16 v[12:15], v[132:135], v[198:201], v[12:15]
	v_mfma_f32_16x16x32_bf16 v[8:11], v[150:153], v[198:201], v[8:11]
	v_mfma_f32_16x16x32_bf16 v[60:63], v[146:149], v[178:181], v[60:63]
	v_mfma_f32_16x16x32_bf16 v[56:59], v[154:157], v[178:181], v[56:59]
	v_mfma_f32_16x16x32_bf16 v[44:47], v[146:149], v[186:189], v[44:47]
	v_mfma_f32_16x16x32_bf16 v[40:43], v[154:157], v[186:189], v[40:43]
	v_mfma_f32_16x16x32_bf16 v[28:31], v[146:149], v[194:197], v[28:31]
	v_mfma_f32_16x16x32_bf16 v[24:27], v[154:157], v[194:197], v[24:27]
	s_waitcnt lgkmcnt(0)
	v_mfma_f32_16x16x32_bf16 v[12:15], v[146:149], v[202:205], v[12:15]
	v_mfma_f32_16x16x32_bf16 v[8:11], v[154:157], v[202:205], v[8:11]
	v_mfma_f32_16x16x32_bf16 v[52:55], v[158:161], v[174:177], v[52:55]
	v_mfma_f32_16x16x32_bf16 v[48:51], v[166:169], v[174:177], v[48:51]
	v_mfma_f32_16x16x32_bf16 v[36:39], v[158:161], v[182:185], v[36:39]
	v_mfma_f32_16x16x32_bf16 v[32:35], v[166:169], v[182:185], v[32:35]
	v_mfma_f32_16x16x32_bf16 v[20:23], v[158:161], v[190:193], v[20:23]
	v_mfma_f32_16x16x32_bf16 v[16:19], v[166:169], v[190:193], v[16:19]
	v_mfma_f32_16x16x32_bf16 v[4:7], v[158:161], v[198:201], v[4:7]
	v_mfma_f32_16x16x32_bf16 v[0:3], v[166:169], v[198:201], v[0:3]
	v_mfma_f32_16x16x32_bf16 v[52:55], v[162:165], v[178:181], v[52:55]
	v_mfma_f32_16x16x32_bf16 v[48:51], v[170:173], v[178:181], v[48:51]
	v_mfma_f32_16x16x32_bf16 v[36:39], v[162:165], v[186:189], v[36:39]
	v_mfma_f32_16x16x32_bf16 v[32:35], v[170:173], v[186:189], v[32:35]
	v_mfma_f32_16x16x32_bf16 v[20:23], v[162:165], v[194:197], v[20:23]
	v_mfma_f32_16x16x32_bf16 v[16:19], v[170:173], v[194:197], v[16:19]
	v_mfma_f32_16x16x32_bf16 v[4:7], v[162:165], v[202:205], v[4:7]
	v_mfma_f32_16x16x32_bf16 v[0:3], v[170:173], v[202:205], v[0:3]
	s_barrier
	ds_read_b128 v[132:135], v143
	ds_read_b128 v[146:149], v143 offset:1024
	ds_read_b128 v[150:153], v143 offset:2048
	ds_read_b128 v[154:157], v143 offset:3072
	ds_read_b128 v[158:161], v144
	ds_read_b128 v[162:165], v144 offset:1024
	ds_read_b128 v[166:169], v144 offset:2048
	ds_read_b128 v[170:173], v144 offset:3072
	s_add_i32 s61, s61, 0x160000
	s_mov_b32 m0, s34
	ds_read_b128 v[174:177], v142 offset:32768
	ds_read_b128 v[178:181], v142 offset:33792
	ds_read_b128 v[182:185], v142 offset:34816
	ds_read_b128 v[186:189], v142 offset:35840
	ds_read_b128 v[190:193], v142 offset:36864
	ds_read_b128 v[194:197], v142 offset:37888
	ds_read_b128 v[198:201], v142 offset:38912
	ds_read_b128 v[202:205], v142 offset:39936
	buffer_load_dwordx4 v136, s[8:11], s61 offen lds
	s_mov_b32 m0, s35
	s_nop 0
	buffer_load_dwordx4 v138, s[8:11], s61 offen lds
	s_waitcnt vmcnt(8)
	s_waitcnt lgkmcnt(0)
	s_barrier
; #define PG8_STAGE(bufoff, soff, voff) do { _Pragma("unroll") for (int _i = 0; _i < 2; ++_i) \
;         __builtin_amdgcn_raw_ptr_buffer_load_lds(rs_##voff, (PG8_LAS unsigned*)(lds + (bufoff) + ldsw + _i * 8192), 16, (int)(voff)[_i], (int)(soff), 0, 0); } while (0)
; #define PG8_LDA(dst, b, h) do { _Pragma("unroll") for (int m = 0; m < 4; ++m) _Pragma("unroll") for (int k = 0; k < 2; ++k) dst[m][k] = *(const PG8_LAS bf16x8*)(lds + PG8_SA(b, h) + aoff + m * 2048 + k * 1024); } while (0)
; #define PG8_LDB(dst, b, h) do { _Pragma("unroll") for (int n = 0; n < 2; ++n) _Pragma("unroll") for (int k = 0; k < 2; ++k) dst[n][k] = *(const PG8_LAS bf16x8*)(lds + PG8_SB(b, h) + boff + n * 2048 + k * 1024); } while (0)
; template <class Epi, class Sched, bool ALIGN_EPI = false, bool SP2 = false>
; __device__ __forceinline__ void gemm_phase(PG8_LAS unsigned char* lds, const Gemm g, const Sched& S, const Epi& E, const int wid  ) {
;     ...
;         for (int t = 0; t < nt; t += 2) {
;             const bool last = (t == nt - 2);
;             const unsigned a1 = cA + (unsigned)(t + 1) * kstep;
;             const unsigned a2 = last ? nA : cA + (unsigned)(t + 2) * kstep, b2 = last ? nB : cB + (unsigned)(t + 2) * kstep;
;             const unsigned a3 = a2 + kstep, b3 = b2 + kstep;
;             if (last && has_next) S.a_ready(nxt);
;             if constexpr (SP2) {
;             PG8_LDB(B0, 0, 0); PG8_LDB(B1, 0, 1); PG8_SCHED; PG8_LDA(At, 0, 0); PG8_STAGE(PG8_SA(1, 1), a1 + hstep, voffA);
;             PG8_WAIT_V(8); PG8_WAIT_L(0); PG8_BAR; PG8_MMA(0, 0, At, B0); PG8_MMA(0, 1, At, B1); PG8_BAR; PG8_SCHED;
;             PG8_LDA(At, 0, 1); PG8_STAGE(PG8_SB(0, 0), b2, voffB); PG8_STAGE(PG8_SB(0, 1), b2 + hstep, voffB); PG8_STAGE(PG8_SA(0, 0), a2, voffA);
;             PG8_WAIT_V(8); PG8_WAIT_L(0); PG8_BAR; PG8_MMA(1, 0, At, B0); PG8_MMA(1, 1, At, B1); PG8_BAR; PG8_SCHED;
;             PG8_LDB(B0, 1, 0); PG8_LDB(B1, 1, 1); PG8_SCHED; PG8_LDA(At, 1, 0); PG8_STAGE(PG8_SA(0, 1), a2 + hstep, voffA);
;             PG8_WAIT_V(8); PG8_WAIT_L(0); PG8_BAR; PG8_MMA(0, 0, At, B0); PG8_MMA(0, 1, At, B1); PG8_BAR; PG8_SCHED;
;             PG8_LDA(At, 1, 1); PG8_STAGE(PG8_SB(1, 0), b3, voffB); PG8_STAGE(PG8_SB(1, 1), b3 + hstep, voffB); PG8_STAGE(PG8_SA(1, 0), a3, voffA);
;             PG8_WAIT_V(8); PG8_WAIT_L(0); PG8_BAR; PG8_MMA(1, 0, At, B0); PG8_MMA(1, 1, At, B1); PG8_BAR; PG8_SCHED;
	s_waitcnt lgkmcnt(7)
	v_mfma_f32_16x16x32_bf16 v[124:127], v[132:135], v[174:177], v[124:127]
	v_mfma_f32_16x16x32_bf16 v[120:123], v[150:153], v[174:177], v[120:123]
	s_waitcnt lgkmcnt(5)
	v_mfma_f32_16x16x32_bf16 v[108:111], v[132:135], v[182:185], v[108:111]
	v_mfma_f32_16x16x32_bf16 v[104:107], v[150:153], v[182:185], v[104:107]
	s_waitcnt lgkmcnt(3)
	v_mfma_f32_16x16x32_bf16 v[92:95], v[132:135], v[190:193], v[92:95]
	v_mfma_f32_16x16x32_bf16 v[88:91], v[150:153], v[190:193], v[88:91]
	s_waitcnt lgkmcnt(1)
	v_mfma_f32_16x16x32_bf16 v[76:79], v[132:135], v[198:201], v[76:79]
	v_mfma_f32_16x16x32_bf16 v[72:75], v[150:153], v[198:201], v[72:75]
	v_mfma_f32_16x16x32_bf16 v[124:127], v[146:149], v[178:181], v[124:127]
	v_mfma_f32_16x16x32_bf16 v[120:123], v[154:157], v[178:181], v[120:123]
	v_mfma_f32_16x16x32_bf16 v[108:111], v[146:149], v[186:189], v[108:111]
	v_mfma_f32_16x16x32_bf16 v[104:107], v[154:157], v[186:189], v[104:107]
	v_mfma_f32_16x16x32_bf16 v[92:95], v[146:149], v[194:197], v[92:95]
	v_mfma_f32_16x16x32_bf16 v[88:91], v[154:157], v[194:197], v[88:91]
	s_waitcnt lgkmcnt(0)
	v_mfma_f32_16x16x32_bf16 v[76:79], v[146:149], v[202:205], v[76:79]
	v_mfma_f32_16x16x32_bf16 v[72:75], v[154:157], v[202:205], v[72:75]
	v_mfma_f32_16x16x32_bf16 v[116:119], v[158:161], v[174:177], v[116:119]
	v_mfma_f32_16x16x32_bf16 v[112:115], v[166:169], v[174:177], v[112:115]
	v_mfma_f32_16x16x32_bf16 v[100:103], v[158:161], v[182:185], v[100:103]
	v_mfma_f32_16x16x32_bf16 v[96:99], v[166:169], v[182:185], v[96:99]
	v_mfma_f32_16x16x32_bf16 v[84:87], v[158:161], v[190:193], v[84:87]
	v_mfma_f32_16x16x32_bf16 v[80:83], v[166:169], v[190:193], v[80:83]
	v_mfma_f32_16x16x32_bf16 v[68:71], v[158:161], v[198:201], v[68:71]
	v_mfma_f32_16x16x32_bf16 v[64:67], v[166:169], v[198:201], v[64:67]
	v_mfma_f32_16x16x32_bf16 v[116:119], v[162:165], v[178:181], v[116:119]
	v_mfma_f32_16x16x32_bf16 v[112:115], v[170:173], v[178:181], v[112:115]
	v_mfma_f32_16x16x32_bf16 v[100:103], v[162:165], v[186:189], v[100:103]
	v_mfma_f32_16x16x32_bf16 v[96:99], v[170:173], v[186:189], v[96:99]
	v_mfma_f32_16x16x32_bf16 v[84:87], v[162:165], v[194:197], v[84:87]
	v_mfma_f32_16x16x32_bf16 v[80:83], v[170:173], v[194:197], v[80:83]
	v_mfma_f32_16x16x32_bf16 v[68:71], v[162:165], v[202:205], v[68:71]
	v_mfma_f32_16x16x32_bf16 v[64:67], v[170:173], v[202:205], v[64:67]
	s_barrier
	s_mov_b32 m0, s36
	s_or_b32 s61, s60, 0x80
	ds_read_b128 v[174:177], v142 offset:49152
	ds_read_b128 v[178:181], v142 offset:50176
	ds_read_b128 v[182:185], v142 offset:51200
	ds_read_b128 v[186:189], v142 offset:52224
	ds_read_b128 v[190:193], v142 offset:53248
	ds_read_b128 v[194:197], v142 offset:54272
	ds_read_b128 v[198:201], v142 offset:55296
	ds_read_b128 v[202:205], v142 offset:56320
	buffer_load_dwordx4 v137, s[12:15], s61 offen lds
	s_mov_b32 m0, s37
	s_add_i32 s60, s60, 0x160080
	buffer_load_dwordx4 v139, s[12:15], s61 offen lds
	s_mov_b32 m0, s40
	s_nop 0
	buffer_load_dwordx4 v137, s[12:15], s60 offen lds
	s_mov_b32 m0, s41
	s_nop 0
	buffer_load_dwordx4 v139, s[12:15], s60 offen lds
	s_mov_b32 m0, s38
	s_nop 0
	buffer_load_dwordx4 v136, s[8:11], s59 offen lds
	s_mov_b32 m0, s39
	s_nop 0
	buffer_load_dwordx4 v138, s[8:11], s59 offen lds
	s_waitcnt vmcnt(8)
	s_waitcnt lgkmcnt(0)
	s_barrier
	s_waitcnt lgkmcnt(7)
	v_mfma_f32_16x16x32_bf16 v[60:63], v[132:135], v[174:177], v[60:63]
	v_mfma_f32_16x16x32_bf16 v[56:59], v[150:153], v[174:177], v[56:59]
	s_waitcnt lgkmcnt(5)
	v_mfma_f32_16x16x32_bf16 v[44:47], v[132:135], v[182:185], v[44:47]
	v_mfma_f32_16x16x32_bf16 v[40:43], v[150:153], v[182:185], v[40:43]
	s_waitcnt lgkmcnt(3)
	v_mfma_f32_16x16x32_bf16 v[28:31], v[132:135], v[190:193], v[28:31]
	v_mfma_f32_16x16x32_bf16 v[24:27], v[150:153], v[190:193], v[24:27]
	s_waitcnt lgkmcnt(1)
	v_mfma_f32_16x16x32_bf16 v[12:15], v[132:135], v[198:201], v[12:15]
	v_mfma_f32_16x16x32_bf16 v[8:11], v[150:153], v[198:201], v[8:11]
	v_mfma_f32_16x16x32_bf16 v[60:63], v[146:149], v[178:181], v[60:63]
	v_mfma_f32_16x16x32_bf16 v[56:59], v[154:157], v[178:181], v[56:59]
	v_mfma_f32_16x16x32_bf16 v[44:47], v[146:149], v[186:189], v[44:47]
	v_mfma_f32_16x16x32_bf16 v[40:43], v[154:157], v[186:189], v[40:43]
	v_mfma_f32_16x16x32_bf16 v[28:31], v[146:149], v[194:197], v[28:31]
	v_mfma_f32_16x16x32_bf16 v[24:27], v[154:157], v[194:197], v[24:27]
	s_waitcnt lgkmcnt(0)
	v_mfma_f32_16x16x32_bf16 v[12:15], v[146:149], v[202:205], v[12:15]
	v_mfma_f32_16x16x32_bf16 v[8:11], v[154:157], v[202:205], v[8:11]
	v_mfma_f32_16x16x32_bf16 v[52:55], v[158:161], v[174:177], v[52:55]
	v_mfma_f32_16x16x32_bf16 v[48:51], v[166:169], v[174:177], v[48:51]
	v_mfma_f32_16x16x32_bf16 v[36:39], v[158:161], v[182:185], v[36:39]
	v_mfma_f32_16x16x32_bf16 v[32:35], v[166:169], v[182:185], v[32:35]
	v_mfma_f32_16x16x32_bf16 v[20:23], v[158:161], v[190:193], v[20:23]
	v_mfma_f32_16x16x32_bf16 v[16:19], v[166:169], v[190:193], v[16:19]
	v_mfma_f32_16x16x32_bf16 v[4:7], v[158:161], v[198:201], v[4:7]
	v_mfma_f32_16x16x32_bf16 v[0:3], v[166:169], v[198:201], v[0:3]
	v_mfma_f32_16x16x32_bf16 v[52:55], v[162:165], v[178:181], v[52:55]
	v_mfma_f32_16x16x32_bf16 v[48:51], v[170:173], v[178:181], v[48:51]
	v_mfma_f32_16x16x32_bf16 v[36:39], v[162:165], v[186:189], v[36:39]
	v_mfma_f32_16x16x32_bf16 v[32:35], v[170:173], v[186:189], v[32:35]
	v_mfma_f32_16x16x32_bf16 v[20:23], v[162:165], v[194:197], v[20:23]
	v_mfma_f32_16x16x32_bf16 v[16:19], v[170:173], v[194:197], v[16:19]
	v_mfma_f32_16x16x32_bf16 v[4:7], v[162:165], v[202:205], v[4:7]
	v_mfma_f32_16x16x32_bf16 v[0:3], v[170:173], v[202:205], v[0:3]
	s_barrier
	s_add_i32 s58, s58, 2
	s_addk_i32 s16, 0x100
	s_addk_i32 s55, 0x100
	s_cmpk_gt_u32 s58, 0x55
	s_cbranch_scc0 .LBB0_2380
	s_setprio 0
	s_and_b64 vcc, exec, s[24:25]
	s_cbranch_vccz .LBB0_2383
	s_barrier

; #define PG8_STAGE(bufoff, soff, voff) do { _Pragma("unroll") for (int _i = 0; _i < 2; ++_i) \
;         __builtin_amdgcn_raw_ptr_buffer_load_lds(rs_##voff, (PG8_LAS unsigned*)(lds + (bufoff) + ldsw + _i * 8192), 16, (int)(voff)[_i], (int)(soff), 0, 0); } while (0)
; #define PG8_LDA(dst, b, h) do { _Pragma("unroll") for (int m = 0; m < 4; ++m) _Pragma("unroll") for (int k = 0; k < 2; ++k) dst[m][k] = *(const PG8_LAS bf16x8*)(lds + PG8_SA(b, h) + aoff + m * 2048 + k * 1024); } while (0)
; #define PG8_LDB(dst, b, h) do { _Pragma("unroll") for (int n = 0; n < 2; ++n) _Pragma("unroll") for (int k = 0; k < 2; ++k) dst[n][k] = *(const PG8_LAS bf16x8*)(lds + PG8_SB(b, h) + boff + n * 2048 + k * 1024); } while (0)
; #define PG8_MMA(ai, bj, At, Bt) do { __builtin_amdgcn_s_setprio(1); _Pragma("unroll") for (int m = 0; m < 4; ++m) _Pragma("unroll") for (int n = 0; n < 2; ++n) _Pragma("unroll") for (int k = 0; k < 2; ++k) \
;         acc[ai][bj][m][n] = __builtin_amdgcn_mfma_f32_16x16x32_bf16(Bt[n][k], At[m][k], acc[ai][bj][m][n], 0, 0, 0); __builtin_amdgcn_s_setprio(0); } while (0)
; #define PG8_WAIT_V(n) asm volatile("s_waitcnt vmcnt(" #n ")" ::: "memory")
; #define PG8_BAR __builtin_amdgcn_s_barrier()
; template <class Epi, class Sched, bool ALIGN_EPI = false, bool SP2 = false>
; __device__ __forceinline__ void gemm_phase(PG8_LAS unsigned char* lds, const Gemm g, const Sched& S, const Epi& E, const int wid  ) {
;     ...
;         for (int t = 0; t < nt; t += 2) {
;             const bool last = (t == nt - 2);
;             const unsigned a1 = cA + (unsigned)(t + 1) * kstep;
;             const unsigned a2 = last ? nA : cA + (unsigned)(t + 2) * kstep, b2 = last ? nB : cB + (unsigned)(t + 2) * kstep;
;             const unsigned a3 = a2 + kstep, b3 = b2 + kstep;
;             if (last && has_next) S.a_ready(nxt);
;             if constexpr (SP2) {
;             PG8_LDB(B0, 0, 0); PG8_LDB(B1, 0, 1); PG8_SCHED; PG8_LDA(At, 0, 0); PG8_STAGE(PG8_SA(1, 1), a1 + hstep, voffA);
;             PG8_WAIT_V(8); PG8_WAIT_L(0); PG8_BAR; PG8_MMA(0, 0, At, B0); PG8_MMA(0, 1, At, B1); PG8_BAR; PG8_SCHED;
;             PG8_LDA(At, 0, 1); PG8_STAGE(PG8_SB(0, 0), b2, voffB); PG8_STAGE(PG8_SB(0, 1), b2 + hstep, voffB); PG8_STAGE(PG8_SA(0, 0), a2, voffA);
;             PG8_WAIT_V(8); PG8_WAIT_L(0); PG8_BAR; PG8_MMA(1, 0, At, B0); PG8_MMA(1, 1, At, B1); PG8_BAR; PG8_SCHED;
.Lprio_2575:
.LBB0_2575:
	ds_read_b128 v[132:135], v144
	ds_read_b128 v[150:153], v144 offset:1024
	ds_read_b128 v[154:157], v144 offset:2048
	ds_read_b128 v[158:161], v144 offset:3072
	ds_read_b128 v[162:165], v145
	ds_read_b128 v[166:169], v145 offset:1024
	ds_read_b128 v[170:173], v145 offset:2048
	ds_read_b128 v[174:177], v145 offset:3072
	s_add_i32 s14, s65, 0xfff80080
	s_cmp_eq_u32 s67, 28
	s_cselect_b32 s70, s63, s14
	s_cselect_b32 s69, s64, s66
	s_or_b32 s68, s70, 0x80
	s_mov_b32 m0, s47
	ds_read_b128 v[178:181], v146
	ds_read_b128 v[182:185], v146 offset:1024
	ds_read_b128 v[186:189], v146 offset:2048
	ds_read_b128 v[190:193], v146 offset:3072
	ds_read_b128 v[194:197], v146 offset:4096
	ds_read_b128 v[198:201], v146 offset:5120
	ds_read_b128 v[202:205], v146 offset:6144
	ds_read_b128 v[206:209], v146 offset:7168
	buffer_load_dwordx4 v138, s[8:11], s65 offen lds
	s_mov_b32 m0, s48
	s_nop 0
	buffer_load_dwordx4 v140, s[8:11], s65 offen lds
	s_waitcnt vmcnt(8)
	s_waitcnt lgkmcnt(0)
	s_barrier
	s_waitcnt lgkmcnt(7)
	v_mfma_f32_16x16x32_bf16 v[124:127], v[132:135], v[178:181], v[124:127]
	v_mfma_f32_16x16x32_bf16 v[120:123], v[154:157], v[178:181], v[120:123]
	s_waitcnt lgkmcnt(5)
	v_mfma_f32_16x16x32_bf16 v[112:115], v[132:135], v[186:189], v[112:115]
	v_mfma_f32_16x16x32_bf16 v[104:107], v[154:157], v[186:189], v[104:107]
	s_waitcnt lgkmcnt(3)
	v_mfma_f32_16x16x32_bf16 v[96:99], v[132:135], v[194:197], v[96:99]
	v_mfma_f32_16x16x32_bf16 v[88:91], v[154:157], v[194:197], v[88:91]
	s_waitcnt lgkmcnt(1)
	v_mfma_f32_16x16x32_bf16 v[80:83], v[132:135], v[202:205], v[80:83]
	v_mfma_f32_16x16x32_bf16 v[72:75], v[154:157], v[202:205], v[72:75]
	v_mfma_f32_16x16x32_bf16 v[124:127], v[150:153], v[182:185], v[124:127]
	v_mfma_f32_16x16x32_bf16 v[120:123], v[158:161], v[182:185], v[120:123]
	v_mfma_f32_16x16x32_bf16 v[112:115], v[150:153], v[190:193], v[112:115]
	v_mfma_f32_16x16x32_bf16 v[104:107], v[158:161], v[190:193], v[104:107]
	v_mfma_f32_16x16x32_bf16 v[96:99], v[150:153], v[198:201], v[96:99]
	v_mfma_f32_16x16x32_bf16 v[88:91], v[158:161], v[198:201], v[88:91]
	s_waitcnt lgkmcnt(0)
	v_mfma_f32_16x16x32_bf16 v[80:83], v[150:153], v[206:209], v[80:83]
	v_mfma_f32_16x16x32_bf16 v[72:75], v[158:161], v[206:209], v[72:75]
	v_mfma_f32_16x16x32_bf16 v[116:119], v[162:165], v[178:181], v[116:119]
	v_mfma_f32_16x16x32_bf16 v[108:111], v[170:173], v[178:181], v[108:111]
	v_mfma_f32_16x16x32_bf16 v[100:103], v[162:165], v[186:189], v[100:103]
	v_mfma_f32_16x16x32_bf16 v[92:95], v[170:173], v[186:189], v[92:95]
	v_mfma_f32_16x16x32_bf16 v[84:87], v[162:165], v[194:197], v[84:87]
	v_mfma_f32_16x16x32_bf16 v[76:79], v[170:173], v[194:197], v[76:79]
	v_mfma_f32_16x16x32_bf16 v[68:71], v[162:165], v[202:205], v[68:71]
	v_mfma_f32_16x16x32_bf16 v[64:67], v[170:173], v[202:205], v[64:67]
	v_mfma_f32_16x16x32_bf16 v[116:119], v[166:169], v[182:185], v[116:119]
	v_mfma_f32_16x16x32_bf16 v[108:111], v[174:177], v[182:185], v[108:111]
	v_mfma_f32_16x16x32_bf16 v[100:103], v[166:169], v[190:193], v[100:103]
	v_mfma_f32_16x16x32_bf16 v[92:95], v[174:177], v[190:193], v[92:95]
	v_mfma_f32_16x16x32_bf16 v[84:87], v[166:169], v[198:201], v[84:87]
	v_mfma_f32_16x16x32_bf16 v[76:79], v[174:177], v[198:201], v[76:79]
	v_mfma_f32_16x16x32_bf16 v[68:71], v[166:169], v[206:209], v[68:71]
	v_mfma_f32_16x16x32_bf16 v[64:67], v[174:177], v[206:209], v[64:67]
	s_barrier
	s_mov_b32 m0, s30
	s_mov_b32 s14, s10
	s_mov_b32 s15, s11
	ds_read_b128 v[178:181], v146 offset:16384
	ds_read_b128 v[182:185], v146 offset:17408
	ds_read_b128 v[186:189], v146 offset:18432
	ds_read_b128 v[190:193], v146 offset:19456
	ds_read_b128 v[194:197], v146 offset:20480
	ds_read_b128 v[198:201], v146 offset:21504
	ds_read_b128 v[202:205], v146 offset:22528
	ds_read_b128 v[206:209], v146 offset:23552
	buffer_load_dwordx4 v139, s[12:15], s69 offen lds
	s_mov_b32 m0, s31
	s_add_i32 s71, s69, 0x80000
	buffer_load_dwordx4 v141, s[12:15], s69 offen lds
	s_mov_b32 m0, s33
	s_nop 0
	buffer_load_dwordx4 v139, s[12:15], s71 offen lds
	s_mov_b32 m0, s34
	s_nop 0
	buffer_load_dwordx4 v141, s[12:15], s71 offen lds
	s_mov_b32 m0, s29
	s_nop 0
	buffer_load_dwordx4 v138, s[8:11], s70 offen lds
	s_mov_b32 m0, s35
	s_nop 0
	buffer_load_dwordx4 v140, s[8:11], s70 offen lds
	s_waitcnt vmcnt(8)
	s_waitcnt lgkmcnt(0)
	s_barrier
	s_waitcnt lgkmcnt(7)
	v_mfma_f32_16x16x32_bf16 v[60:63], v[132:135], v[178:181], v[60:63]
	v_mfma_f32_16x16x32_bf16 v[56:59], v[154:157], v[178:181], v[56:59]
	s_waitcnt lgkmcnt(5)
	v_mfma_f32_16x16x32_bf16 v[48:51], v[132:135], v[186:189], v[48:51]
	v_mfma_f32_16x16x32_bf16 v[40:43], v[154:157], v[186:189], v[40:43]
	s_waitcnt lgkmcnt(3)
	v_mfma_f32_16x16x32_bf16 v[32:35], v[132:135], v[194:197], v[32:35]
	v_mfma_f32_16x16x32_bf16 v[24:27], v[154:157], v[194:197], v[24:27]
	s_waitcnt lgkmcnt(1)
	v_mfma_f32_16x16x32_bf16 v[16:19], v[132:135], v[202:205], v[16:19]
	v_mfma_f32_16x16x32_bf16 v[8:11], v[154:157], v[202:205], v[8:11]
	v_mfma_f32_16x16x32_bf16 v[60:63], v[150:153], v[182:185], v[60:63]
	v_mfma_f32_16x16x32_bf16 v[56:59], v[158:161], v[182:185], v[56:59]
	v_mfma_f32_16x16x32_bf16 v[48:51], v[150:153], v[190:193], v[48:51]
	v_mfma_f32_16x16x32_bf16 v[40:43], v[158:161], v[190:193], v[40:43]
	v_mfma_f32_16x16x32_bf16 v[32:35], v[150:153], v[198:201], v[32:35]
	v_mfma_f32_16x16x32_bf16 v[24:27], v[158:161], v[198:201], v[24:27]
	s_waitcnt lgkmcnt(0)
	v_mfma_f32_16x16x32_bf16 v[16:19], v[150:153], v[206:209], v[16:19]
	v_mfma_f32_16x16x32_bf16 v[8:11], v[158:161], v[206:209], v[8:11]
	v_mfma_f32_16x16x32_bf16 v[52:55], v[162:165], v[178:181], v[52:55]
	v_mfma_f32_16x16x32_bf16 v[44:47], v[170:173], v[178:181], v[44:47]
	v_mfma_f32_16x16x32_bf16 v[36:39], v[162:165], v[186:189], v[36:39]
	v_mfma_f32_16x16x32_bf16 v[28:31], v[170:173], v[186:189], v[28:31]
	v_mfma_f32_16x16x32_bf16 v[20:23], v[162:165], v[194:197], v[20:23]
	v_mfma_f32_16x16x32_bf16 v[12:15], v[170:173], v[194:197], v[12:15]
	v_mfma_f32_16x16x32_bf16 v[4:7], v[162:165], v[202:205], v[4:7]
	v_mfma_f32_16x16x32_bf16 v[0:3], v[170:173], v[202:205], v[0:3]
	v_mfma_f32_16x16x32_bf16 v[52:55], v[166:169], v[182:185], v[52:55]
	v_mfma_f32_16x16x32_bf16 v[44:47], v[174:177], v[182:185], v[44:47]
	v_mfma_f32_16x16x32_bf16 v[36:39], v[166:169], v[190:193], v[36:39]
	v_mfma_f32_16x16x32_bf16 v[28:31], v[174:177], v[190:193], v[28:31]
	v_mfma_f32_16x16x32_bf16 v[20:23], v[166:169], v[198:201], v[20:23]
	v_mfma_f32_16x16x32_bf16 v[12:15], v[174:177], v[198:201], v[12:15]
	v_mfma_f32_16x16x32_bf16 v[4:7], v[166:169], v[206:209], v[4:7]
	v_mfma_f32_16x16x32_bf16 v[0:3], v[174:177], v[206:209], v[0:3]
	s_barrier
; #define PG8_STAGE(bufoff, soff, voff) do { _Pragma("unroll") for (int _i = 0; _i < 2; ++_i) \
;         __builtin_amdgcn_raw_ptr_buffer_load_lds(rs_##voff, (PG8_LAS unsigned*)(lds + (bufoff) + ldsw + _i * 8192), 16, (int)(voff)[_i], (int)(soff), 0, 0); } while (0)
; #define PG8_LDA(dst, b, h) do { _Pragma("unroll") for (int m = 0; m < 4; ++m) _Pragma("unroll") for (int k = 0; k < 2; ++k) dst[m][k] = *(const PG8_LAS bf16x8*)(lds + PG8_SA(b, h) + aoff + m * 2048 + k * 1024); } while (0)
; #define PG8_LDB(dst, b, h) do { _Pragma("unroll") for (int n = 0; n < 2; ++n) _Pragma("unroll") for (int k = 0; k < 2; ++k) dst[n][k] = *(const PG8_LAS bf16x8*)(lds + PG8_SB(b, h) + boff + n * 2048 + k * 1024); } while (0)
; #define PG8_MMA(ai, bj, At, Bt) do { __builtin_amdgcn_s_setprio(1); _Pragma("unroll") for (int m = 0; m < 4; ++m) _Pragma("unroll") for (int n = 0; n < 2; ++n) _Pragma("unroll") for (int k = 0; k < 2; ++k) \
;         acc[ai][bj][m][n] = __builtin_amdgcn_mfma_f32_16x16x32_bf16(Bt[n][k], At[m][k], acc[ai][bj][m][n], 0, 0, 0); __builtin_amdgcn_s_setprio(0); } while (0)
; #define PG8_WAIT_V(n) asm volatile("s_waitcnt vmcnt(" #n ")" ::: "memory")
; #define PG8_WAIT_L(n) asm volatile("s_waitcnt lgkmcnt(" #n ")" ::: "memory")
; #define PG8_BAR __builtin_amdgcn_s_barrier()
; #define PG8_SCHED __builtin_amdgcn_sched_barrier(0)
; template <class Epi, class Sched, bool ALIGN_EPI = false, bool SP2 = false>
; __device__ __forceinline__ void gemm_phase(PG8_LAS unsigned char* lds, const Gemm g, const Sched& S, const Epi& E, const int wid  ) {
;     ...
;             PG8_WAIT_V(8); PG8_WAIT_L(0); PG8_BAR; PG8_MMA(1, 0, At, B0); PG8_MMA(1, 1, At, B1); PG8_BAR; PG8_SCHED;
;             PG8_LDB(B0, 1, 0); PG8_LDB(B1, 1, 1); PG8_SCHED; PG8_LDA(At, 1, 0); PG8_STAGE(PG8_SA(0, 1), a2 + hstep, voffA);
;             PG8_WAIT_V(8); PG8_WAIT_L(0); PG8_BAR; PG8_MMA(0, 0, At, B0); PG8_MMA(0, 1, At, B1); PG8_BAR; PG8_SCHED;
;             PG8_LDA(At, 1, 1); PG8_STAGE(PG8_SB(1, 0), b3, voffB); PG8_STAGE(PG8_SB(1, 1), b3 + hstep, voffB); PG8_STAGE(PG8_SA(1, 0), a3, voffA);
;             PG8_WAIT_V(8); PG8_WAIT_L(0); PG8_BAR; PG8_MMA(1, 0, At, B0); PG8_MMA(1, 1, At, B1); PG8_BAR; PG8_SCHED;
	ds_read_b128 v[132:135], v147
	ds_read_b128 v[150:153], v147 offset:1024
	ds_read_b128 v[154:157], v147 offset:2048
	ds_read_b128 v[158:161], v147 offset:3072
	ds_read_b128 v[162:165], v148
	ds_read_b128 v[166:169], v148 offset:1024
	ds_read_b128 v[170:173], v148 offset:2048
	ds_read_b128 v[174:177], v148 offset:3072
	s_add_i32 s70, s70, 0x80000
	s_mov_b32 m0, s36
	ds_read_b128 v[178:181], v146 offset:32768
	ds_read_b128 v[182:185], v146 offset:33792
	ds_read_b128 v[186:189], v146 offset:34816
	ds_read_b128 v[190:193], v146 offset:35840
	ds_read_b128 v[194:197], v146 offset:36864
	ds_read_b128 v[198:201], v146 offset:37888
	ds_read_b128 v[202:205], v146 offset:38912
	ds_read_b128 v[206:209], v146 offset:39936
	buffer_load_dwordx4 v138, s[8:11], s70 offen lds
	s_mov_b32 m0, s37
	s_nop 0
	buffer_load_dwordx4 v140, s[8:11], s70 offen lds
	s_waitcnt vmcnt(8)
	s_waitcnt lgkmcnt(0)
	s_barrier
	s_waitcnt lgkmcnt(7)
	v_mfma_f32_16x16x32_bf16 v[124:127], v[132:135], v[178:181], v[124:127]
	v_mfma_f32_16x16x32_bf16 v[120:123], v[154:157], v[178:181], v[120:123]
	s_waitcnt lgkmcnt(5)
	v_mfma_f32_16x16x32_bf16 v[112:115], v[132:135], v[186:189], v[112:115]
	v_mfma_f32_16x16x32_bf16 v[104:107], v[154:157], v[186:189], v[104:107]
	s_waitcnt lgkmcnt(3)
	v_mfma_f32_16x16x32_bf16 v[96:99], v[132:135], v[194:197], v[96:99]
	v_mfma_f32_16x16x32_bf16 v[88:91], v[154:157], v[194:197], v[88:91]
	s_waitcnt lgkmcnt(1)
	v_mfma_f32_16x16x32_bf16 v[80:83], v[132:135], v[202:205], v[80:83]
	v_mfma_f32_16x16x32_bf16 v[72:75], v[154:157], v[202:205], v[72:75]
	v_mfma_f32_16x16x32_bf16 v[124:127], v[150:153], v[182:185], v[124:127]
	v_mfma_f32_16x16x32_bf16 v[120:123], v[158:161], v[182:185], v[120:123]
	v_mfma_f32_16x16x32_bf16 v[112:115], v[150:153], v[190:193], v[112:115]
	v_mfma_f32_16x16x32_bf16 v[104:107], v[158:161], v[190:193], v[104:107]
	v_mfma_f32_16x16x32_bf16 v[96:99], v[150:153], v[198:201], v[96:99]
	v_mfma_f32_16x16x32_bf16 v[88:91], v[158:161], v[198:201], v[88:91]
	s_waitcnt lgkmcnt(0)
	v_mfma_f32_16x16x32_bf16 v[80:83], v[150:153], v[206:209], v[80:83]
	v_mfma_f32_16x16x32_bf16 v[72:75], v[158:161], v[206:209], v[72:75]
	v_mfma_f32_16x16x32_bf16 v[116:119], v[162:165], v[178:181], v[116:119]
	v_mfma_f32_16x16x32_bf16 v[108:111], v[170:173], v[178:181], v[108:111]
	v_mfma_f32_16x16x32_bf16 v[100:103], v[162:165], v[186:189], v[100:103]
	v_mfma_f32_16x16x32_bf16 v[92:95], v[170:173], v[186:189], v[92:95]
	v_mfma_f32_16x16x32_bf16 v[84:87], v[162:165], v[194:197], v[84:87]
	v_mfma_f32_16x16x32_bf16 v[76:79], v[170:173], v[194:197], v[76:79]
	v_mfma_f32_16x16x32_bf16 v[68:71], v[162:165], v[202:205], v[68:71]
	v_mfma_f32_16x16x32_bf16 v[64:67], v[170:173], v[202:205], v[64:67]
	v_mfma_f32_16x16x32_bf16 v[116:119], v[166:169], v[182:185], v[116:119]
	v_mfma_f32_16x16x32_bf16 v[108:111], v[174:177], v[182:185], v[108:111]
	v_mfma_f32_16x16x32_bf16 v[100:103], v[166:169], v[190:193], v[100:103]
	v_mfma_f32_16x16x32_bf16 v[92:95], v[174:177], v[190:193], v[92:95]
	v_mfma_f32_16x16x32_bf16 v[84:87], v[166:169], v[198:201], v[84:87]
	v_mfma_f32_16x16x32_bf16 v[76:79], v[174:177], v[198:201], v[76:79]
	v_mfma_f32_16x16x32_bf16 v[68:71], v[166:169], v[206:209], v[68:71]
	v_mfma_f32_16x16x32_bf16 v[64:67], v[174:177], v[206:209], v[64:67]
	s_barrier
	s_mov_b32 m0, s39
	s_or_b32 s70, s69, 0x80
	ds_read_b128 v[178:181], v146 offset:49152
	ds_read_b128 v[182:185], v146 offset:50176
	ds_read_b128 v[186:189], v146 offset:51200
	ds_read_b128 v[190:193], v146 offset:52224
	ds_read_b128 v[194:197], v146 offset:53248
	ds_read_b128 v[198:201], v146 offset:54272
	ds_read_b128 v[202:205], v146 offset:55296
	ds_read_b128 v[206:209], v146 offset:56320
	buffer_load_dwordx4 v139, s[12:15], s70 offen lds
	s_mov_b32 m0, s40
	s_add_i32 s69, s69, 0x80080
	buffer_load_dwordx4 v141, s[12:15], s70 offen lds
	s_mov_b32 m0, s43
	s_nop 0
	buffer_load_dwordx4 v139, s[12:15], s69 offen lds
	s_mov_b32 m0, s44
	s_nop 0
	buffer_load_dwordx4 v141, s[12:15], s69 offen lds
	s_mov_b32 m0, s41
	s_nop 0
	buffer_load_dwordx4 v138, s[8:11], s68 offen lds
	s_mov_b32 m0, s42
	s_nop 0
	buffer_load_dwordx4 v140, s[8:11], s68 offen lds
	s_waitcnt vmcnt(8)
	s_waitcnt lgkmcnt(0)
	s_barrier
	s_waitcnt lgkmcnt(7)
	v_mfma_f32_16x16x32_bf16 v[60:63], v[132:135], v[178:181], v[60:63]
	v_mfma_f32_16x16x32_bf16 v[56:59], v[154:157], v[178:181], v[56:59]
	s_waitcnt lgkmcnt(5)
	v_mfma_f32_16x16x32_bf16 v[48:51], v[132:135], v[186:189], v[48:51]
	v_mfma_f32_16x16x32_bf16 v[40:43], v[154:157], v[186:189], v[40:43]
	s_waitcnt lgkmcnt(3)
	v_mfma_f32_16x16x32_bf16 v[32:35], v[132:135], v[194:197], v[32:35]
	v_mfma_f32_16x16x32_bf16 v[24:27], v[154:157], v[194:197], v[24:27]
	s_waitcnt lgkmcnt(1)
	v_mfma_f32_16x16x32_bf16 v[16:19], v[132:135], v[202:205], v[16:19]
	v_mfma_f32_16x16x32_bf16 v[8:11], v[154:157], v[202:205], v[8:11]
	v_mfma_f32_16x16x32_bf16 v[60:63], v[150:153], v[182:185], v[60:63]
	v_mfma_f32_16x16x32_bf16 v[56:59], v[158:161], v[182:185], v[56:59]
	v_mfma_f32_16x16x32_bf16 v[48:51], v[150:153], v[190:193], v[48:51]
	v_mfma_f32_16x16x32_bf16 v[40:43], v[158:161], v[190:193], v[40:43]
	v_mfma_f32_16x16x32_bf16 v[32:35], v[150:153], v[198:201], v[32:35]
	v_mfma_f32_16x16x32_bf16 v[24:27], v[158:161], v[198:201], v[24:27]
	s_waitcnt lgkmcnt(0)
	v_mfma_f32_16x16x32_bf16 v[16:19], v[150:153], v[206:209], v[16:19]
	v_mfma_f32_16x16x32_bf16 v[8:11], v[158:161], v[206:209], v[8:11]
	v_mfma_f32_16x16x32_bf16 v[52:55], v[162:165], v[178:181], v[52:55]
	v_mfma_f32_16x16x32_bf16 v[44:47], v[170:173], v[178:181], v[44:47]
	v_mfma_f32_16x16x32_bf16 v[36:39], v[162:165], v[186:189], v[36:39]
	v_mfma_f32_16x16x32_bf16 v[28:31], v[170:173], v[186:189], v[28:31]
	v_mfma_f32_16x16x32_bf16 v[20:23], v[162:165], v[194:197], v[20:23]
	v_mfma_f32_16x16x32_bf16 v[12:15], v[170:173], v[194:197], v[12:15]
	v_mfma_f32_16x16x32_bf16 v[4:7], v[162:165], v[202:205], v[4:7]
	v_mfma_f32_16x16x32_bf16 v[0:3], v[170:173], v[202:205], v[0:3]
	v_mfma_f32_16x16x32_bf16 v[52:55], v[166:169], v[182:185], v[52:55]
	v_mfma_f32_16x16x32_bf16 v[44:47], v[174:177], v[182:185], v[44:47]
	v_mfma_f32_16x16x32_bf16 v[36:39], v[166:169], v[190:193], v[36:39]
	v_mfma_f32_16x16x32_bf16 v[28:31], v[174:177], v[190:193], v[28:31]
	v_mfma_f32_16x16x32_bf16 v[20:23], v[166:169], v[198:201], v[20:23]
	v_mfma_f32_16x16x32_bf16 v[12:15], v[174:177], v[198:201], v[12:15]
	v_mfma_f32_16x16x32_bf16 v[4:7], v[166:169], v[206:209], v[4:7]
	v_mfma_f32_16x16x32_bf16 v[0:3], v[174:177], v[206:209], v[0:3]
	s_barrier
	s_add_i32 s67, s67, 2
	s_addk_i32 s65, 0x100
	s_addk_i32 s66, 0x100
	s_cmp_gt_u32 s67, 29
	s_cbranch_scc0 .LBB0_2575
	s_setprio 0
	s_and_b64 vcc, exec, s[18:19]
	s_cbranch_vccz .LBB0_2578
	s_barrier

; #define PG8_STAGE(bufoff, soff, voff) do { _Pragma("unroll") for (int _i = 0; _i < 2; ++_i) \
;         __builtin_amdgcn_raw_ptr_buffer_load_lds(rs_##voff, (PG8_LAS unsigned*)(lds + (bufoff) + ldsw + _i * 8192), 16, (int)(voff)[_i], (int)(soff), 0, 0); } while (0)
; #define PG8_LDA(dst, b, h) do { _Pragma("unroll") for (int m = 0; m < 4; ++m) _Pragma("unroll") for (int k = 0; k < 2; ++k) dst[m][k] = *(const PG8_LAS bf16x8*)(lds + PG8_SA(b, h) + aoff + m * 2048 + k * 1024); } while (0)
; #define PG8_LDB(dst, b, h) do { _Pragma("unroll") for (int n = 0; n < 2; ++n) _Pragma("unroll") for (int k = 0; k < 2; ++k) dst[n][k] = *(const PG8_LAS bf16x8*)(lds + PG8_SB(b, h) + boff + n * 2048 + k * 1024); } while (0)
; #define PG8_MMA(ai, bj, At, Bt) do { __builtin_amdgcn_s_setprio(1); _Pragma("unroll") for (int m = 0; m < 4; ++m) _Pragma("unroll") for (int n = 0; n < 2; ++n) _Pragma("unroll") for (int k = 0; k < 2; ++k) \
;         acc[ai][bj][m][n] = __builtin_amdgcn_mfma_f32_16x16x32_bf16(Bt[n][k], At[m][k], acc[ai][bj][m][n], 0, 0, 0); __builtin_amdgcn_s_setprio(0); } while (0)
; #define PG8_WAIT_V(n) asm volatile("s_waitcnt vmcnt(" #n ")" ::: "memory")
; #define PG8_BAR __builtin_amdgcn_s_barrier()
; template <class Epi, class Sched, bool ALIGN_EPI = false, bool SP2 = false>
; __device__ __forceinline__ void gemm_phase(PG8_LAS unsigned char* lds, const Gemm g, const Sched& S, const Epi& E, const int wid  ) {
;     ...
;         for (int t = 0; t < nt; t += 2) {
;             const bool last = (t == nt - 2);
;             const unsigned a1 = cA + (unsigned)(t + 1) * kstep;
;             const unsigned a2 = last ? nA : cA + (unsigned)(t + 2) * kstep, b2 = last ? nB : cB + (unsigned)(t + 2) * kstep;
;             const unsigned a3 = a2 + kstep, b3 = b2 + kstep;
;             if (last && has_next) S.a_ready(nxt);
;             if constexpr (SP2) {
;             PG8_LDB(B0, 0, 0); PG8_LDB(B1, 0, 1); PG8_SCHED; PG8_LDA(At, 0, 0); PG8_STAGE(PG8_SA(1, 1), a1 + hstep, voffA);
;             PG8_WAIT_V(8); PG8_WAIT_L(0); PG8_BAR; PG8_MMA(0, 0, At, B0); PG8_MMA(0, 1, At, B1); PG8_BAR; PG8_SCHED;
;             PG8_LDA(At, 0, 1); PG8_STAGE(PG8_SB(0, 0), b2, voffB); PG8_STAGE(PG8_SB(0, 1), b2 + hstep, voffB); PG8_STAGE(PG8_SA(0, 0), a2, voffA);
;             PG8_WAIT_V(8); PG8_WAIT_L(0); PG8_BAR; PG8_MMA(1, 0, At, B0); PG8_MMA(1, 1, At, B1); PG8_BAR; PG8_SCHED;
.Lprio_2813:
.LBB0_2813:
	s_waitcnt lgkmcnt(0)
	ds_read_b128 v[16:19], v188
	ds_read_b128 v[20:23], v188 offset:1024
	ds_read_b128 v[24:27], v188 offset:2048
	ds_read_b128 v[28:31], v188 offset:3072
	ds_read_b128 v[32:35], v189
	ds_read_b128 v[36:39], v189 offset:1024
	ds_read_b128 v[40:43], v189 offset:2048
	ds_read_b128 v[44:47], v189 offset:3072
	s_add_i32 s18, s8, 0xfff80080
	s_cmp_eq_u32 s48, 28
	s_cselect_b32 s93, s6, s18
	s_cselect_b32 s92, s7, s9
	s_or_b32 s49, s93, 0x80
	s_mov_b32 m0, s74
	ds_read_b128 v[160:163], v190
	ds_read_b128 v[170:173], v190 offset:1024
	ds_read_b128 v[174:177], v190 offset:2048
	ds_read_b128 v[178:181], v190 offset:3072
	ds_read_b128 v[194:197], v190 offset:4096
	ds_read_b128 v[198:201], v190 offset:5120
	ds_read_b128 v[202:205], v190 offset:6144
	ds_read_b128 v[206:209], v190 offset:7168
	buffer_load_dwordx4 v182, s[12:15], s8 offen lds
	s_mov_b32 m0, s76
	s_nop 0
	buffer_load_dwordx4 v184, s[12:15], s8 offen lds
	s_waitcnt vmcnt(8)
	s_waitcnt lgkmcnt(0)
	s_barrier
	s_waitcnt lgkmcnt(7)
	v_mfma_f32_16x16x32_bf16 v[152:155], v[16:19], v[160:163], v[152:155]
	v_mfma_f32_16x16x32_bf16 v[52:55], v[24:27], v[160:163], v[52:55]
	s_waitcnt lgkmcnt(5)
	v_mfma_f32_16x16x32_bf16 v[148:151], v[16:19], v[174:177], v[148:151]
	v_mfma_f32_16x16x32_bf16 v[144:147], v[24:27], v[174:177], v[144:147]
	s_waitcnt lgkmcnt(3)
	v_mfma_f32_16x16x32_bf16 v[140:143], v[16:19], v[194:197], v[140:143]
	v_mfma_f32_16x16x32_bf16 v[132:135], v[24:27], v[194:197], v[132:135]
	s_waitcnt lgkmcnt(1)
	v_mfma_f32_16x16x32_bf16 v[156:159], v[16:19], v[202:205], v[156:159]
	v_mfma_f32_16x16x32_bf16 v[120:123], v[24:27], v[202:205], v[120:123]
	v_mfma_f32_16x16x32_bf16 v[152:155], v[20:23], v[170:173], v[152:155]
	v_mfma_f32_16x16x32_bf16 v[52:55], v[28:31], v[170:173], v[52:55]
	v_mfma_f32_16x16x32_bf16 v[148:151], v[20:23], v[178:181], v[148:151]
	v_mfma_f32_16x16x32_bf16 v[144:147], v[28:31], v[178:181], v[144:147]
	v_mfma_f32_16x16x32_bf16 v[140:143], v[20:23], v[198:201], v[140:143]
	v_mfma_f32_16x16x32_bf16 v[132:135], v[28:31], v[198:201], v[132:135]
	s_waitcnt lgkmcnt(0)
	v_mfma_f32_16x16x32_bf16 v[156:159], v[20:23], v[206:209], v[156:159]
	v_mfma_f32_16x16x32_bf16 v[120:123], v[28:31], v[206:209], v[120:123]
	v_mfma_f32_16x16x32_bf16 v[12:15], v[32:35], v[160:163], v[12:15]
	v_mfma_f32_16x16x32_bf16 v[8:11], v[40:43], v[160:163], v[8:11]
	v_mfma_f32_16x16x32_bf16 v[136:139], v[32:35], v[174:177], v[136:139]
	v_mfma_f32_16x16x32_bf16 v[128:131], v[40:43], v[174:177], v[128:131]
	v_mfma_f32_16x16x32_bf16 v[124:127], v[32:35], v[194:197], v[124:127]
	v_mfma_f32_16x16x32_bf16 v[116:119], v[40:43], v[194:197], v[116:119]
	v_mfma_f32_16x16x32_bf16 v[112:115], v[32:35], v[202:205], v[112:115]
	v_mfma_f32_16x16x32_bf16 v[108:111], v[40:43], v[202:205], v[108:111]
	v_mfma_f32_16x16x32_bf16 v[12:15], v[36:39], v[170:173], v[12:15]
	v_mfma_f32_16x16x32_bf16 v[8:11], v[44:47], v[170:173], v[8:11]
	v_mfma_f32_16x16x32_bf16 v[136:139], v[36:39], v[178:181], v[136:139]
	v_mfma_f32_16x16x32_bf16 v[128:131], v[44:47], v[178:181], v[128:131]
	v_mfma_f32_16x16x32_bf16 v[124:127], v[36:39], v[198:201], v[124:127]
	v_mfma_f32_16x16x32_bf16 v[116:119], v[44:47], v[198:201], v[116:119]
	v_mfma_f32_16x16x32_bf16 v[112:115], v[36:39], v[206:209], v[112:115]
	v_mfma_f32_16x16x32_bf16 v[108:111], v[44:47], v[206:209], v[108:111]
	s_barrier
	s_mov_b32 m0, s34
	s_mov_b32 s18, s14
	s_mov_b32 s19, s15
	ds_read_b128 v[160:163], v190 offset:16384
	ds_read_b128 v[170:173], v190 offset:17408
	ds_read_b128 v[174:177], v190 offset:18432
	ds_read_b128 v[178:181], v190 offset:19456
	ds_read_b128 v[194:197], v190 offset:20480
	ds_read_b128 v[198:201], v190 offset:21504
	ds_read_b128 v[202:205], v190 offset:22528
	ds_read_b128 v[206:209], v190 offset:23552
	buffer_load_dwordx4 v183, s[16:19], s92 offen lds
	s_mov_b32 m0, s35
	s_add_i32 s94, s92, 0x80000
	buffer_load_dwordx4 v185, s[16:19], s92 offen lds
	s_mov_b32 m0, s50
	s_nop 0
	buffer_load_dwordx4 v183, s[16:19], s94 offen lds
	s_mov_b32 m0, s51
	s_nop 0
	buffer_load_dwordx4 v185, s[16:19], s94 offen lds
	s_mov_b32 m0, s33
	s_nop 0
	buffer_load_dwordx4 v182, s[12:15], s93 offen lds
	s_mov_b32 m0, s53
	s_nop 0
	buffer_load_dwordx4 v184, s[12:15], s93 offen lds
	s_waitcnt vmcnt(8)
	s_waitcnt lgkmcnt(0)
	s_barrier
	s_waitcnt lgkmcnt(7)
	v_mfma_f32_16x16x32_bf16 v[104:107], v[16:19], v[160:163], v[104:107]
	v_mfma_f32_16x16x32_bf16 v[100:103], v[24:27], v[160:163], v[100:103]
	s_waitcnt lgkmcnt(5)
	v_mfma_f32_16x16x32_bf16 v[96:99], v[16:19], v[174:177], v[96:99]
	v_mfma_f32_16x16x32_bf16 v[88:91], v[24:27], v[174:177], v[88:91]
	s_waitcnt lgkmcnt(3)
	v_mfma_f32_16x16x32_bf16 v[84:87], v[16:19], v[194:197], v[84:87]
	v_mfma_f32_16x16x32_bf16 v[76:79], v[24:27], v[194:197], v[76:79]
	s_waitcnt lgkmcnt(1)
	v_mfma_f32_16x16x32_bf16 v[16:19], v[16:19], v[202:205], v[92:95]
	v_mfma_f32_16x16x32_bf16 v[104:107], v[20:23], v[170:173], v[104:107]
	v_mfma_f32_16x16x32_bf16 v[100:103], v[28:31], v[170:173], v[100:103]
	v_mfma_f32_16x16x32_bf16 v[96:99], v[20:23], v[178:181], v[96:99]
	v_mfma_f32_16x16x32_bf16 v[88:91], v[28:31], v[178:181], v[88:91]
	v_mfma_f32_16x16x32_bf16 v[84:87], v[20:23], v[198:201], v[84:87]
	v_mfma_f32_16x16x32_bf16 v[76:79], v[28:31], v[198:201], v[76:79]
	s_waitcnt lgkmcnt(0)
	v_mfma_f32_16x16x32_bf16 v[16:19], v[20:23], v[206:209], v[16:19]
	v_mfma_f32_16x16x32_bf16 v[20:23], v[24:27], v[202:205], v[48:51]
	v_mfma_f32_16x16x32_bf16 v[20:23], v[28:31], v[206:209], v[20:23]
	v_mfma_f32_16x16x32_bf16 v[48:51], v[32:35], v[194:197], v[68:71]
	v_mfma_f32_16x16x32_bf16 v[4:7], v[32:35], v[160:163], v[4:7]
	v_mfma_f32_16x16x32_bf16 v[0:3], v[40:43], v[160:163], v[0:3]
	v_mfma_f32_16x16x32_bf16 v[24:27], v[32:35], v[174:177], v[80:83]
	v_mfma_f32_16x16x32_bf16 v[68:71], v[36:39], v[198:201], v[48:51]
	v_mfma_f32_16x16x32_bf16 v[48:51], v[40:43], v[194:197], v[64:67]
	v_mfma_f32_16x16x32_bf16 v[32:35], v[32:35], v[202:205], v[60:63]
	v_mfma_f32_16x16x32_bf16 v[4:7], v[36:39], v[170:173], v[4:7]
	v_mfma_f32_16x16x32_bf16 v[0:3], v[44:47], v[170:173], v[0:3]
	v_mfma_f32_16x16x32_bf16 v[24:27], v[36:39], v[178:181], v[24:27]
	v_mfma_f32_16x16x32_bf16 v[28:31], v[40:43], v[174:177], v[72:75]
	v_mfma_f32_16x16x32_bf16 v[64:67], v[44:47], v[198:201], v[48:51]
	v_mfma_f32_16x16x32_bf16 v[32:35], v[36:39], v[206:209], v[32:35]
	v_mfma_f32_16x16x32_bf16 v[36:39], v[40:43], v[202:205], v[56:59]
	v_mfma_f32_16x16x32_bf16 v[28:31], v[44:47], v[178:181], v[28:31]
	v_mfma_f32_16x16x32_bf16 v[36:39], v[44:47], v[206:209], v[36:39]
	s_barrier
; #define PG8_STAGE(bufoff, soff, voff) do { _Pragma("unroll") for (int _i = 0; _i < 2; ++_i) \
;         __builtin_amdgcn_raw_ptr_buffer_load_lds(rs_##voff, (PG8_LAS unsigned*)(lds + (bufoff) + ldsw + _i * 8192), 16, (int)(voff)[_i], (int)(soff), 0, 0); } while (0)
; #define PG8_LDA(dst, b, h) do { _Pragma("unroll") for (int m = 0; m < 4; ++m) _Pragma("unroll") for (int k = 0; k < 2; ++k) dst[m][k] = *(const PG8_LAS bf16x8*)(lds + PG8_SA(b, h) + aoff + m * 2048 + k * 1024); } while (0)
; #define PG8_LDB(dst, b, h) do { _Pragma("unroll") for (int n = 0; n < 2; ++n) _Pragma("unroll") for (int k = 0; k < 2; ++k) dst[n][k] = *(const PG8_LAS bf16x8*)(lds + PG8_SB(b, h) + boff + n * 2048 + k * 1024); } while (0)
; #define PG8_MMA(ai, bj, At, Bt) do { __builtin_amdgcn_s_setprio(1); _Pragma("unroll") for (int m = 0; m < 4; ++m) _Pragma("unroll") for (int n = 0; n < 2; ++n) _Pragma("unroll") for (int k = 0; k < 2; ++k) \
;         acc[ai][bj][m][n] = __builtin_amdgcn_mfma_f32_16x16x32_bf16(Bt[n][k], At[m][k], acc[ai][bj][m][n], 0, 0, 0); __builtin_amdgcn_s_setprio(0); } while (0)
; #define PG8_WAIT_V(n) asm volatile("s_waitcnt vmcnt(" #n ")" ::: "memory")
; #define PG8_WAIT_L(n) asm volatile("s_waitcnt lgkmcnt(" #n ")" ::: "memory")
; #define PG8_BAR __builtin_amdgcn_s_barrier()
; #define PG8_SCHED __builtin_amdgcn_sched_barrier(0)
; template <class Epi, class Sched, bool ALIGN_EPI = false, bool SP2 = false>
; __device__ __forceinline__ void gemm_phase(PG8_LAS unsigned char* lds, const Gemm g, const Sched& S, const Epi& E, const int wid  ) {
;     ...
;             PG8_WAIT_V(8); PG8_WAIT_L(0); PG8_BAR; PG8_MMA(1, 0, At, B0); PG8_MMA(1, 1, At, B1); PG8_BAR; PG8_SCHED;
;             PG8_LDB(B0, 1, 0); PG8_LDB(B1, 1, 1); PG8_SCHED; PG8_LDA(At, 1, 0); PG8_STAGE(PG8_SA(0, 1), a2 + hstep, voffA);
;             PG8_WAIT_V(8); PG8_WAIT_L(0); PG8_BAR; PG8_MMA(0, 0, At, B0); PG8_MMA(0, 1, At, B1); PG8_BAR; PG8_SCHED;
;             PG8_LDA(At, 1, 1); PG8_STAGE(PG8_SB(1, 0), b3, voffB); PG8_STAGE(PG8_SB(1, 1), b3 + hstep, voffB); PG8_STAGE(PG8_SA(1, 0), a3, voffA);
;             PG8_WAIT_V(8); PG8_WAIT_L(0); PG8_BAR; PG8_MMA(1, 0, At, B0); PG8_MMA(1, 1, At, B1); PG8_BAR; PG8_SCHED;
	ds_read_b128 v[40:43], v191
	ds_read_b128 v[44:47], v191 offset:1024
	ds_read_b128 v[48:51], v191 offset:2048
	ds_read_b128 v[56:59], v191 offset:3072
	ds_read_b128 v[60:63], v192
	ds_read_b128 v[160:163], v192 offset:1024
	ds_read_b128 v[170:173], v192 offset:2048
	ds_read_b128 v[174:177], v192 offset:3072
	s_add_i32 s93, s93, 0x80000
	s_mov_b32 m0, s54
	ds_read_b128 v[72:75], v190 offset:32768
	ds_read_b128 v[80:83], v190 offset:33792
	ds_read_b128 v[92:95], v190 offset:34816
	ds_read_b128 v[178:181], v190 offset:35840
	ds_read_b128 v[194:197], v190 offset:36864
	ds_read_b128 v[198:201], v190 offset:37888
	ds_read_b128 v[202:205], v190 offset:38912
	ds_read_b128 v[206:209], v190 offset:39936
	buffer_load_dwordx4 v182, s[12:15], s93 offen lds
	s_mov_b32 m0, s58
	s_nop 0
	buffer_load_dwordx4 v184, s[12:15], s93 offen lds
	s_waitcnt vmcnt(8)
	s_waitcnt lgkmcnt(0)
	s_barrier
	s_waitcnt lgkmcnt(7)
	v_mfma_f32_16x16x32_bf16 v[152:155], v[40:43], v[72:75], v[152:155]
	v_mfma_f32_16x16x32_bf16 v[52:55], v[48:51], v[72:75], v[52:55]
	s_waitcnt lgkmcnt(5)
	v_mfma_f32_16x16x32_bf16 v[148:151], v[40:43], v[92:95], v[148:151]
	v_mfma_f32_16x16x32_bf16 v[144:147], v[48:51], v[92:95], v[144:147]
	s_waitcnt lgkmcnt(3)
	v_mfma_f32_16x16x32_bf16 v[140:143], v[40:43], v[194:197], v[140:143]
	v_mfma_f32_16x16x32_bf16 v[132:135], v[48:51], v[194:197], v[132:135]
	s_waitcnt lgkmcnt(1)
	v_mfma_f32_16x16x32_bf16 v[156:159], v[40:43], v[202:205], v[156:159]
	v_mfma_f32_16x16x32_bf16 v[120:123], v[48:51], v[202:205], v[120:123]
	v_mfma_f32_16x16x32_bf16 v[152:155], v[44:47], v[80:83], v[152:155]
	v_mfma_f32_16x16x32_bf16 v[52:55], v[56:59], v[80:83], v[52:55]
	v_mfma_f32_16x16x32_bf16 v[148:151], v[44:47], v[178:181], v[148:151]
	v_mfma_f32_16x16x32_bf16 v[144:147], v[56:59], v[178:181], v[144:147]
	v_mfma_f32_16x16x32_bf16 v[140:143], v[44:47], v[198:201], v[140:143]
	v_mfma_f32_16x16x32_bf16 v[132:135], v[56:59], v[198:201], v[132:135]
	s_waitcnt lgkmcnt(0)
	v_mfma_f32_16x16x32_bf16 v[156:159], v[44:47], v[206:209], v[156:159]
	v_mfma_f32_16x16x32_bf16 v[120:123], v[56:59], v[206:209], v[120:123]
	v_mfma_f32_16x16x32_bf16 v[12:15], v[60:63], v[72:75], v[12:15]
	v_mfma_f32_16x16x32_bf16 v[8:11], v[170:173], v[72:75], v[8:11]
	v_mfma_f32_16x16x32_bf16 v[72:75], v[60:63], v[92:95], v[136:139]
	v_mfma_f32_16x16x32_bf16 v[136:139], v[160:163], v[178:181], v[72:75]
	v_mfma_f32_16x16x32_bf16 v[72:75], v[170:173], v[92:95], v[128:131]
	v_mfma_f32_16x16x32_bf16 v[128:131], v[174:177], v[178:181], v[72:75]
	v_mfma_f32_16x16x32_bf16 v[72:75], v[60:63], v[194:197], v[124:127]
	v_mfma_f32_16x16x32_bf16 v[124:127], v[160:163], v[198:201], v[72:75]
	v_mfma_f32_16x16x32_bf16 v[72:75], v[170:173], v[194:197], v[116:119]
	v_mfma_f32_16x16x32_bf16 v[116:119], v[174:177], v[198:201], v[72:75]
	v_mfma_f32_16x16x32_bf16 v[72:75], v[60:63], v[202:205], v[112:115]
	v_mfma_f32_16x16x32_bf16 v[112:115], v[160:163], v[206:209], v[72:75]
	v_mfma_f32_16x16x32_bf16 v[72:75], v[170:173], v[202:205], v[108:111]
	v_mfma_f32_16x16x32_bf16 v[12:15], v[160:163], v[80:83], v[12:15]
	v_mfma_f32_16x16x32_bf16 v[8:11], v[174:177], v[80:83], v[8:11]
	v_mfma_f32_16x16x32_bf16 v[108:111], v[174:177], v[206:209], v[72:75]
	s_barrier
	s_mov_b32 m0, s63
	s_or_b32 s93, s92, 0x80
	s_nop 0
	ds_read_b128 v[72:75], v190 offset:49152
	ds_read_b128 v[80:83], v190 offset:50176
	ds_read_b128 v[178:181], v190 offset:51200
	ds_read_b128 v[194:197], v190 offset:52224
	ds_read_b128 v[198:201], v190 offset:53248
	ds_read_b128 v[202:205], v190 offset:54272
	ds_read_b128 v[206:209], v190 offset:55296
	ds_read_b128 v[210:213], v190 offset:56320
	buffer_load_dwordx4 v183, s[16:19], s93 offen lds
	s_mov_b32 m0, s65
	s_add_i32 s92, s92, 0x80080
	buffer_load_dwordx4 v185, s[16:19], s93 offen lds
	s_mov_b32 m0, s68
	s_nop 0
	buffer_load_dwordx4 v183, s[16:19], s92 offen lds
	s_mov_b32 m0, s69
	s_nop 0
	buffer_load_dwordx4 v185, s[16:19], s92 offen lds
	s_mov_b32 m0, s66
	s_nop 0
	buffer_load_dwordx4 v182, s[12:15], s49 offen lds
	s_mov_b32 m0, s67
	s_nop 0
	buffer_load_dwordx4 v184, s[12:15], s49 offen lds
	s_waitcnt vmcnt(8)
	s_waitcnt lgkmcnt(0)
	s_barrier
	s_waitcnt lgkmcnt(7)
	v_mfma_f32_16x16x32_bf16 v[92:95], v[40:43], v[72:75], v[104:107]
	s_waitcnt lgkmcnt(6)
	v_mfma_f32_16x16x32_bf16 v[104:107], v[44:47], v[80:83], v[92:95]
	v_mfma_f32_16x16x32_bf16 v[92:95], v[48:51], v[72:75], v[100:103]
	v_mfma_f32_16x16x32_bf16 v[100:103], v[56:59], v[80:83], v[92:95]
	s_waitcnt lgkmcnt(5)
	v_mfma_f32_16x16x32_bf16 v[92:95], v[40:43], v[178:181], v[96:99]
	s_waitcnt lgkmcnt(1)
	v_mfma_f32_16x16x32_bf16 v[16:19], v[40:43], v[206:209], v[16:19]
	v_mfma_f32_16x16x32_bf16 v[96:99], v[44:47], v[194:197], v[92:95]
	v_mfma_f32_16x16x32_bf16 v[88:91], v[48:51], v[178:181], v[88:91]
	v_mfma_f32_16x16x32_bf16 v[84:87], v[40:43], v[198:201], v[84:87]
	v_mfma_f32_16x16x32_bf16 v[76:79], v[48:51], v[198:201], v[76:79]
	s_waitcnt lgkmcnt(0)
	v_mfma_f32_16x16x32_bf16 v[92:95], v[44:47], v[210:213], v[16:19]
	v_mfma_f32_16x16x32_bf16 v[16:19], v[48:51], v[206:209], v[20:23]
	v_mfma_f32_16x16x32_bf16 v[88:91], v[56:59], v[194:197], v[88:91]
	v_mfma_f32_16x16x32_bf16 v[84:87], v[44:47], v[202:205], v[84:87]
	v_mfma_f32_16x16x32_bf16 v[76:79], v[56:59], v[202:205], v[76:79]
	v_mfma_f32_16x16x32_bf16 v[48:51], v[56:59], v[210:213], v[16:19]
	v_mfma_f32_16x16x32_bf16 v[4:7], v[60:63], v[72:75], v[4:7]
	v_mfma_f32_16x16x32_bf16 v[0:3], v[170:173], v[72:75], v[0:3]
	v_mfma_f32_16x16x32_bf16 v[16:19], v[60:63], v[178:181], v[24:27]
	v_mfma_f32_16x16x32_bf16 v[4:7], v[160:163], v[80:83], v[4:7]
	v_mfma_f32_16x16x32_bf16 v[0:3], v[174:177], v[80:83], v[0:3]
	v_mfma_f32_16x16x32_bf16 v[80:83], v[160:163], v[194:197], v[16:19]
	v_mfma_f32_16x16x32_bf16 v[16:19], v[170:173], v[178:181], v[28:31]
	v_mfma_f32_16x16x32_bf16 v[72:75], v[174:177], v[194:197], v[16:19]
	v_mfma_f32_16x16x32_bf16 v[16:19], v[60:63], v[198:201], v[68:71]
	v_mfma_f32_16x16x32_bf16 v[68:71], v[160:163], v[202:205], v[16:19]
	v_mfma_f32_16x16x32_bf16 v[16:19], v[170:173], v[198:201], v[64:67]
	v_mfma_f32_16x16x32_bf16 v[64:67], v[174:177], v[202:205], v[16:19]
	v_mfma_f32_16x16x32_bf16 v[16:19], v[60:63], v[206:209], v[32:35]
	v_mfma_f32_16x16x32_bf16 v[60:63], v[160:163], v[210:213], v[16:19]
	v_mfma_f32_16x16x32_bf16 v[16:19], v[170:173], v[206:209], v[36:39]
	v_mfma_f32_16x16x32_bf16 v[56:59], v[174:177], v[210:213], v[16:19]
	s_barrier
	s_add_i32 s48, s48, 2
	s_addk_i32 s8, 0x100
	s_addk_i32 s9, 0x100
	s_cmp_gt_u32 s48, 29
	s_cbranch_scc0 .LBB0_2813
	s_setprio 0
	s_and_b64 vcc, exec, s[26:27]
	s_cbranch_vccz .LBB0_2816
	s_barrier

; #define PG8_STAGE(bufoff, soff, voff) do { _Pragma("unroll") for (int _i = 0; _i < 2; ++_i) \
;         __builtin_amdgcn_raw_ptr_buffer_load_lds(rs_##voff, (PG8_LAS unsigned*)(lds + (bufoff) + ldsw + _i * 8192), 16, (int)(voff)[_i], (int)(soff), 0, 0); } while (0)
; #define PG8_LDA(dst, b, h) do { _Pragma("unroll") for (int m = 0; m < 4; ++m) _Pragma("unroll") for (int k = 0; k < 2; ++k) dst[m][k] = *(const PG8_LAS bf16x8*)(lds + PG8_SA(b, h) + aoff + m * 2048 + k * 1024); } while (0)
; #define PG8_LDB(dst, b, h) do { _Pragma("unroll") for (int n = 0; n < 2; ++n) _Pragma("unroll") for (int k = 0; k < 2; ++k) dst[n][k] = *(const PG8_LAS bf16x8*)(lds + PG8_SB(b, h) + boff + n * 2048 + k * 1024); } while (0)
; #define PG8_MMA(ai, bj, At, Bt) do { __builtin_amdgcn_s_setprio(1); _Pragma("unroll") for (int m = 0; m < 4; ++m) _Pragma("unroll") for (int n = 0; n < 2; ++n) _Pragma("unroll") for (int k = 0; k < 2; ++k) \
;         acc[ai][bj][m][n] = __builtin_amdgcn_mfma_f32_16x16x32_bf16(Bt[n][k], At[m][k], acc[ai][bj][m][n], 0, 0, 0); __builtin_amdgcn_s_setprio(0); } while (0)
; #define PG8_WAIT_V(n) asm volatile("s_waitcnt vmcnt(" #n ")" ::: "memory")
; #define PG8_WAIT_L(n) asm volatile("s_waitcnt lgkmcnt(" #n ")" ::: "memory")
; #define PG8_BAR __builtin_amdgcn_s_barrier()
; #define PG8_SCHED __builtin_amdgcn_sched_barrier(0)
; template <class Epi, class Sched, bool ALIGN_EPI = false, bool SP2 = false>
; __device__ __forceinline__ void gemm_phase(PG8_LAS unsigned char* lds, const Gemm g, const Sched& S, const Epi& E, const int wid  ) {
;     ...
;             PG8_LDB(B0, 0, 0); PG8_LDB(B1, 0, 1); PG8_SCHED; PG8_LDA(At, 0, 0); PG8_STAGE(PG8_SA(1, 1), a1 + hstep, voffA);
;             PG8_WAIT_V(8); PG8_WAIT_L(0); PG8_BAR; PG8_MMA(0, 0, At, B0); PG8_MMA(0, 1, At, B1); PG8_BAR; PG8_SCHED;
;     ...
; #pragma unroll
;         for (int a = 0; a < 2; ++a)
; #pragma unroll
;             for (int b = 0; b < 2; ++b)
; #pragma unroll
;                 for (int m = 0; m < 4; ++m)
; #pragma unroll
;                     for (int n = 0; n < 2; ++n) acc[a][b][m][n] = (f32x4){0.f, 0.f, 0.f, 0.f};
;         cur = nxt; cA = nA; cB = nB; ++ui;
.LBB0_4015:
	s_lshl_b32 s70, s69, 20
	s_and_b64 s[14:15], s[4:5], exec
	s_cselect_b32 s33, s70, s41
	s_lshl_b32 s71, s68, 20
	s_and_b64 s[14:15], s[4:5], exec
	v_mov_b32_e32 v0, 0
	s_cselect_b32 s40, s71, s73
	s_add_i32 s41, s41, 0x80080
	s_add_i32 s72, s73, 0x100
	s_mov_b32 s73, -2
	s_waitcnt lgkmcnt(0)
	v_mov_b32_e32 v1, v0
	v_mov_b32_e32 v2, v0
	v_mov_b32_e32 v3, v0
	v_mov_b32_e32 v4, v0
	v_mov_b32_e32 v5, v0
	s_waitcnt lgkmcnt(6)
	v_mov_b32_e32 v6, v0
	v_mov_b32_e32 v7, v0
	s_waitcnt lgkmcnt(1)
	v_mov_b32_e32 v16, v0
	v_mov_b32_e32 v17, v0
	s_waitcnt lgkmcnt(0)
	v_mov_b32_e32 v18, v0
	v_mov_b32_e32 v19, v0
	v_mov_b32_e32 v20, v0
	v_mov_b32_e32 v21, v0
	v_mov_b32_e32 v22, v0
	v_mov_b32_e32 v23, v0
	v_mov_b32_e32 v32, v0
	v_mov_b32_e32 v33, v0
	v_mov_b32_e32 v34, v0
	v_mov_b32_e32 v35, v0
	v_mov_b32_e32 v36, v0
	v_mov_b32_e32 v37, v0
	v_mov_b32_e32 v38, v0
	v_mov_b32_e32 v39, v0
	v_mov_b32_e32 v48, v0
	v_mov_b32_e32 v49, v0
	v_mov_b32_e32 v50, v0
	v_mov_b32_e32 v51, v0
	v_mov_b32_e32 v52, v0
	v_mov_b32_e32 v53, v0
	v_mov_b32_e32 v54, v0
	v_mov_b32_e32 v55, v0
	v_mov_b32_e32 v8, v0
	v_mov_b32_e32 v9, v0
	v_mov_b32_e32 v10, v0
	v_mov_b32_e32 v11, v0
	v_mov_b32_e32 v12, v0
	v_mov_b32_e32 v13, v0
	v_mov_b32_e32 v14, v0
	v_mov_b32_e32 v15, v0
	v_mov_b32_e32 v24, v0
	v_mov_b32_e32 v25, v0
	v_mov_b32_e32 v26, v0
	v_mov_b32_e32 v27, v0
	v_mov_b32_e32 v28, v0
	v_mov_b32_e32 v29, v0
	v_mov_b32_e32 v30, v0
	v_mov_b32_e32 v31, v0
	v_mov_b32_e32 v40, v0
	v_mov_b32_e32 v41, v0
	v_mov_b32_e32 v42, v0
	v_mov_b32_e32 v43, v0
	v_mov_b32_e32 v44, v0
	v_mov_b32_e32 v45, v0
	v_mov_b32_e32 v46, v0
	v_mov_b32_e32 v47, v0
	v_mov_b32_e32 v56, v0
	v_mov_b32_e32 v57, v0
	v_mov_b32_e32 v58, v0
	v_mov_b32_e32 v59, v0
	v_mov_b32_e32 v60, v0
	v_mov_b32_e32 v61, v0
	v_mov_b32_e32 v62, v0
	v_mov_b32_e32 v63, v0
	v_mov_b32_e32 v64, v0
	v_mov_b32_e32 v65, v0
	v_mov_b32_e32 v66, v0
	v_mov_b32_e32 v67, v0
	v_mov_b32_e32 v68, v0
	v_mov_b32_e32 v69, v0
	v_mov_b32_e32 v70, v0
	v_mov_b32_e32 v71, v0
	v_mov_b32_e32 v80, v0
	v_mov_b32_e32 v81, v0
	v_mov_b32_e32 v82, v0
	v_mov_b32_e32 v83, v0
	v_mov_b32_e32 v84, v0
	v_mov_b32_e32 v85, v0
	v_mov_b32_e32 v86, v0
	v_mov_b32_e32 v87, v0
	v_mov_b32_e32 v96, v0
	v_mov_b32_e32 v97, v0
	v_mov_b32_e32 v98, v0
	v_mov_b32_e32 v99, v0
	v_mov_b32_e32 v100, v0
	v_mov_b32_e32 v101, v0
	v_mov_b32_e32 v102, v0
	v_mov_b32_e32 v103, v0
	v_mov_b32_e32 v112, v0
	v_mov_b32_e32 v113, v0
	v_mov_b32_e32 v114, v0
	v_mov_b32_e32 v115, v0
	v_mov_b32_e32 v116, v0
	v_mov_b32_e32 v117, v0
	v_mov_b32_e32 v118, v0
	v_mov_b32_e32 v119, v0
	v_mov_b32_e32 v72, v0
	v_mov_b32_e32 v73, v0
	v_mov_b32_e32 v74, v0
	v_mov_b32_e32 v75, v0
	v_mov_b32_e32 v76, v0
	v_mov_b32_e32 v77, v0
	v_mov_b32_e32 v78, v0
	v_mov_b32_e32 v79, v0
	v_mov_b32_e32 v88, v0
	v_mov_b32_e32 v89, v0
	v_mov_b32_e32 v90, v0
	v_mov_b32_e32 v91, v0
	v_mov_b32_e32 v92, v0
	v_mov_b32_e32 v93, v0
	v_mov_b32_e32 v94, v0
	v_mov_b32_e32 v95, v0
	v_mov_b32_e32 v104, v0
	v_mov_b32_e32 v105, v0
	v_mov_b32_e32 v106, v0
	v_mov_b32_e32 v107, v0
	v_mov_b32_e32 v108, v0
	v_mov_b32_e32 v109, v0
	v_mov_b32_e32 v110, v0
	v_mov_b32_e32 v111, v0
	v_mov_b32_e32 v120, v0
	v_mov_b32_e32 v121, v0
	v_mov_b32_e32 v122, v0
	v_mov_b32_e32 v123, v0
	v_mov_b32_e32 v124, v0
	v_mov_b32_e32 v125, v0
	v_mov_b32_e32 v126, v0
	v_mov_b32_e32 v127, v0
	v_readlane_b32 vcc_lo, v246, 6
	s_nop 1
	s_cmp_ge_u32 vcc_lo, 4
	s_cbranch_scc0 .Lprio_4016
	s_setprio 1
.Lprio_4016:
.LBB0_4016:
	ds_read_b128 v[132:135], v152
	ds_read_b128 v[136:139], v152 offset:1024
	ds_read_b128 v[140:143], v152 offset:2048
	ds_read_b128 v[158:161], v152 offset:3072
	ds_read_b128 v[162:165], v153
	ds_read_b128 v[166:169], v153 offset:1024
	ds_read_b128 v[170:173], v153 offset:2048
	ds_read_b128 v[174:177], v153 offset:3072
	s_add_i32 s14, s41, 0xfff80080
	s_cmp_eq_u32 s73, 28
	s_cselect_b32 s76, s33, s14
	s_cselect_b32 s75, s40, s72
	s_or_b32 s74, s76, 0x80
	s_mov_b32 m0, s60
	ds_read_b128 v[178:181], v154
	ds_read_b128 v[182:185], v154 offset:1024
	ds_read_b128 v[186:189], v154 offset:2048
	ds_read_b128 v[190:193], v154 offset:3072
	ds_read_b128 v[194:197], v154 offset:4096
	ds_read_b128 v[198:201], v154 offset:5120
	ds_read_b128 v[202:205], v154 offset:6144
	ds_read_b128 v[206:209], v154 offset:7168
	buffer_load_dwordx4 v146, s[8:11], s41 offen lds
	s_mov_b32 m0, s61
	s_nop 0
	buffer_load_dwordx4 v148, s[8:11], s41 offen lds
	s_waitcnt vmcnt(8)
	s_waitcnt lgkmcnt(0)
	s_barrier
	s_waitcnt lgkmcnt(7)
	v_mfma_f32_16x16x32_bf16 v[124:127], v[132:135], v[178:181], v[124:127]
	v_mfma_f32_16x16x32_bf16 v[120:123], v[140:143], v[178:181], v[120:123]
	s_waitcnt lgkmcnt(5)
	v_mfma_f32_16x16x32_bf16 v[108:111], v[132:135], v[186:189], v[108:111]
	v_mfma_f32_16x16x32_bf16 v[104:107], v[140:143], v[186:189], v[104:107]
	s_waitcnt lgkmcnt(3)
	v_mfma_f32_16x16x32_bf16 v[92:95], v[132:135], v[194:197], v[92:95]
	v_mfma_f32_16x16x32_bf16 v[88:91], v[140:143], v[194:197], v[88:91]
	s_waitcnt lgkmcnt(1)
	v_mfma_f32_16x16x32_bf16 v[76:79], v[132:135], v[202:205], v[76:79]
	v_mfma_f32_16x16x32_bf16 v[72:75], v[140:143], v[202:205], v[72:75]
	v_mfma_f32_16x16x32_bf16 v[124:127], v[136:139], v[182:185], v[124:127]
	v_mfma_f32_16x16x32_bf16 v[120:123], v[158:161], v[182:185], v[120:123]
	v_mfma_f32_16x16x32_bf16 v[108:111], v[136:139], v[190:193], v[108:111]
	v_mfma_f32_16x16x32_bf16 v[104:107], v[158:161], v[190:193], v[104:107]
	v_mfma_f32_16x16x32_bf16 v[92:95], v[136:139], v[198:201], v[92:95]
	v_mfma_f32_16x16x32_bf16 v[88:91], v[158:161], v[198:201], v[88:91]
	s_waitcnt lgkmcnt(0)
	v_mfma_f32_16x16x32_bf16 v[76:79], v[136:139], v[206:209], v[76:79]
	v_mfma_f32_16x16x32_bf16 v[72:75], v[158:161], v[206:209], v[72:75]
	v_mfma_f32_16x16x32_bf16 v[116:119], v[162:165], v[178:181], v[116:119]
	v_mfma_f32_16x16x32_bf16 v[112:115], v[170:173], v[178:181], v[112:115]
	v_mfma_f32_16x16x32_bf16 v[100:103], v[162:165], v[186:189], v[100:103]
	v_mfma_f32_16x16x32_bf16 v[96:99], v[170:173], v[186:189], v[96:99]
	v_mfma_f32_16x16x32_bf16 v[84:87], v[162:165], v[194:197], v[84:87]
	v_mfma_f32_16x16x32_bf16 v[80:83], v[170:173], v[194:197], v[80:83]
	v_mfma_f32_16x16x32_bf16 v[68:71], v[162:165], v[202:205], v[68:71]
	v_mfma_f32_16x16x32_bf16 v[64:67], v[170:173], v[202:205], v[64:67]
	v_mfma_f32_16x16x32_bf16 v[116:119], v[166:169], v[182:185], v[116:119]
	v_mfma_f32_16x16x32_bf16 v[112:115], v[174:177], v[182:185], v[112:115]
	v_mfma_f32_16x16x32_bf16 v[100:103], v[166:169], v[190:193], v[100:103]
	v_mfma_f32_16x16x32_bf16 v[96:99], v[174:177], v[190:193], v[96:99]
	v_mfma_f32_16x16x32_bf16 v[84:87], v[166:169], v[198:201], v[84:87]
	v_mfma_f32_16x16x32_bf16 v[80:83], v[174:177], v[198:201], v[80:83]
	v_mfma_f32_16x16x32_bf16 v[68:71], v[166:169], v[206:209], v[68:71]
	v_mfma_f32_16x16x32_bf16 v[64:67], v[174:177], v[206:209], v[64:67]
	s_barrier
; #define PG8_STAGE(bufoff, soff, voff) do { _Pragma("unroll") for (int _i = 0; _i < 2; ++_i) \
;         __builtin_amdgcn_raw_ptr_buffer_load_lds(rs_##voff, (PG8_LAS unsigned*)(lds + (bufoff) + ldsw + _i * 8192), 16, (int)(voff)[_i], (int)(soff), 0, 0); } while (0)
; #define PG8_LDA(dst, b, h) do { _Pragma("unroll") for (int m = 0; m < 4; ++m) _Pragma("unroll") for (int k = 0; k < 2; ++k) dst[m][k] = *(const PG8_LAS bf16x8*)(lds + PG8_SA(b, h) + aoff + m * 2048 + k * 1024); } while (0)
; #define PG8_LDB(dst, b, h) do { _Pragma("unroll") for (int n = 0; n < 2; ++n) _Pragma("unroll") for (int k = 0; k < 2; ++k) dst[n][k] = *(const PG8_LAS bf16x8*)(lds + PG8_SB(b, h) + boff + n * 2048 + k * 1024); } while (0)
; #define PG8_MMA(ai, bj, At, Bt) do { __builtin_amdgcn_s_setprio(1); _Pragma("unroll") for (int m = 0; m < 4; ++m) _Pragma("unroll") for (int n = 0; n < 2; ++n) _Pragma("unroll") for (int k = 0; k < 2; ++k) \
;         acc[ai][bj][m][n] = __builtin_amdgcn_mfma_f32_16x16x32_bf16(Bt[n][k], At[m][k], acc[ai][bj][m][n], 0, 0, 0); __builtin_amdgcn_s_setprio(0); } while (0)
; #define PG8_WAIT_V(n) asm volatile("s_waitcnt vmcnt(" #n ")" ::: "memory")
; #define PG8_WAIT_L(n) asm volatile("s_waitcnt lgkmcnt(" #n ")" ::: "memory")
; #define PG8_BAR __builtin_amdgcn_s_barrier()
; #define PG8_SCHED __builtin_amdgcn_sched_barrier(0)
; template <class Epi, class Sched, bool ALIGN_EPI = false, bool SP2 = false>
; __device__ __forceinline__ void gemm_phase(PG8_LAS unsigned char* lds, const Gemm g, const Sched& S, const Epi& E, const int wid  ) {
;     ...
;             PG8_WAIT_V(8); PG8_WAIT_L(0); PG8_BAR; PG8_MMA(0, 0, At, B0); PG8_MMA(0, 1, At, B1); PG8_BAR; PG8_SCHED;
;             PG8_LDA(At, 0, 1); PG8_STAGE(PG8_SB(0, 0), b2, voffB); PG8_STAGE(PG8_SB(0, 1), b2 + hstep, voffB); PG8_STAGE(PG8_SA(0, 0), a2, voffA);
;             PG8_WAIT_V(8); PG8_WAIT_L(0); PG8_BAR; PG8_MMA(1, 0, At, B0); PG8_MMA(1, 1, At, B1); PG8_BAR; PG8_SCHED;
;             PG8_LDB(B0, 1, 0); PG8_LDB(B1, 1, 1); PG8_SCHED; PG8_LDA(At, 1, 0); PG8_STAGE(PG8_SA(0, 1), a2 + hstep, voffA);
;             PG8_WAIT_V(8); PG8_WAIT_L(0); PG8_BAR; PG8_MMA(0, 0, At, B0); PG8_MMA(0, 1, At, B1); PG8_BAR; PG8_SCHED;
	s_mov_b32 m0, s35
	s_mov_b32 s14, s10
	s_mov_b32 s15, s11
	ds_read_b128 v[178:181], v154 offset:16384
	ds_read_b128 v[182:185], v154 offset:17408
	ds_read_b128 v[186:189], v154 offset:18432
	ds_read_b128 v[190:193], v154 offset:19456
	ds_read_b128 v[194:197], v154 offset:20480
	ds_read_b128 v[198:201], v154 offset:21504
	ds_read_b128 v[202:205], v154 offset:22528
	ds_read_b128 v[206:209], v154 offset:23552
	buffer_load_dwordx4 v147, s[12:15], s75 offen lds
	s_mov_b32 m0, s42
	s_add_i32 s77, s75, 0x80000
	buffer_load_dwordx4 v149, s[12:15], s75 offen lds
	s_mov_b32 m0, s43
	s_nop 0
	buffer_load_dwordx4 v147, s[12:15], s77 offen lds
	s_mov_b32 m0, s44
	s_nop 0
	buffer_load_dwordx4 v149, s[12:15], s77 offen lds
	s_mov_b32 m0, s34
	s_nop 0
	buffer_load_dwordx4 v146, s[8:11], s76 offen lds
	s_mov_b32 m0, s45
	s_nop 0
	buffer_load_dwordx4 v148, s[8:11], s76 offen lds
	s_waitcnt vmcnt(8)
	s_waitcnt lgkmcnt(0)
	s_barrier
	s_waitcnt lgkmcnt(7)
	v_mfma_f32_16x16x32_bf16 v[60:63], v[132:135], v[178:181], v[60:63]
	v_mfma_f32_16x16x32_bf16 v[56:59], v[140:143], v[178:181], v[56:59]
	s_waitcnt lgkmcnt(5)
	v_mfma_f32_16x16x32_bf16 v[44:47], v[132:135], v[186:189], v[44:47]
	v_mfma_f32_16x16x32_bf16 v[40:43], v[140:143], v[186:189], v[40:43]
	s_waitcnt lgkmcnt(3)
	v_mfma_f32_16x16x32_bf16 v[28:31], v[132:135], v[194:197], v[28:31]
	v_mfma_f32_16x16x32_bf16 v[24:27], v[140:143], v[194:197], v[24:27]
	s_waitcnt lgkmcnt(1)
	v_mfma_f32_16x16x32_bf16 v[12:15], v[132:135], v[202:205], v[12:15]
	v_mfma_f32_16x16x32_bf16 v[8:11], v[140:143], v[202:205], v[8:11]
	v_mfma_f32_16x16x32_bf16 v[60:63], v[136:139], v[182:185], v[60:63]
	v_mfma_f32_16x16x32_bf16 v[56:59], v[158:161], v[182:185], v[56:59]
	v_mfma_f32_16x16x32_bf16 v[44:47], v[136:139], v[190:193], v[44:47]
	v_mfma_f32_16x16x32_bf16 v[40:43], v[158:161], v[190:193], v[40:43]
	v_mfma_f32_16x16x32_bf16 v[28:31], v[136:139], v[198:201], v[28:31]
	v_mfma_f32_16x16x32_bf16 v[24:27], v[158:161], v[198:201], v[24:27]
	s_waitcnt lgkmcnt(0)
	v_mfma_f32_16x16x32_bf16 v[12:15], v[136:139], v[206:209], v[12:15]
	v_mfma_f32_16x16x32_bf16 v[8:11], v[158:161], v[206:209], v[8:11]
	v_mfma_f32_16x16x32_bf16 v[52:55], v[162:165], v[178:181], v[52:55]
	v_mfma_f32_16x16x32_bf16 v[48:51], v[170:173], v[178:181], v[48:51]
	v_mfma_f32_16x16x32_bf16 v[36:39], v[162:165], v[186:189], v[36:39]
	v_mfma_f32_16x16x32_bf16 v[32:35], v[170:173], v[186:189], v[32:35]
	v_mfma_f32_16x16x32_bf16 v[20:23], v[162:165], v[194:197], v[20:23]
	v_mfma_f32_16x16x32_bf16 v[16:19], v[170:173], v[194:197], v[16:19]
	v_mfma_f32_16x16x32_bf16 v[4:7], v[162:165], v[202:205], v[4:7]
	v_mfma_f32_16x16x32_bf16 v[0:3], v[170:173], v[202:205], v[0:3]
	v_mfma_f32_16x16x32_bf16 v[52:55], v[166:169], v[182:185], v[52:55]
	v_mfma_f32_16x16x32_bf16 v[48:51], v[174:177], v[182:185], v[48:51]
	v_mfma_f32_16x16x32_bf16 v[36:39], v[166:169], v[190:193], v[36:39]
	v_mfma_f32_16x16x32_bf16 v[32:35], v[174:177], v[190:193], v[32:35]
	v_mfma_f32_16x16x32_bf16 v[20:23], v[166:169], v[198:201], v[20:23]
	v_mfma_f32_16x16x32_bf16 v[16:19], v[174:177], v[198:201], v[16:19]
	v_mfma_f32_16x16x32_bf16 v[4:7], v[166:169], v[206:209], v[4:7]
	v_mfma_f32_16x16x32_bf16 v[0:3], v[174:177], v[206:209], v[0:3]
	s_barrier
	ds_read_b128 v[132:135], v155
	ds_read_b128 v[136:139], v155 offset:1024
	ds_read_b128 v[140:143], v155 offset:2048
	ds_read_b128 v[158:161], v155 offset:3072
	ds_read_b128 v[162:165], v156
	ds_read_b128 v[166:169], v156 offset:1024
	ds_read_b128 v[170:173], v156 offset:2048
	ds_read_b128 v[174:177], v156 offset:3072
	s_add_i32 s76, s76, 0x80000
	s_mov_b32 m0, s46
	ds_read_b128 v[178:181], v154 offset:32768
	ds_read_b128 v[182:185], v154 offset:33792
	ds_read_b128 v[186:189], v154 offset:34816
	ds_read_b128 v[190:193], v154 offset:35840
	ds_read_b128 v[194:197], v154 offset:36864
	ds_read_b128 v[198:201], v154 offset:37888
	ds_read_b128 v[202:205], v154 offset:38912
	ds_read_b128 v[206:209], v154 offset:39936
	buffer_load_dwordx4 v146, s[8:11], s76 offen lds
	s_mov_b32 m0, s48
	s_nop 0
	buffer_load_dwordx4 v148, s[8:11], s76 offen lds
	s_waitcnt vmcnt(8)
	s_waitcnt lgkmcnt(0)
	s_barrier
; #define PG8_STAGE(bufoff, soff, voff) do { _Pragma("unroll") for (int _i = 0; _i < 2; ++_i) \
;         __builtin_amdgcn_raw_ptr_buffer_load_lds(rs_##voff, (PG8_LAS unsigned*)(lds + (bufoff) + ldsw + _i * 8192), 16, (int)(voff)[_i], (int)(soff), 0, 0); } while (0)
; #define PG8_LDA(dst, b, h) do { _Pragma("unroll") for (int m = 0; m < 4; ++m) _Pragma("unroll") for (int k = 0; k < 2; ++k) dst[m][k] = *(const PG8_LAS bf16x8*)(lds + PG8_SA(b, h) + aoff + m * 2048 + k * 1024); } while (0)
; #define PG8_LDB(dst, b, h) do { _Pragma("unroll") for (int n = 0; n < 2; ++n) _Pragma("unroll") for (int k = 0; k < 2; ++k) dst[n][k] = *(const PG8_LAS bf16x8*)(lds + PG8_SB(b, h) + boff + n * 2048 + k * 1024); } while (0)
; template <class Epi, class Sched, bool ALIGN_EPI = false, bool SP2 = false>
; __device__ __forceinline__ void gemm_phase(PG8_LAS unsigned char* lds, const Gemm g, const Sched& S, const Epi& E, const int wid  ) {
;     ...
;         for (int t = 0; t < nt; t += 2) {
;             const bool last = (t == nt - 2);
;             const unsigned a1 = cA + (unsigned)(t + 1) * kstep;
;             const unsigned a2 = last ? nA : cA + (unsigned)(t + 2) * kstep, b2 = last ? nB : cB + (unsigned)(t + 2) * kstep;
;             const unsigned a3 = a2 + kstep, b3 = b2 + kstep;
;             if (last && has_next) S.a_ready(nxt);
;             if constexpr (SP2) {
;             PG8_LDB(B0, 0, 0); PG8_LDB(B1, 0, 1); PG8_SCHED; PG8_LDA(At, 0, 0); PG8_STAGE(PG8_SA(1, 1), a1 + hstep, voffA);
;             PG8_WAIT_V(8); PG8_WAIT_L(0); PG8_BAR; PG8_MMA(0, 0, At, B0); PG8_MMA(0, 1, At, B1); PG8_BAR; PG8_SCHED;
;             PG8_LDA(At, 0, 1); PG8_STAGE(PG8_SB(0, 0), b2, voffB); PG8_STAGE(PG8_SB(0, 1), b2 + hstep, voffB); PG8_STAGE(PG8_SA(0, 0), a2, voffA);
;             PG8_WAIT_V(8); PG8_WAIT_L(0); PG8_BAR; PG8_MMA(1, 0, At, B0); PG8_MMA(1, 1, At, B1); PG8_BAR; PG8_SCHED;
;             PG8_LDB(B0, 1, 0); PG8_LDB(B1, 1, 1); PG8_SCHED; PG8_LDA(At, 1, 0); PG8_STAGE(PG8_SA(0, 1), a2 + hstep, voffA);
;             PG8_WAIT_V(8); PG8_WAIT_L(0); PG8_BAR; PG8_MMA(0, 0, At, B0); PG8_MMA(0, 1, At, B1); PG8_BAR; PG8_SCHED;
;             PG8_LDA(At, 1, 1); PG8_STAGE(PG8_SB(1, 0), b3, voffB); PG8_STAGE(PG8_SB(1, 1), b3 + hstep, voffB); PG8_STAGE(PG8_SA(1, 0), a3, voffA);
;             PG8_WAIT_V(8); PG8_WAIT_L(0); PG8_BAR; PG8_MMA(1, 0, At, B0); PG8_MMA(1, 1, At, B1); PG8_BAR; PG8_SCHED;
	s_waitcnt lgkmcnt(7)
	v_mfma_f32_16x16x32_bf16 v[124:127], v[132:135], v[178:181], v[124:127]
	v_mfma_f32_16x16x32_bf16 v[120:123], v[140:143], v[178:181], v[120:123]
	s_waitcnt lgkmcnt(5)
	v_mfma_f32_16x16x32_bf16 v[108:111], v[132:135], v[186:189], v[108:111]
	v_mfma_f32_16x16x32_bf16 v[104:107], v[140:143], v[186:189], v[104:107]
	s_waitcnt lgkmcnt(3)
	v_mfma_f32_16x16x32_bf16 v[92:95], v[132:135], v[194:197], v[92:95]
	v_mfma_f32_16x16x32_bf16 v[88:91], v[140:143], v[194:197], v[88:91]
	s_waitcnt lgkmcnt(1)
	v_mfma_f32_16x16x32_bf16 v[76:79], v[132:135], v[202:205], v[76:79]
	v_mfma_f32_16x16x32_bf16 v[72:75], v[140:143], v[202:205], v[72:75]
	v_mfma_f32_16x16x32_bf16 v[124:127], v[136:139], v[182:185], v[124:127]
	v_mfma_f32_16x16x32_bf16 v[120:123], v[158:161], v[182:185], v[120:123]
	v_mfma_f32_16x16x32_bf16 v[108:111], v[136:139], v[190:193], v[108:111]
	v_mfma_f32_16x16x32_bf16 v[104:107], v[158:161], v[190:193], v[104:107]
	v_mfma_f32_16x16x32_bf16 v[92:95], v[136:139], v[198:201], v[92:95]
	v_mfma_f32_16x16x32_bf16 v[88:91], v[158:161], v[198:201], v[88:91]
	s_waitcnt lgkmcnt(0)
	v_mfma_f32_16x16x32_bf16 v[76:79], v[136:139], v[206:209], v[76:79]
	v_mfma_f32_16x16x32_bf16 v[72:75], v[158:161], v[206:209], v[72:75]
	v_mfma_f32_16x16x32_bf16 v[116:119], v[162:165], v[178:181], v[116:119]
	v_mfma_f32_16x16x32_bf16 v[112:115], v[170:173], v[178:181], v[112:115]
	v_mfma_f32_16x16x32_bf16 v[100:103], v[162:165], v[186:189], v[100:103]
	v_mfma_f32_16x16x32_bf16 v[96:99], v[170:173], v[186:189], v[96:99]
	v_mfma_f32_16x16x32_bf16 v[84:87], v[162:165], v[194:197], v[84:87]
	v_mfma_f32_16x16x32_bf16 v[80:83], v[170:173], v[194:197], v[80:83]
	v_mfma_f32_16x16x32_bf16 v[68:71], v[162:165], v[202:205], v[68:71]
	v_mfma_f32_16x16x32_bf16 v[64:67], v[170:173], v[202:205], v[64:67]
	v_mfma_f32_16x16x32_bf16 v[116:119], v[166:169], v[182:185], v[116:119]
	v_mfma_f32_16x16x32_bf16 v[112:115], v[174:177], v[182:185], v[112:115]
	v_mfma_f32_16x16x32_bf16 v[100:103], v[166:169], v[190:193], v[100:103]
	v_mfma_f32_16x16x32_bf16 v[96:99], v[174:177], v[190:193], v[96:99]
	v_mfma_f32_16x16x32_bf16 v[84:87], v[166:169], v[198:201], v[84:87]
	v_mfma_f32_16x16x32_bf16 v[80:83], v[174:177], v[198:201], v[80:83]
	v_mfma_f32_16x16x32_bf16 v[68:71], v[166:169], v[206:209], v[68:71]
	v_mfma_f32_16x16x32_bf16 v[64:67], v[174:177], v[206:209], v[64:67]
	s_barrier
	s_mov_b32 m0, s50
	s_or_b32 s76, s75, 0x80
	ds_read_b128 v[178:181], v154 offset:49152
	ds_read_b128 v[182:185], v154 offset:50176
	ds_read_b128 v[186:189], v154 offset:51200
	ds_read_b128 v[190:193], v154 offset:52224
	ds_read_b128 v[194:197], v154 offset:53248
	ds_read_b128 v[198:201], v154 offset:54272
	ds_read_b128 v[202:205], v154 offset:55296
	ds_read_b128 v[206:209], v154 offset:56320
	buffer_load_dwordx4 v147, s[12:15], s76 offen lds
	s_mov_b32 m0, s51
	s_add_i32 s75, s75, 0x80080
	buffer_load_dwordx4 v149, s[12:15], s76 offen lds
	s_mov_b32 m0, s55
	s_nop 0
	buffer_load_dwordx4 v147, s[12:15], s75 offen lds
	s_mov_b32 m0, s58
	s_nop 0
	buffer_load_dwordx4 v149, s[12:15], s75 offen lds
	s_mov_b32 m0, s53
	s_nop 0
	buffer_load_dwordx4 v146, s[8:11], s74 offen lds
	s_mov_b32 m0, s54
	s_nop 0
	buffer_load_dwordx4 v148, s[8:11], s74 offen lds
	s_waitcnt vmcnt(8)
	s_waitcnt lgkmcnt(0)
	s_barrier
	s_waitcnt lgkmcnt(7)
	v_mfma_f32_16x16x32_bf16 v[60:63], v[132:135], v[178:181], v[60:63]
	v_mfma_f32_16x16x32_bf16 v[56:59], v[140:143], v[178:181], v[56:59]
	s_waitcnt lgkmcnt(5)
	v_mfma_f32_16x16x32_bf16 v[44:47], v[132:135], v[186:189], v[44:47]
	v_mfma_f32_16x16x32_bf16 v[40:43], v[140:143], v[186:189], v[40:43]
	s_waitcnt lgkmcnt(3)
	v_mfma_f32_16x16x32_bf16 v[28:31], v[132:135], v[194:197], v[28:31]
	v_mfma_f32_16x16x32_bf16 v[24:27], v[140:143], v[194:197], v[24:27]
	s_waitcnt lgkmcnt(1)
	v_mfma_f32_16x16x32_bf16 v[12:15], v[132:135], v[202:205], v[12:15]
	v_mfma_f32_16x16x32_bf16 v[8:11], v[140:143], v[202:205], v[8:11]
	v_mfma_f32_16x16x32_bf16 v[60:63], v[136:139], v[182:185], v[60:63]
	v_mfma_f32_16x16x32_bf16 v[56:59], v[158:161], v[182:185], v[56:59]
	v_mfma_f32_16x16x32_bf16 v[44:47], v[136:139], v[190:193], v[44:47]
	v_mfma_f32_16x16x32_bf16 v[40:43], v[158:161], v[190:193], v[40:43]
	v_mfma_f32_16x16x32_bf16 v[28:31], v[136:139], v[198:201], v[28:31]
	v_mfma_f32_16x16x32_bf16 v[24:27], v[158:161], v[198:201], v[24:27]
	s_waitcnt lgkmcnt(0)
	v_mfma_f32_16x16x32_bf16 v[12:15], v[136:139], v[206:209], v[12:15]
	v_mfma_f32_16x16x32_bf16 v[8:11], v[158:161], v[206:209], v[8:11]
	v_mfma_f32_16x16x32_bf16 v[52:55], v[162:165], v[178:181], v[52:55]
	v_mfma_f32_16x16x32_bf16 v[48:51], v[170:173], v[178:181], v[48:51]
	v_mfma_f32_16x16x32_bf16 v[36:39], v[162:165], v[186:189], v[36:39]
	v_mfma_f32_16x16x32_bf16 v[32:35], v[170:173], v[186:189], v[32:35]
	v_mfma_f32_16x16x32_bf16 v[20:23], v[162:165], v[194:197], v[20:23]
	v_mfma_f32_16x16x32_bf16 v[16:19], v[170:173], v[194:197], v[16:19]
	v_mfma_f32_16x16x32_bf16 v[4:7], v[162:165], v[202:205], v[4:7]
	v_mfma_f32_16x16x32_bf16 v[0:3], v[170:173], v[202:205], v[0:3]
	v_mfma_f32_16x16x32_bf16 v[52:55], v[166:169], v[182:185], v[52:55]
	v_mfma_f32_16x16x32_bf16 v[48:51], v[174:177], v[182:185], v[48:51]
	v_mfma_f32_16x16x32_bf16 v[36:39], v[166:169], v[190:193], v[36:39]
	v_mfma_f32_16x16x32_bf16 v[32:35], v[174:177], v[190:193], v[32:35]
	v_mfma_f32_16x16x32_bf16 v[20:23], v[166:169], v[198:201], v[20:23]
	v_mfma_f32_16x16x32_bf16 v[16:19], v[174:177], v[198:201], v[16:19]
	v_mfma_f32_16x16x32_bf16 v[4:7], v[166:169], v[206:209], v[4:7]
	v_mfma_f32_16x16x32_bf16 v[0:3], v[174:177], v[206:209], v[0:3]
	s_barrier
	s_add_i32 s73, s73, 2
	s_addk_i32 s41, 0x100
	s_addk_i32 s72, 0x100
	s_cmp_gt_u32 s73, 29
	s_cbranch_scc0 .LBB0_4016
	s_setprio 0
	s_and_b64 vcc, exec, s[26:27]
	s_cbranch_vccz .LBB0_4019
	s_barrier
